# speedup vs baseline: 1.0217x; 1.0037x over previous
; #define POOL_ACC(v, sgn) do { acc0 += sgn bf_lo(v.x); acc1 += sgn bf_hi(v.x); acc2 += sgn bf_lo(v.y); acc3 += sgn bf_hi(v.y); \
;     acc4 += sgn bf_lo(v.z); acc5 += sgn bf_hi(v.z); acc6 += sgn bf_lo(v.w); acc7 += sgn bf_hi(v.w); } while (0)
; template <int WIN>
; __device__ __forceinline__ void pool_run(const u16* U, u16* PL, int tok_s, int c0) {
;   const int pos_s = tok_s & (SEQ - 1);
;   float acc0 = 0.f, acc1 = 0.f, acc2 = 0.f, acc3 = 0.f, acc4 = 0.f, acc5 = 0.f, acc6 = 0.f, acc7 = 0.f;
;   #pragma unroll
;   for (int w = 1; w < WIN; ++w) {
;     if (pos_s - w >= 0) { const uint4 v = *(const uint4*)(U + (long)(tok_s - w) * LD0 + c0); POOL_ACC(v, +); }
;   }
;   #pragma unroll
;   for (int tt = 0; tt < 16; ++tt) {
;     const int tok = tok_s + tt, pos = pos_s + tt;
;     const uint4 cur = *(const uint4*)(U + (long)tok * LD0 + c0);
; __device__ __forceinline__ void pool_item(const Params& p, int item, const int wv) {
;   const u16* U = (const u16*)(p.ws + OFF_PB0) + 4096;
;   u16* PL = (u16*)(p.ws + OFF_PL);
;   const int tid = opaque_tid(wv), ch = tid & 255, half = tid >> 8;
;   const int c0 = ch * 8;
;   const int tok_s = item * 32 + half * 16;
;   const int g = (wv & 3);
;   if (g == 0) pool_run<2>(U, PL, tok_s, c0);
;   else if (g == 1) pool_run<4>(U, PL, tok_s, c0);
;   else if (g == 2) pool_run<8>(U, PL, tok_s, c0);
;   else pool_run<16>(U, PL, tok_s, c0);
.LBB0_339:
	s_or_b64 exec, exec, s[0:1]
	v_add_u32_e32 v0, 0, v0
	s_waitcnt lgkmcnt(0)
	s_barrier
	ds_read_b32 v0, v0
	s_mov_b64 s[0:1], -1
	s_waitcnt lgkmcnt(0)
	v_readfirstlane_b32 s6, v0
	s_cmpk_gt_i32 s6, 0x5ff
	s_cbranch_scc1 .LBB0_334
	s_cmpk_gt_i32 s6, 0x3ff
	s_cbranch_scc0 .LBB0_437
	v_mbcnt_lo_u32_b32 v0, -1, 0
	v_mbcnt_hi_u32_b32 v0, -1, v0
	s_lshl_b32 s0, s6, 5
	v_or_b32_e32 v0, s67, v0
	v_lshlrev_b32_e32 v1, 3, v0
	v_ashrrev_i32_e32 v0, 4, v0
	s_addk_i32 s0, 0x8000
	v_and_b32_e32 v0, -16, v0
	v_add_u32_e32 v16, s0, v0
	v_readlane_b32 s0, v255, 24
	v_and_b32_e32 v22, 0x7f8, v1
	v_and_b32_e32 v23, 0xff0, v16
	s_nop 1
	v_readfirstlane_b32 s1, v23
	s_nop 3
	s_cmp_eq_u32 s1, 0
	s_cbranch_scc1 .Lpool_slow
	s_cmp_eq_u32 s0, 0
	s_cbranch_scc1 .Lpool_w2
	s_cmp_eq_u32 s0, 1
	s_cbranch_scc1 .Lpool_w4
	s_cmp_eq_u32 s0, 2
	s_cbranch_scc1 .Lpool_w8
	v_readlane_b32 s0, v255, 20
	v_readlane_b32 s1, v255, 21
	v_lshlrev_b32_e32 v140, 1, v22
	v_add_u32_e32 v0, -15, v16
	s_nop 3
	v_lshl_add_u64 v[18:19], s[0:1], 0, v[140:141]
	v_readlane_b32 s0, v255, 22
	v_readlane_b32 s1, v255, 23
	v_ashrrev_i32_e32 v17, 31, v16
	v_lshlrev_b64 v[12:13], 12, v[16:17]
	s_nop 3
	v_lshl_add_u64 v[20:21], s[0:1], 0, v[140:141]
	v_mad_i64_i32 v[194:195], s[0:1], v0, s13, v[18:19]
	v_lshl_add_u64 v[196:197], v[20:21], 0, v[12:13]
	global_load_dwordx4 v[24:27], v[194:195], off
	v_add_co_u32_e32 v194, vcc, 0x5000, v194
	s_nop 1
	v_addc_co_u32_e32 v195, vcc, 0, v195, vcc
	global_load_dwordx4 v[28:31], v[194:195], off
	v_add_co_u32_e32 v194, vcc, 0x5000, v194
	s_nop 1
	v_addc_co_u32_e32 v195, vcc, 0, v195, vcc
	global_load_dwordx4 v[32:35], v[194:195], off
	v_add_co_u32_e32 v194, vcc, 0x5000, v194
	s_nop 1
	v_addc_co_u32_e32 v195, vcc, 0, v195, vcc
	global_load_dwordx4 v[36:39], v[194:195], off
	v_add_co_u32_e32 v194, vcc, 0x5000, v194
	s_nop 1
	v_addc_co_u32_e32 v195, vcc, 0, v195, vcc
	global_load_dwordx4 v[40:43], v[194:195], off
	v_add_co_u32_e32 v194, vcc, 0x5000, v194
	s_nop 1
	v_addc_co_u32_e32 v195, vcc, 0, v195, vcc
	global_load_dwordx4 v[44:47], v[194:195], off
	v_add_co_u32_e32 v194, vcc, 0x5000, v194
	s_nop 1
	v_addc_co_u32_e32 v195, vcc, 0, v195, vcc
	global_load_dwordx4 v[48:51], v[194:195], off
	v_add_co_u32_e32 v194, vcc, 0x5000, v194
	s_nop 1
	v_addc_co_u32_e32 v195, vcc, 0, v195, vcc
	global_load_dwordx4 v[52:55], v[194:195], off
	v_add_co_u32_e32 v194, vcc, 0x5000, v194
	s_nop 1
	v_addc_co_u32_e32 v195, vcc, 0, v195, vcc
	global_load_dwordx4 v[56:59], v[194:195], off
	v_add_co_u32_e32 v194, vcc, 0x5000, v194
	s_nop 1
	v_addc_co_u32_e32 v195, vcc, 0, v195, vcc
	global_load_dwordx4 v[60:63], v[194:195], off
	v_add_co_u32_e32 v194, vcc, 0x5000, v194
	s_nop 1
	v_addc_co_u32_e32 v195, vcc, 0, v195, vcc
	global_load_dwordx4 v[64:67], v[194:195], off
	v_add_co_u32_e32 v194, vcc, 0x5000, v194
	s_nop 1
	v_addc_co_u32_e32 v195, vcc, 0, v195, vcc
	global_load_dwordx4 v[68:71], v[194:195], off
	v_add_co_u32_e32 v194, vcc, 0x5000, v194
	s_nop 1
	v_addc_co_u32_e32 v195, vcc, 0, v195, vcc
	global_load_dwordx4 v[72:75], v[194:195], off
	v_add_co_u32_e32 v194, vcc, 0x5000, v194
	s_nop 1
	v_addc_co_u32_e32 v195, vcc, 0, v195, vcc
	global_load_dwordx4 v[76:79], v[194:195], off
	v_add_co_u32_e32 v194, vcc, 0x5000, v194
	s_nop 1
	v_addc_co_u32_e32 v195, vcc, 0, v195, vcc
	global_load_dwordx4 v[80:83], v[194:195], off
	v_add_co_u32_e32 v194, vcc, 0x5000, v194
	s_nop 1
	v_addc_co_u32_e32 v195, vcc, 0, v195, vcc
	global_load_dwordx4 v[84:87], v[194:195], off
	v_add_co_u32_e32 v194, vcc, 0x5000, v194
	s_nop 1
	v_addc_co_u32_e32 v195, vcc, 0, v195, vcc
	global_load_dwordx4 v[88:91], v[194:195], off
	v_add_co_u32_e32 v194, vcc, 0x5000, v194
	s_nop 1
	v_addc_co_u32_e32 v195, vcc, 0, v195, vcc
	global_load_dwordx4 v[92:95], v[194:195], off
	v_add_co_u32_e32 v194, vcc, 0x5000, v194
	s_nop 1
	v_addc_co_u32_e32 v195, vcc, 0, v195, vcc
	global_load_dwordx4 v[96:99], v[194:195], off
	v_add_co_u32_e32 v194, vcc, 0x5000, v194
	s_nop 1
	v_addc_co_u32_e32 v195, vcc, 0, v195, vcc
	global_load_dwordx4 v[100:103], v[194:195], off
	v_add_co_u32_e32 v194, vcc, 0x5000, v194
	s_nop 1
	v_addc_co_u32_e32 v195, vcc, 0, v195, vcc
	global_load_dwordx4 v[104:107], v[194:195], off
	v_add_co_u32_e32 v194, vcc, 0x5000, v194
	s_nop 1
	v_addc_co_u32_e32 v195, vcc, 0, v195, vcc
	global_load_dwordx4 v[108:111], v[194:195], off
	v_add_co_u32_e32 v194, vcc, 0x5000, v194
	s_nop 1
	v_addc_co_u32_e32 v195, vcc, 0, v195, vcc
	global_load_dwordx4 v[112:115], v[194:195], off
	v_add_co_u32_e32 v194, vcc, 0x5000, v194
	s_nop 1
	v_addc_co_u32_e32 v195, vcc, 0, v195, vcc
	global_load_dwordx4 v[116:119], v[194:195], off
	v_add_co_u32_e32 v194, vcc, 0x5000, v194
	s_nop 1
	v_addc_co_u32_e32 v195, vcc, 0, v195, vcc
	global_load_dwordx4 v[120:123], v[194:195], off
	v_add_co_u32_e32 v194, vcc, 0x5000, v194
	s_nop 1
	v_addc_co_u32_e32 v195, vcc, 0, v195, vcc
	global_load_dwordx4 v[124:127], v[194:195], off
	v_add_co_u32_e32 v194, vcc, 0x5000, v194
	s_nop 1
	v_addc_co_u32_e32 v195, vcc, 0, v195, vcc
	global_load_dwordx4 v[128:131], v[194:195], off
	v_add_co_u32_e32 v194, vcc, 0x5000, v194
	s_nop 1
	v_addc_co_u32_e32 v195, vcc, 0, v195, vcc
	global_load_dwordx4 v[132:135], v[194:195], off
	v_add_co_u32_e32 v194, vcc, 0x5000, v194
	s_nop 1
	v_addc_co_u32_e32 v195, vcc, 0, v195, vcc
	global_load_dwordx4 v[136:139], v[194:195], off
	v_add_co_u32_e32 v194, vcc, 0x5000, v194
	s_nop 1
	v_addc_co_u32_e32 v195, vcc, 0, v195, vcc
	global_load_dwordx4 v[144:147], v[194:195], off
	v_add_co_u32_e32 v194, vcc, 0x5000, v194
	s_nop 1
	v_addc_co_u32_e32 v195, vcc, 0, v195, vcc
	global_load_dwordx4 v[148:151], v[194:195], off
	v_mov_b32_e32 v192, 0x3d800000
	v_mov_b32_e32 v193, 0x3d800000
	v_mov_b32_e32 v164, 0
	v_mov_b32_e32 v165, 0
	v_mov_b32_e32 v166, 0
	v_mov_b32_e32 v167, 0
	v_mov_b32_e32 v168, 0
	v_mov_b32_e32 v169, 0
	v_mov_b32_e32 v170, 0
	v_mov_b32_e32 v171, 0
	s_waitcnt vmcnt(0)
; #define POOL_ACC(v, sgn) do { acc0 += sgn bf_lo(v.x); acc1 += sgn bf_hi(v.x); acc2 += sgn bf_lo(v.y); acc3 += sgn bf_hi(v.y); \
;     acc4 += sgn bf_lo(v.z); acc5 += sgn bf_hi(v.z); acc6 += sgn bf_lo(v.w); acc7 += sgn bf_hi(v.w); } while (0)
; template <int WIN>
; __device__ __forceinline__ void pool_run(const u16* U, u16* PL, int tok_s, int c0) {
;     ...
;   #pragma unroll
;   for (int w = 1; w < WIN; ++w) {
;     if (pos_s - w >= 0) { const uint4 v = *(const uint4*)(U + (long)(tok_s - w) * LD0 + c0); POOL_ACC(v, +); }
;   }
;   #pragma unroll
;   for (int tt = 0; tt < 16; ++tt) {
;     const int tok = tok_s + tt, pos = pos_s + tt;
;     const uint4 cur = *(const uint4*)(U + (long)tok * LD0 + c0);
;     POOL_ACC(cur, +);
	v_lshlrev_b32_e32 v172, 16, v80
	v_and_b32_e32 v173, 0xffff0000, v80
	v_lshlrev_b32_e32 v174, 16, v81
	v_and_b32_e32 v175, 0xffff0000, v81
	v_lshlrev_b32_e32 v176, 16, v82
	v_and_b32_e32 v177, 0xffff0000, v82
	v_lshlrev_b32_e32 v178, 16, v83
	v_and_b32_e32 v179, 0xffff0000, v83
	v_pk_add_f32 v[164:165], v[164:165], v[172:173]
	v_pk_add_f32 v[166:167], v[166:167], v[174:175]
	v_pk_add_f32 v[168:169], v[168:169], v[176:177]
	v_pk_add_f32 v[170:171], v[170:171], v[178:179]
	v_lshlrev_b32_e32 v172, 16, v76
	v_and_b32_e32 v173, 0xffff0000, v76
	v_lshlrev_b32_e32 v174, 16, v77
	v_and_b32_e32 v175, 0xffff0000, v77
	v_lshlrev_b32_e32 v176, 16, v78
	v_and_b32_e32 v177, 0xffff0000, v78
	v_lshlrev_b32_e32 v178, 16, v79
	v_and_b32_e32 v179, 0xffff0000, v79
	v_pk_add_f32 v[164:165], v[164:165], v[172:173]
	v_pk_add_f32 v[166:167], v[166:167], v[174:175]
	v_pk_add_f32 v[168:169], v[168:169], v[176:177]
	v_pk_add_f32 v[170:171], v[170:171], v[178:179]
	v_lshlrev_b32_e32 v172, 16, v72
	v_and_b32_e32 v173, 0xffff0000, v72
	v_lshlrev_b32_e32 v174, 16, v73
	v_and_b32_e32 v175, 0xffff0000, v73
	v_lshlrev_b32_e32 v176, 16, v74
	v_and_b32_e32 v177, 0xffff0000, v74
	v_lshlrev_b32_e32 v178, 16, v75
	v_and_b32_e32 v179, 0xffff0000, v75
	v_pk_add_f32 v[164:165], v[164:165], v[172:173]
	v_pk_add_f32 v[166:167], v[166:167], v[174:175]
	v_pk_add_f32 v[168:169], v[168:169], v[176:177]
	v_pk_add_f32 v[170:171], v[170:171], v[178:179]
	v_lshlrev_b32_e32 v172, 16, v68
	v_and_b32_e32 v173, 0xffff0000, v68
	v_lshlrev_b32_e32 v174, 16, v69
	v_and_b32_e32 v175, 0xffff0000, v69
	v_lshlrev_b32_e32 v176, 16, v70
	v_and_b32_e32 v177, 0xffff0000, v70
	v_lshlrev_b32_e32 v178, 16, v71
	v_and_b32_e32 v179, 0xffff0000, v71
	v_pk_add_f32 v[164:165], v[164:165], v[172:173]
	v_pk_add_f32 v[166:167], v[166:167], v[174:175]
	v_pk_add_f32 v[168:169], v[168:169], v[176:177]
	v_pk_add_f32 v[170:171], v[170:171], v[178:179]
	v_lshlrev_b32_e32 v172, 16, v64
	v_and_b32_e32 v173, 0xffff0000, v64
	v_lshlrev_b32_e32 v174, 16, v65
	v_and_b32_e32 v175, 0xffff0000, v65
	v_lshlrev_b32_e32 v176, 16, v66
	v_and_b32_e32 v177, 0xffff0000, v66
	v_lshlrev_b32_e32 v178, 16, v67
	v_and_b32_e32 v179, 0xffff0000, v67
	v_pk_add_f32 v[164:165], v[164:165], v[172:173]
	v_pk_add_f32 v[166:167], v[166:167], v[174:175]
	v_pk_add_f32 v[168:169], v[168:169], v[176:177]
	v_pk_add_f32 v[170:171], v[170:171], v[178:179]
	v_lshlrev_b32_e32 v172, 16, v60
	v_and_b32_e32 v173, 0xffff0000, v60
	v_lshlrev_b32_e32 v174, 16, v61
	v_and_b32_e32 v175, 0xffff0000, v61
	v_lshlrev_b32_e32 v176, 16, v62
	v_and_b32_e32 v177, 0xffff0000, v62
	v_lshlrev_b32_e32 v178, 16, v63
	v_and_b32_e32 v179, 0xffff0000, v63
	v_pk_add_f32 v[164:165], v[164:165], v[172:173]
	v_pk_add_f32 v[166:167], v[166:167], v[174:175]
	v_pk_add_f32 v[168:169], v[168:169], v[176:177]
	v_pk_add_f32 v[170:171], v[170:171], v[178:179]
	v_lshlrev_b32_e32 v172, 16, v56
	v_and_b32_e32 v173, 0xffff0000, v56
	v_lshlrev_b32_e32 v174, 16, v57
	v_and_b32_e32 v175, 0xffff0000, v57
	v_lshlrev_b32_e32 v176, 16, v58
	v_and_b32_e32 v177, 0xffff0000, v58
	v_lshlrev_b32_e32 v178, 16, v59
	v_and_b32_e32 v179, 0xffff0000, v59
	v_pk_add_f32 v[164:165], v[164:165], v[172:173]
	v_pk_add_f32 v[166:167], v[166:167], v[174:175]
	v_pk_add_f32 v[168:169], v[168:169], v[176:177]
	v_pk_add_f32 v[170:171], v[170:171], v[178:179]
	v_lshlrev_b32_e32 v172, 16, v52
	v_and_b32_e32 v173, 0xffff0000, v52
	v_lshlrev_b32_e32 v174, 16, v53
	v_and_b32_e32 v175, 0xffff0000, v53
	v_lshlrev_b32_e32 v176, 16, v54
	v_and_b32_e32 v177, 0xffff0000, v54
	v_lshlrev_b32_e32 v178, 16, v55
	v_and_b32_e32 v179, 0xffff0000, v55
	v_pk_add_f32 v[164:165], v[164:165], v[172:173]
	v_pk_add_f32 v[166:167], v[166:167], v[174:175]
	v_pk_add_f32 v[168:169], v[168:169], v[176:177]
	v_pk_add_f32 v[170:171], v[170:171], v[178:179]
	v_lshlrev_b32_e32 v172, 16, v48
	v_and_b32_e32 v173, 0xffff0000, v48
	v_lshlrev_b32_e32 v174, 16, v49
	v_and_b32_e32 v175, 0xffff0000, v49
	v_lshlrev_b32_e32 v176, 16, v50
	v_and_b32_e32 v177, 0xffff0000, v50
	v_lshlrev_b32_e32 v178, 16, v51
	v_and_b32_e32 v179, 0xffff0000, v51
	v_pk_add_f32 v[164:165], v[164:165], v[172:173]
	v_pk_add_f32 v[166:167], v[166:167], v[174:175]
	v_pk_add_f32 v[168:169], v[168:169], v[176:177]
	v_pk_add_f32 v[170:171], v[170:171], v[178:179]
	v_lshlrev_b32_e32 v172, 16, v44
	v_and_b32_e32 v173, 0xffff0000, v44
	v_lshlrev_b32_e32 v174, 16, v45
	v_and_b32_e32 v175, 0xffff0000, v45
	v_lshlrev_b32_e32 v176, 16, v46
	v_and_b32_e32 v177, 0xffff0000, v46
	v_lshlrev_b32_e32 v178, 16, v47
	v_and_b32_e32 v179, 0xffff0000, v47
	v_pk_add_f32 v[164:165], v[164:165], v[172:173]
	v_pk_add_f32 v[166:167], v[166:167], v[174:175]
	v_pk_add_f32 v[168:169], v[168:169], v[176:177]
	v_pk_add_f32 v[170:171], v[170:171], v[178:179]
	v_lshlrev_b32_e32 v172, 16, v40
	v_and_b32_e32 v173, 0xffff0000, v40
	v_lshlrev_b32_e32 v174, 16, v41
	v_and_b32_e32 v175, 0xffff0000, v41
	v_lshlrev_b32_e32 v176, 16, v42
	v_and_b32_e32 v177, 0xffff0000, v42
	v_lshlrev_b32_e32 v178, 16, v43
	v_and_b32_e32 v179, 0xffff0000, v43
	v_pk_add_f32 v[164:165], v[164:165], v[172:173]
	v_pk_add_f32 v[166:167], v[166:167], v[174:175]
	v_pk_add_f32 v[168:169], v[168:169], v[176:177]
	v_pk_add_f32 v[170:171], v[170:171], v[178:179]
	v_lshlrev_b32_e32 v172, 16, v36
	v_and_b32_e32 v173, 0xffff0000, v36
	v_lshlrev_b32_e32 v174, 16, v37
	v_and_b32_e32 v175, 0xffff0000, v37
	v_lshlrev_b32_e32 v176, 16, v38
	v_and_b32_e32 v177, 0xffff0000, v38
	v_lshlrev_b32_e32 v178, 16, v39
	v_and_b32_e32 v179, 0xffff0000, v39
	v_pk_add_f32 v[164:165], v[164:165], v[172:173]
	v_pk_add_f32 v[166:167], v[166:167], v[174:175]
	v_pk_add_f32 v[168:169], v[168:169], v[176:177]
; __device__ __forceinline__ float bf_lo(u32 v) { return __uint_as_float(v << 16); }
; __device__ __forceinline__ float bf_hi(u32 v) { return __uint_as_float(v & 0xffff0000u); }
; #define POOL_ACC(v, sgn) do { acc0 += sgn bf_lo(v.x); acc1 += sgn bf_hi(v.x); acc2 += sgn bf_lo(v.y); acc3 += sgn bf_hi(v.y); \
;     acc4 += sgn bf_lo(v.z); acc5 += sgn bf_hi(v.z); acc6 += sgn bf_lo(v.w); acc7 += sgn bf_hi(v.w); } while (0)
; template <int WIN>
; __device__ __forceinline__ void pool_run(const u16* U, u16* PL, int tok_s, int c0) {
;     ...
;   #pragma unroll
;   for (int tt = 0; tt < 16; ++tt) {
;     const int tok = tok_s + tt, pos = pos_s + tt;
;     const uint4 cur = *(const uint4*)(U + (long)tok * LD0 + c0);
;     POOL_ACC(cur, +);
;     const float ic = 1.0f / (float)min(WIN, pos + 1);
;     uint4 pk;
;     pk.x = pack2(acc0 * ic - bf_lo(cur.x), acc1 * ic - bf_hi(cur.x));
;     pk.y = pack2(acc2 * ic - bf_lo(cur.y), acc3 * ic - bf_hi(cur.y));
;     pk.z = pack2(acc4 * ic - bf_lo(cur.z), acc5 * ic - bf_hi(cur.z));
;     pk.w = pack2(acc6 * ic - bf_lo(cur.w), acc7 * ic - bf_hi(cur.w));
;     *(uint4*)(PL + (long)tok * 2048 + c0) = pk;
;     if (pos - (WIN - 1) >= 0) { const uint4 old = *(const uint4*)(U + (long)(tok - (WIN - 1)) * LD0 + c0); POOL_ACC(old, -); }
	v_pk_add_f32 v[170:171], v[170:171], v[178:179]
	v_lshlrev_b32_e32 v172, 16, v32
	v_and_b32_e32 v173, 0xffff0000, v32
	v_lshlrev_b32_e32 v174, 16, v33
	v_and_b32_e32 v175, 0xffff0000, v33
	v_lshlrev_b32_e32 v176, 16, v34
	v_and_b32_e32 v177, 0xffff0000, v34
	v_lshlrev_b32_e32 v178, 16, v35
	v_and_b32_e32 v179, 0xffff0000, v35
	v_pk_add_f32 v[164:165], v[164:165], v[172:173]
	v_pk_add_f32 v[166:167], v[166:167], v[174:175]
	v_pk_add_f32 v[168:169], v[168:169], v[176:177]
	v_pk_add_f32 v[170:171], v[170:171], v[178:179]
	v_lshlrev_b32_e32 v172, 16, v28
	v_and_b32_e32 v173, 0xffff0000, v28
	v_lshlrev_b32_e32 v174, 16, v29
	v_and_b32_e32 v175, 0xffff0000, v29
	v_lshlrev_b32_e32 v176, 16, v30
	v_and_b32_e32 v177, 0xffff0000, v30
	v_lshlrev_b32_e32 v178, 16, v31
	v_and_b32_e32 v179, 0xffff0000, v31
	v_pk_add_f32 v[164:165], v[164:165], v[172:173]
	v_pk_add_f32 v[166:167], v[166:167], v[174:175]
	v_pk_add_f32 v[168:169], v[168:169], v[176:177]
	v_pk_add_f32 v[170:171], v[170:171], v[178:179]
	v_lshlrev_b32_e32 v172, 16, v24
	v_and_b32_e32 v173, 0xffff0000, v24
	v_lshlrev_b32_e32 v174, 16, v25
	v_and_b32_e32 v175, 0xffff0000, v25
	v_lshlrev_b32_e32 v176, 16, v26
	v_and_b32_e32 v177, 0xffff0000, v26
	v_lshlrev_b32_e32 v178, 16, v27
	v_and_b32_e32 v179, 0xffff0000, v27
	v_pk_add_f32 v[164:165], v[164:165], v[172:173]
	v_pk_add_f32 v[166:167], v[166:167], v[174:175]
	v_pk_add_f32 v[168:169], v[168:169], v[176:177]
	v_pk_add_f32 v[170:171], v[170:171], v[178:179]
	v_lshlrev_b32_e32 v172, 16, v84
	v_and_b32_e32 v173, 0xffff0000, v84
	v_lshlrev_b32_e32 v174, 16, v85
	v_and_b32_e32 v175, 0xffff0000, v85
	v_lshlrev_b32_e32 v176, 16, v86
	v_and_b32_e32 v177, 0xffff0000, v86
	v_lshlrev_b32_e32 v178, 16, v87
	v_and_b32_e32 v179, 0xffff0000, v87
	v_pk_add_f32 v[164:165], v[164:165], v[172:173]
	v_pk_add_f32 v[166:167], v[166:167], v[174:175]
	v_pk_add_f32 v[168:169], v[168:169], v[176:177]
	v_pk_add_f32 v[170:171], v[170:171], v[178:179]
	v_pk_fma_f32 v[180:181], v[164:165], v[192:193], v[172:173] neg_lo:[0,0,1] neg_hi:[0,0,1]
	v_pk_fma_f32 v[182:183], v[166:167], v[192:193], v[174:175] neg_lo:[0,0,1] neg_hi:[0,0,1]
	v_pk_fma_f32 v[184:185], v[168:169], v[192:193], v[176:177] neg_lo:[0,0,1] neg_hi:[0,0,1]
	v_pk_fma_f32 v[186:187], v[170:171], v[192:193], v[178:179] neg_lo:[0,0,1] neg_hi:[0,0,1]
	v_cvt_pk_bf16_f32 v188, v180, v181
	v_cvt_pk_bf16_f32 v189, v182, v183
	v_cvt_pk_bf16_f32 v190, v184, v185
	v_cvt_pk_bf16_f32 v191, v186, v187
	s_nop 0
	global_store_dwordx4 v[196:197], v[188:191], off
	v_add_co_u32_e32 v196, vcc, 0x1000, v196
	s_nop 1
	v_addc_co_u32_e32 v197, vcc, 0, v197, vcc
	v_lshlrev_b32_e32 v172, 16, v24
	v_and_b32_e32 v173, 0xffff0000, v24
	v_lshlrev_b32_e32 v174, 16, v25
	v_and_b32_e32 v175, 0xffff0000, v25
	v_lshlrev_b32_e32 v176, 16, v26
	v_and_b32_e32 v177, 0xffff0000, v26
	v_lshlrev_b32_e32 v178, 16, v27
	v_and_b32_e32 v179, 0xffff0000, v27
	v_pk_add_f32 v[164:165], v[164:165], v[172:173] neg_lo:[0,1] neg_hi:[0,1]
	v_pk_add_f32 v[166:167], v[166:167], v[174:175] neg_lo:[0,1] neg_hi:[0,1]
	v_pk_add_f32 v[168:169], v[168:169], v[176:177] neg_lo:[0,1] neg_hi:[0,1]
	v_pk_add_f32 v[170:171], v[170:171], v[178:179] neg_lo:[0,1] neg_hi:[0,1]
	v_lshlrev_b32_e32 v172, 16, v88
	v_and_b32_e32 v173, 0xffff0000, v88
	v_lshlrev_b32_e32 v174, 16, v89
	v_and_b32_e32 v175, 0xffff0000, v89
	v_lshlrev_b32_e32 v176, 16, v90
	v_and_b32_e32 v177, 0xffff0000, v90
	v_lshlrev_b32_e32 v178, 16, v91
	v_and_b32_e32 v179, 0xffff0000, v91
	v_pk_add_f32 v[164:165], v[164:165], v[172:173]
	v_pk_add_f32 v[166:167], v[166:167], v[174:175]
	v_pk_add_f32 v[168:169], v[168:169], v[176:177]
	v_pk_add_f32 v[170:171], v[170:171], v[178:179]
	v_pk_fma_f32 v[180:181], v[164:165], v[192:193], v[172:173] neg_lo:[0,0,1] neg_hi:[0,0,1]
	v_pk_fma_f32 v[182:183], v[166:167], v[192:193], v[174:175] neg_lo:[0,0,1] neg_hi:[0,0,1]
	v_pk_fma_f32 v[184:185], v[168:169], v[192:193], v[176:177] neg_lo:[0,0,1] neg_hi:[0,0,1]
	v_pk_fma_f32 v[186:187], v[170:171], v[192:193], v[178:179] neg_lo:[0,0,1] neg_hi:[0,0,1]
	v_cvt_pk_bf16_f32 v200, v180, v181
	v_cvt_pk_bf16_f32 v201, v182, v183
	v_cvt_pk_bf16_f32 v202, v184, v185
	v_cvt_pk_bf16_f32 v203, v186, v187
	s_nop 0
	global_store_dwordx4 v[196:197], v[200:203], off
	v_add_co_u32_e32 v196, vcc, 0x1000, v196
	s_nop 1
	v_addc_co_u32_e32 v197, vcc, 0, v197, vcc
	v_lshlrev_b32_e32 v172, 16, v28
	v_and_b32_e32 v173, 0xffff0000, v28
	v_lshlrev_b32_e32 v174, 16, v29
	v_and_b32_e32 v175, 0xffff0000, v29
	v_lshlrev_b32_e32 v176, 16, v30
	v_and_b32_e32 v177, 0xffff0000, v30
	v_lshlrev_b32_e32 v178, 16, v31
	v_and_b32_e32 v179, 0xffff0000, v31
	v_pk_add_f32 v[164:165], v[164:165], v[172:173] neg_lo:[0,1] neg_hi:[0,1]
	v_pk_add_f32 v[166:167], v[166:167], v[174:175] neg_lo:[0,1] neg_hi:[0,1]
	v_pk_add_f32 v[168:169], v[168:169], v[176:177] neg_lo:[0,1] neg_hi:[0,1]
	v_pk_add_f32 v[170:171], v[170:171], v[178:179] neg_lo:[0,1] neg_hi:[0,1]
	v_lshlrev_b32_e32 v172, 16, v92
	v_and_b32_e32 v173, 0xffff0000, v92
	v_lshlrev_b32_e32 v174, 16, v93
	v_and_b32_e32 v175, 0xffff0000, v93
	v_lshlrev_b32_e32 v176, 16, v94
	v_and_b32_e32 v177, 0xffff0000, v94
	v_lshlrev_b32_e32 v178, 16, v95
	v_and_b32_e32 v179, 0xffff0000, v95
	v_pk_add_f32 v[164:165], v[164:165], v[172:173]
	v_pk_add_f32 v[166:167], v[166:167], v[174:175]
	v_pk_add_f32 v[168:169], v[168:169], v[176:177]
	v_pk_add_f32 v[170:171], v[170:171], v[178:179]
	v_pk_fma_f32 v[180:181], v[164:165], v[192:193], v[172:173] neg_lo:[0,0,1] neg_hi:[0,0,1]
	v_pk_fma_f32 v[182:183], v[166:167], v[192:193], v[174:175] neg_lo:[0,0,1] neg_hi:[0,0,1]
	v_pk_fma_f32 v[184:185], v[168:169], v[192:193], v[176:177] neg_lo:[0,0,1] neg_hi:[0,0,1]
; __device__ __forceinline__ float bf_lo(u32 v) { return __uint_as_float(v << 16); }
; __device__ __forceinline__ float bf_hi(u32 v) { return __uint_as_float(v & 0xffff0000u); }
; #define POOL_ACC(v, sgn) do { acc0 += sgn bf_lo(v.x); acc1 += sgn bf_hi(v.x); acc2 += sgn bf_lo(v.y); acc3 += sgn bf_hi(v.y); \
;     acc4 += sgn bf_lo(v.z); acc5 += sgn bf_hi(v.z); acc6 += sgn bf_lo(v.w); acc7 += sgn bf_hi(v.w); } while (0)
; template <int WIN>
; __device__ __forceinline__ void pool_run(const u16* U, u16* PL, int tok_s, int c0) {
;     ...
;   #pragma unroll
;   for (int tt = 0; tt < 16; ++tt) {
;     const int tok = tok_s + tt, pos = pos_s + tt;
;     const uint4 cur = *(const uint4*)(U + (long)tok * LD0 + c0);
;     POOL_ACC(cur, +);
;     const float ic = 1.0f / (float)min(WIN, pos + 1);
;     uint4 pk;
;     pk.x = pack2(acc0 * ic - bf_lo(cur.x), acc1 * ic - bf_hi(cur.x));
;     pk.y = pack2(acc2 * ic - bf_lo(cur.y), acc3 * ic - bf_hi(cur.y));
;     pk.z = pack2(acc4 * ic - bf_lo(cur.z), acc5 * ic - bf_hi(cur.z));
;     pk.w = pack2(acc6 * ic - bf_lo(cur.w), acc7 * ic - bf_hi(cur.w));
;     *(uint4*)(PL + (long)tok * 2048 + c0) = pk;
;     if (pos - (WIN - 1) >= 0) { const uint4 old = *(const uint4*)(U + (long)(tok - (WIN - 1)) * LD0 + c0); POOL_ACC(old, -); }
	v_pk_fma_f32 v[186:187], v[170:171], v[192:193], v[178:179] neg_lo:[0,0,1] neg_hi:[0,0,1]
	v_cvt_pk_bf16_f32 v188, v180, v181
	v_cvt_pk_bf16_f32 v189, v182, v183
	v_cvt_pk_bf16_f32 v190, v184, v185
	v_cvt_pk_bf16_f32 v191, v186, v187
	s_nop 0
	global_store_dwordx4 v[196:197], v[188:191], off
	v_add_co_u32_e32 v196, vcc, 0x1000, v196
	s_nop 1
	v_addc_co_u32_e32 v197, vcc, 0, v197, vcc
	v_lshlrev_b32_e32 v172, 16, v32
	v_and_b32_e32 v173, 0xffff0000, v32
	v_lshlrev_b32_e32 v174, 16, v33
	v_and_b32_e32 v175, 0xffff0000, v33
	v_lshlrev_b32_e32 v176, 16, v34
	v_and_b32_e32 v177, 0xffff0000, v34
	v_lshlrev_b32_e32 v178, 16, v35
	v_and_b32_e32 v179, 0xffff0000, v35
	v_pk_add_f32 v[164:165], v[164:165], v[172:173] neg_lo:[0,1] neg_hi:[0,1]
	v_pk_add_f32 v[166:167], v[166:167], v[174:175] neg_lo:[0,1] neg_hi:[0,1]
	v_pk_add_f32 v[168:169], v[168:169], v[176:177] neg_lo:[0,1] neg_hi:[0,1]
	v_pk_add_f32 v[170:171], v[170:171], v[178:179] neg_lo:[0,1] neg_hi:[0,1]
	v_lshlrev_b32_e32 v172, 16, v96
	v_and_b32_e32 v173, 0xffff0000, v96
	v_lshlrev_b32_e32 v174, 16, v97
	v_and_b32_e32 v175, 0xffff0000, v97
	v_lshlrev_b32_e32 v176, 16, v98
	v_and_b32_e32 v177, 0xffff0000, v98
	v_lshlrev_b32_e32 v178, 16, v99
	v_and_b32_e32 v179, 0xffff0000, v99
	v_pk_add_f32 v[164:165], v[164:165], v[172:173]
	v_pk_add_f32 v[166:167], v[166:167], v[174:175]
	v_pk_add_f32 v[168:169], v[168:169], v[176:177]
	v_pk_add_f32 v[170:171], v[170:171], v[178:179]
	v_pk_fma_f32 v[180:181], v[164:165], v[192:193], v[172:173] neg_lo:[0,0,1] neg_hi:[0,0,1]
	v_pk_fma_f32 v[182:183], v[166:167], v[192:193], v[174:175] neg_lo:[0,0,1] neg_hi:[0,0,1]
	v_pk_fma_f32 v[184:185], v[168:169], v[192:193], v[176:177] neg_lo:[0,0,1] neg_hi:[0,0,1]
	v_pk_fma_f32 v[186:187], v[170:171], v[192:193], v[178:179] neg_lo:[0,0,1] neg_hi:[0,0,1]
	v_cvt_pk_bf16_f32 v200, v180, v181
	v_cvt_pk_bf16_f32 v201, v182, v183
	v_cvt_pk_bf16_f32 v202, v184, v185
	v_cvt_pk_bf16_f32 v203, v186, v187
	s_nop 0
	global_store_dwordx4 v[196:197], v[200:203], off
	v_add_co_u32_e32 v196, vcc, 0x1000, v196
	s_nop 1
	v_addc_co_u32_e32 v197, vcc, 0, v197, vcc
	v_lshlrev_b32_e32 v172, 16, v36
	v_and_b32_e32 v173, 0xffff0000, v36
	v_lshlrev_b32_e32 v174, 16, v37
	v_and_b32_e32 v175, 0xffff0000, v37
	v_lshlrev_b32_e32 v176, 16, v38
	v_and_b32_e32 v177, 0xffff0000, v38
	v_lshlrev_b32_e32 v178, 16, v39
	v_and_b32_e32 v179, 0xffff0000, v39
	v_pk_add_f32 v[164:165], v[164:165], v[172:173] neg_lo:[0,1] neg_hi:[0,1]
	v_pk_add_f32 v[166:167], v[166:167], v[174:175] neg_lo:[0,1] neg_hi:[0,1]
	v_pk_add_f32 v[168:169], v[168:169], v[176:177] neg_lo:[0,1] neg_hi:[0,1]
	v_pk_add_f32 v[170:171], v[170:171], v[178:179] neg_lo:[0,1] neg_hi:[0,1]
	v_lshlrev_b32_e32 v172, 16, v100
	v_and_b32_e32 v173, 0xffff0000, v100
	v_lshlrev_b32_e32 v174, 16, v101
	v_and_b32_e32 v175, 0xffff0000, v101
	v_lshlrev_b32_e32 v176, 16, v102
	v_and_b32_e32 v177, 0xffff0000, v102
	v_lshlrev_b32_e32 v178, 16, v103
	v_and_b32_e32 v179, 0xffff0000, v103
	v_pk_add_f32 v[164:165], v[164:165], v[172:173]
	v_pk_add_f32 v[166:167], v[166:167], v[174:175]
	v_pk_add_f32 v[168:169], v[168:169], v[176:177]
	v_pk_add_f32 v[170:171], v[170:171], v[178:179]
	v_pk_fma_f32 v[180:181], v[164:165], v[192:193], v[172:173] neg_lo:[0,0,1] neg_hi:[0,0,1]
	v_pk_fma_f32 v[182:183], v[166:167], v[192:193], v[174:175] neg_lo:[0,0,1] neg_hi:[0,0,1]
	v_pk_fma_f32 v[184:185], v[168:169], v[192:193], v[176:177] neg_lo:[0,0,1] neg_hi:[0,0,1]
	v_pk_fma_f32 v[186:187], v[170:171], v[192:193], v[178:179] neg_lo:[0,0,1] neg_hi:[0,0,1]
	v_cvt_pk_bf16_f32 v188, v180, v181
	v_cvt_pk_bf16_f32 v189, v182, v183
	v_cvt_pk_bf16_f32 v190, v184, v185
	v_cvt_pk_bf16_f32 v191, v186, v187
	s_nop 0
	global_store_dwordx4 v[196:197], v[188:191], off
	v_add_co_u32_e32 v196, vcc, 0x1000, v196
	s_nop 1
	v_addc_co_u32_e32 v197, vcc, 0, v197, vcc
	v_lshlrev_b32_e32 v172, 16, v40
	v_and_b32_e32 v173, 0xffff0000, v40
	v_lshlrev_b32_e32 v174, 16, v41
	v_and_b32_e32 v175, 0xffff0000, v41
	v_lshlrev_b32_e32 v176, 16, v42
	v_and_b32_e32 v177, 0xffff0000, v42
	v_lshlrev_b32_e32 v178, 16, v43
	v_and_b32_e32 v179, 0xffff0000, v43
	v_pk_add_f32 v[164:165], v[164:165], v[172:173] neg_lo:[0,1] neg_hi:[0,1]
	v_pk_add_f32 v[166:167], v[166:167], v[174:175] neg_lo:[0,1] neg_hi:[0,1]
	v_pk_add_f32 v[168:169], v[168:169], v[176:177] neg_lo:[0,1] neg_hi:[0,1]
	v_pk_add_f32 v[170:171], v[170:171], v[178:179] neg_lo:[0,1] neg_hi:[0,1]
	v_lshlrev_b32_e32 v172, 16, v104
	v_and_b32_e32 v173, 0xffff0000, v104
	v_lshlrev_b32_e32 v174, 16, v105
	v_and_b32_e32 v175, 0xffff0000, v105
	v_lshlrev_b32_e32 v176, 16, v106
	v_and_b32_e32 v177, 0xffff0000, v106
	v_lshlrev_b32_e32 v178, 16, v107
	v_and_b32_e32 v179, 0xffff0000, v107
	v_pk_add_f32 v[164:165], v[164:165], v[172:173]
	v_pk_add_f32 v[166:167], v[166:167], v[174:175]
	v_pk_add_f32 v[168:169], v[168:169], v[176:177]
	v_pk_add_f32 v[170:171], v[170:171], v[178:179]
	v_pk_fma_f32 v[180:181], v[164:165], v[192:193], v[172:173] neg_lo:[0,0,1] neg_hi:[0,0,1]
	v_pk_fma_f32 v[182:183], v[166:167], v[192:193], v[174:175] neg_lo:[0,0,1] neg_hi:[0,0,1]
	v_pk_fma_f32 v[184:185], v[168:169], v[192:193], v[176:177] neg_lo:[0,0,1] neg_hi:[0,0,1]
	v_pk_fma_f32 v[186:187], v[170:171], v[192:193], v[178:179] neg_lo:[0,0,1] neg_hi:[0,0,1]
	v_cvt_pk_bf16_f32 v200, v180, v181
	v_cvt_pk_bf16_f32 v201, v182, v183
	v_cvt_pk_bf16_f32 v202, v184, v185
	v_cvt_pk_bf16_f32 v203, v186, v187
	s_nop 0
	global_store_dwordx4 v[196:197], v[200:203], off
	v_add_co_u32_e32 v196, vcc, 0x1000, v196
	s_nop 1
	v_addc_co_u32_e32 v197, vcc, 0, v197, vcc
	v_lshlrev_b32_e32 v172, 16, v44
	v_and_b32_e32 v173, 0xffff0000, v44
; __device__ __forceinline__ float bf_lo(u32 v) { return __uint_as_float(v << 16); }
; __device__ __forceinline__ float bf_hi(u32 v) { return __uint_as_float(v & 0xffff0000u); }
; #define POOL_ACC(v, sgn) do { acc0 += sgn bf_lo(v.x); acc1 += sgn bf_hi(v.x); acc2 += sgn bf_lo(v.y); acc3 += sgn bf_hi(v.y); \
;     acc4 += sgn bf_lo(v.z); acc5 += sgn bf_hi(v.z); acc6 += sgn bf_lo(v.w); acc7 += sgn bf_hi(v.w); } while (0)
; template <int WIN>
; __device__ __forceinline__ void pool_run(const u16* U, u16* PL, int tok_s, int c0) {
;     ...
;   #pragma unroll
;   for (int tt = 0; tt < 16; ++tt) {
;     const int tok = tok_s + tt, pos = pos_s + tt;
;     const uint4 cur = *(const uint4*)(U + (long)tok * LD0 + c0);
;     POOL_ACC(cur, +);
;     const float ic = 1.0f / (float)min(WIN, pos + 1);
;     uint4 pk;
;     pk.x = pack2(acc0 * ic - bf_lo(cur.x), acc1 * ic - bf_hi(cur.x));
;     pk.y = pack2(acc2 * ic - bf_lo(cur.y), acc3 * ic - bf_hi(cur.y));
;     pk.z = pack2(acc4 * ic - bf_lo(cur.z), acc5 * ic - bf_hi(cur.z));
;     pk.w = pack2(acc6 * ic - bf_lo(cur.w), acc7 * ic - bf_hi(cur.w));
;     *(uint4*)(PL + (long)tok * 2048 + c0) = pk;
;     if (pos - (WIN - 1) >= 0) { const uint4 old = *(const uint4*)(U + (long)(tok - (WIN - 1)) * LD0 + c0); POOL_ACC(old, -); }
	v_lshlrev_b32_e32 v174, 16, v45
	v_and_b32_e32 v175, 0xffff0000, v45
	v_lshlrev_b32_e32 v176, 16, v46
	v_and_b32_e32 v177, 0xffff0000, v46
	v_lshlrev_b32_e32 v178, 16, v47
	v_and_b32_e32 v179, 0xffff0000, v47
	v_pk_add_f32 v[164:165], v[164:165], v[172:173] neg_lo:[0,1] neg_hi:[0,1]
	v_pk_add_f32 v[166:167], v[166:167], v[174:175] neg_lo:[0,1] neg_hi:[0,1]
	v_pk_add_f32 v[168:169], v[168:169], v[176:177] neg_lo:[0,1] neg_hi:[0,1]
	v_pk_add_f32 v[170:171], v[170:171], v[178:179] neg_lo:[0,1] neg_hi:[0,1]
	v_lshlrev_b32_e32 v172, 16, v108
	v_and_b32_e32 v173, 0xffff0000, v108
	v_lshlrev_b32_e32 v174, 16, v109
	v_and_b32_e32 v175, 0xffff0000, v109
	v_lshlrev_b32_e32 v176, 16, v110
	v_and_b32_e32 v177, 0xffff0000, v110
	v_lshlrev_b32_e32 v178, 16, v111
	v_and_b32_e32 v179, 0xffff0000, v111
	v_pk_add_f32 v[164:165], v[164:165], v[172:173]
	v_pk_add_f32 v[166:167], v[166:167], v[174:175]
	v_pk_add_f32 v[168:169], v[168:169], v[176:177]
	v_pk_add_f32 v[170:171], v[170:171], v[178:179]
	v_pk_fma_f32 v[180:181], v[164:165], v[192:193], v[172:173] neg_lo:[0,0,1] neg_hi:[0,0,1]
	v_pk_fma_f32 v[182:183], v[166:167], v[192:193], v[174:175] neg_lo:[0,0,1] neg_hi:[0,0,1]
	v_pk_fma_f32 v[184:185], v[168:169], v[192:193], v[176:177] neg_lo:[0,0,1] neg_hi:[0,0,1]
	v_pk_fma_f32 v[186:187], v[170:171], v[192:193], v[178:179] neg_lo:[0,0,1] neg_hi:[0,0,1]
	v_cvt_pk_bf16_f32 v188, v180, v181
	v_cvt_pk_bf16_f32 v189, v182, v183
	v_cvt_pk_bf16_f32 v190, v184, v185
	v_cvt_pk_bf16_f32 v191, v186, v187
	s_nop 0
	global_store_dwordx4 v[196:197], v[188:191], off
	v_add_co_u32_e32 v196, vcc, 0x1000, v196
	s_nop 1
	v_addc_co_u32_e32 v197, vcc, 0, v197, vcc
	v_lshlrev_b32_e32 v172, 16, v48
	v_and_b32_e32 v173, 0xffff0000, v48
	v_lshlrev_b32_e32 v174, 16, v49
	v_and_b32_e32 v175, 0xffff0000, v49
	v_lshlrev_b32_e32 v176, 16, v50
	v_and_b32_e32 v177, 0xffff0000, v50
	v_lshlrev_b32_e32 v178, 16, v51
	v_and_b32_e32 v179, 0xffff0000, v51
	v_pk_add_f32 v[164:165], v[164:165], v[172:173] neg_lo:[0,1] neg_hi:[0,1]
	v_pk_add_f32 v[166:167], v[166:167], v[174:175] neg_lo:[0,1] neg_hi:[0,1]
	v_pk_add_f32 v[168:169], v[168:169], v[176:177] neg_lo:[0,1] neg_hi:[0,1]
	v_pk_add_f32 v[170:171], v[170:171], v[178:179] neg_lo:[0,1] neg_hi:[0,1]
	v_lshlrev_b32_e32 v172, 16, v112
	v_and_b32_e32 v173, 0xffff0000, v112
	v_lshlrev_b32_e32 v174, 16, v113
	v_and_b32_e32 v175, 0xffff0000, v113
	v_lshlrev_b32_e32 v176, 16, v114
	v_and_b32_e32 v177, 0xffff0000, v114
	v_lshlrev_b32_e32 v178, 16, v115
	v_and_b32_e32 v179, 0xffff0000, v115
	v_pk_add_f32 v[164:165], v[164:165], v[172:173]
	v_pk_add_f32 v[166:167], v[166:167], v[174:175]
	v_pk_add_f32 v[168:169], v[168:169], v[176:177]
	v_pk_add_f32 v[170:171], v[170:171], v[178:179]
	v_pk_fma_f32 v[180:181], v[164:165], v[192:193], v[172:173] neg_lo:[0,0,1] neg_hi:[0,0,1]
	v_pk_fma_f32 v[182:183], v[166:167], v[192:193], v[174:175] neg_lo:[0,0,1] neg_hi:[0,0,1]
	v_pk_fma_f32 v[184:185], v[168:169], v[192:193], v[176:177] neg_lo:[0,0,1] neg_hi:[0,0,1]
	v_pk_fma_f32 v[186:187], v[170:171], v[192:193], v[178:179] neg_lo:[0,0,1] neg_hi:[0,0,1]
	v_cvt_pk_bf16_f32 v200, v180, v181
	v_cvt_pk_bf16_f32 v201, v182, v183
	v_cvt_pk_bf16_f32 v202, v184, v185
	v_cvt_pk_bf16_f32 v203, v186, v187
	s_nop 0
	global_store_dwordx4 v[196:197], v[200:203], off
	v_add_co_u32_e32 v196, vcc, 0x1000, v196
	s_nop 1
	v_addc_co_u32_e32 v197, vcc, 0, v197, vcc
	v_lshlrev_b32_e32 v172, 16, v52
	v_and_b32_e32 v173, 0xffff0000, v52
	v_lshlrev_b32_e32 v174, 16, v53
	v_and_b32_e32 v175, 0xffff0000, v53
	v_lshlrev_b32_e32 v176, 16, v54
	v_and_b32_e32 v177, 0xffff0000, v54
	v_lshlrev_b32_e32 v178, 16, v55
	v_and_b32_e32 v179, 0xffff0000, v55
	v_pk_add_f32 v[164:165], v[164:165], v[172:173] neg_lo:[0,1] neg_hi:[0,1]
	v_pk_add_f32 v[166:167], v[166:167], v[174:175] neg_lo:[0,1] neg_hi:[0,1]
	v_pk_add_f32 v[168:169], v[168:169], v[176:177] neg_lo:[0,1] neg_hi:[0,1]
	v_pk_add_f32 v[170:171], v[170:171], v[178:179] neg_lo:[0,1] neg_hi:[0,1]
	v_lshlrev_b32_e32 v172, 16, v116
	v_and_b32_e32 v173, 0xffff0000, v116
	v_lshlrev_b32_e32 v174, 16, v117
	v_and_b32_e32 v175, 0xffff0000, v117
	v_lshlrev_b32_e32 v176, 16, v118
	v_and_b32_e32 v177, 0xffff0000, v118
	v_lshlrev_b32_e32 v178, 16, v119
	v_and_b32_e32 v179, 0xffff0000, v119
	v_pk_add_f32 v[164:165], v[164:165], v[172:173]
	v_pk_add_f32 v[166:167], v[166:167], v[174:175]
	v_pk_add_f32 v[168:169], v[168:169], v[176:177]
	v_pk_add_f32 v[170:171], v[170:171], v[178:179]
	v_pk_fma_f32 v[180:181], v[164:165], v[192:193], v[172:173] neg_lo:[0,0,1] neg_hi:[0,0,1]
	v_pk_fma_f32 v[182:183], v[166:167], v[192:193], v[174:175] neg_lo:[0,0,1] neg_hi:[0,0,1]
	v_pk_fma_f32 v[184:185], v[168:169], v[192:193], v[176:177] neg_lo:[0,0,1] neg_hi:[0,0,1]
	v_pk_fma_f32 v[186:187], v[170:171], v[192:193], v[178:179] neg_lo:[0,0,1] neg_hi:[0,0,1]
	v_cvt_pk_bf16_f32 v188, v180, v181
	v_cvt_pk_bf16_f32 v189, v182, v183
	v_cvt_pk_bf16_f32 v190, v184, v185
	v_cvt_pk_bf16_f32 v191, v186, v187
	s_nop 0
	global_store_dwordx4 v[196:197], v[188:191], off
	v_add_co_u32_e32 v196, vcc, 0x1000, v196
	s_nop 1
	v_addc_co_u32_e32 v197, vcc, 0, v197, vcc
	v_lshlrev_b32_e32 v172, 16, v56
	v_and_b32_e32 v173, 0xffff0000, v56
	v_lshlrev_b32_e32 v174, 16, v57
	v_and_b32_e32 v175, 0xffff0000, v57
	v_lshlrev_b32_e32 v176, 16, v58
	v_and_b32_e32 v177, 0xffff0000, v58
	v_lshlrev_b32_e32 v178, 16, v59
	v_and_b32_e32 v179, 0xffff0000, v59
	v_pk_add_f32 v[164:165], v[164:165], v[172:173] neg_lo:[0,1] neg_hi:[0,1]
	v_pk_add_f32 v[166:167], v[166:167], v[174:175] neg_lo:[0,1] neg_hi:[0,1]
	v_pk_add_f32 v[168:169], v[168:169], v[176:177] neg_lo:[0,1] neg_hi:[0,1]
; __device__ __forceinline__ float bf_lo(u32 v) { return __uint_as_float(v << 16); }
; __device__ __forceinline__ float bf_hi(u32 v) { return __uint_as_float(v & 0xffff0000u); }
; #define POOL_ACC(v, sgn) do { acc0 += sgn bf_lo(v.x); acc1 += sgn bf_hi(v.x); acc2 += sgn bf_lo(v.y); acc3 += sgn bf_hi(v.y); \
;     acc4 += sgn bf_lo(v.z); acc5 += sgn bf_hi(v.z); acc6 += sgn bf_lo(v.w); acc7 += sgn bf_hi(v.w); } while (0)
; template <int WIN>
; __device__ __forceinline__ void pool_run(const u16* U, u16* PL, int tok_s, int c0) {
;   const int pos_s = tok_s & (SEQ - 1);
;   float acc0 = 0.f, acc1 = 0.f, acc2 = 0.f, acc3 = 0.f, acc4 = 0.f, acc5 = 0.f, acc6 = 0.f, acc7 = 0.f;
;   #pragma unroll
;   for (int w = 1; w < WIN; ++w) {
;     if (pos_s - w >= 0) { const uint4 v = *(const uint4*)(U + (long)(tok_s - w) * LD0 + c0); POOL_ACC(v, +); }
;   }
;   #pragma unroll
;   for (int tt = 0; tt < 16; ++tt) {
;     const int tok = tok_s + tt, pos = pos_s + tt;
;     const uint4 cur = *(const uint4*)(U + (long)tok * LD0 + c0);
;     POOL_ACC(cur, +);
;     const float ic = 1.0f / (float)min(WIN, pos + 1);
;     uint4 pk;
;     pk.x = pack2(acc0 * ic - bf_lo(cur.x), acc1 * ic - bf_hi(cur.x));
;     pk.y = pack2(acc2 * ic - bf_lo(cur.y), acc3 * ic - bf_hi(cur.y));
;     pk.z = pack2(acc4 * ic - bf_lo(cur.z), acc5 * ic - bf_hi(cur.z));
;     pk.w = pack2(acc6 * ic - bf_lo(cur.w), acc7 * ic - bf_hi(cur.w));
;     *(uint4*)(PL + (long)tok * 2048 + c0) = pk;
;     if (pos - (WIN - 1) >= 0) { const uint4 old = *(const uint4*)(U + (long)(tok - (WIN - 1)) * LD0 + c0); POOL_ACC(old, -); }
;   }
; }
	v_pk_add_f32 v[170:171], v[170:171], v[178:179] neg_lo:[0,1] neg_hi:[0,1]
	v_lshlrev_b32_e32 v172, 16, v120
	v_and_b32_e32 v173, 0xffff0000, v120
	v_lshlrev_b32_e32 v174, 16, v121
	v_and_b32_e32 v175, 0xffff0000, v121
	v_lshlrev_b32_e32 v176, 16, v122
	v_and_b32_e32 v177, 0xffff0000, v122
	v_lshlrev_b32_e32 v178, 16, v123
	v_and_b32_e32 v179, 0xffff0000, v123
	v_pk_add_f32 v[164:165], v[164:165], v[172:173]
	v_pk_add_f32 v[166:167], v[166:167], v[174:175]
	v_pk_add_f32 v[168:169], v[168:169], v[176:177]
	v_pk_add_f32 v[170:171], v[170:171], v[178:179]
	v_pk_fma_f32 v[180:181], v[164:165], v[192:193], v[172:173] neg_lo:[0,0,1] neg_hi:[0,0,1]
	v_pk_fma_f32 v[182:183], v[166:167], v[192:193], v[174:175] neg_lo:[0,0,1] neg_hi:[0,0,1]
	v_pk_fma_f32 v[184:185], v[168:169], v[192:193], v[176:177] neg_lo:[0,0,1] neg_hi:[0,0,1]
	v_pk_fma_f32 v[186:187], v[170:171], v[192:193], v[178:179] neg_lo:[0,0,1] neg_hi:[0,0,1]
	v_cvt_pk_bf16_f32 v200, v180, v181
	v_cvt_pk_bf16_f32 v201, v182, v183
	v_cvt_pk_bf16_f32 v202, v184, v185
	v_cvt_pk_bf16_f32 v203, v186, v187
	s_nop 0
	global_store_dwordx4 v[196:197], v[200:203], off
	v_add_co_u32_e32 v196, vcc, 0x1000, v196
	s_nop 1
	v_addc_co_u32_e32 v197, vcc, 0, v197, vcc
	v_lshlrev_b32_e32 v172, 16, v60
	v_and_b32_e32 v173, 0xffff0000, v60
	v_lshlrev_b32_e32 v174, 16, v61
	v_and_b32_e32 v175, 0xffff0000, v61
	v_lshlrev_b32_e32 v176, 16, v62
	v_and_b32_e32 v177, 0xffff0000, v62
	v_lshlrev_b32_e32 v178, 16, v63
	v_and_b32_e32 v179, 0xffff0000, v63
	v_pk_add_f32 v[164:165], v[164:165], v[172:173] neg_lo:[0,1] neg_hi:[0,1]
	v_pk_add_f32 v[166:167], v[166:167], v[174:175] neg_lo:[0,1] neg_hi:[0,1]
	v_pk_add_f32 v[168:169], v[168:169], v[176:177] neg_lo:[0,1] neg_hi:[0,1]
	v_pk_add_f32 v[170:171], v[170:171], v[178:179] neg_lo:[0,1] neg_hi:[0,1]
	v_lshlrev_b32_e32 v172, 16, v124
	v_and_b32_e32 v173, 0xffff0000, v124
	v_lshlrev_b32_e32 v174, 16, v125
	v_and_b32_e32 v175, 0xffff0000, v125
	v_lshlrev_b32_e32 v176, 16, v126
	v_and_b32_e32 v177, 0xffff0000, v126
	v_lshlrev_b32_e32 v178, 16, v127
	v_and_b32_e32 v179, 0xffff0000, v127
	v_pk_add_f32 v[164:165], v[164:165], v[172:173]
	v_pk_add_f32 v[166:167], v[166:167], v[174:175]
	v_pk_add_f32 v[168:169], v[168:169], v[176:177]
	v_pk_add_f32 v[170:171], v[170:171], v[178:179]
	v_pk_fma_f32 v[180:181], v[164:165], v[192:193], v[172:173] neg_lo:[0,0,1] neg_hi:[0,0,1]
	v_pk_fma_f32 v[182:183], v[166:167], v[192:193], v[174:175] neg_lo:[0,0,1] neg_hi:[0,0,1]
	v_pk_fma_f32 v[184:185], v[168:169], v[192:193], v[176:177] neg_lo:[0,0,1] neg_hi:[0,0,1]
	v_pk_fma_f32 v[186:187], v[170:171], v[192:193], v[178:179] neg_lo:[0,0,1] neg_hi:[0,0,1]
	v_cvt_pk_bf16_f32 v188, v180, v181
	v_cvt_pk_bf16_f32 v189, v182, v183
	v_cvt_pk_bf16_f32 v190, v184, v185
	v_cvt_pk_bf16_f32 v191, v186, v187
	s_nop 0
	global_store_dwordx4 v[196:197], v[188:191], off
	v_add_co_u32_e32 v196, vcc, 0x1000, v196
	s_nop 1
	v_addc_co_u32_e32 v197, vcc, 0, v197, vcc
	v_lshlrev_b32_e32 v172, 16, v64
	v_and_b32_e32 v173, 0xffff0000, v64
	v_lshlrev_b32_e32 v174, 16, v65
	v_and_b32_e32 v175, 0xffff0000, v65
	v_lshlrev_b32_e32 v176, 16, v66
	v_and_b32_e32 v177, 0xffff0000, v66
	v_lshlrev_b32_e32 v178, 16, v67
	v_and_b32_e32 v179, 0xffff0000, v67
	v_pk_add_f32 v[164:165], v[164:165], v[172:173] neg_lo:[0,1] neg_hi:[0,1]
	v_pk_add_f32 v[166:167], v[166:167], v[174:175] neg_lo:[0,1] neg_hi:[0,1]
	v_pk_add_f32 v[168:169], v[168:169], v[176:177] neg_lo:[0,1] neg_hi:[0,1]
	v_pk_add_f32 v[170:171], v[170:171], v[178:179] neg_lo:[0,1] neg_hi:[0,1]
	v_lshlrev_b32_e32 v172, 16, v128
	v_and_b32_e32 v173, 0xffff0000, v128
	v_lshlrev_b32_e32 v174, 16, v129
	v_and_b32_e32 v175, 0xffff0000, v129
	v_lshlrev_b32_e32 v176, 16, v130
	v_and_b32_e32 v177, 0xffff0000, v130
	v_lshlrev_b32_e32 v178, 16, v131
	v_and_b32_e32 v179, 0xffff0000, v131
	v_pk_add_f32 v[164:165], v[164:165], v[172:173]
	v_pk_add_f32 v[166:167], v[166:167], v[174:175]
	v_pk_add_f32 v[168:169], v[168:169], v[176:177]
	v_pk_add_f32 v[170:171], v[170:171], v[178:179]
	v_pk_fma_f32 v[180:181], v[164:165], v[192:193], v[172:173] neg_lo:[0,0,1] neg_hi:[0,0,1]
	v_pk_fma_f32 v[182:183], v[166:167], v[192:193], v[174:175] neg_lo:[0,0,1] neg_hi:[0,0,1]
	v_pk_fma_f32 v[184:185], v[168:169], v[192:193], v[176:177] neg_lo:[0,0,1] neg_hi:[0,0,1]
	v_pk_fma_f32 v[186:187], v[170:171], v[192:193], v[178:179] neg_lo:[0,0,1] neg_hi:[0,0,1]
	v_cvt_pk_bf16_f32 v200, v180, v181
	v_cvt_pk_bf16_f32 v201, v182, v183
	v_cvt_pk_bf16_f32 v202, v184, v185
	v_cvt_pk_bf16_f32 v203, v186, v187
	s_nop 0
	global_store_dwordx4 v[196:197], v[200:203], off
	v_add_co_u32_e32 v196, vcc, 0x1000, v196
	s_nop 1
	v_addc_co_u32_e32 v197, vcc, 0, v197, vcc
	v_lshlrev_b32_e32 v172, 16, v68
	v_and_b32_e32 v173, 0xffff0000, v68
	v_lshlrev_b32_e32 v174, 16, v69
	v_and_b32_e32 v175, 0xffff0000, v69
	v_lshlrev_b32_e32 v176, 16, v70
	v_and_b32_e32 v177, 0xffff0000, v70
	v_lshlrev_b32_e32 v178, 16, v71
	v_and_b32_e32 v179, 0xffff0000, v71
	v_pk_add_f32 v[164:165], v[164:165], v[172:173] neg_lo:[0,1] neg_hi:[0,1]
	v_pk_add_f32 v[166:167], v[166:167], v[174:175] neg_lo:[0,1] neg_hi:[0,1]
	v_pk_add_f32 v[168:169], v[168:169], v[176:177] neg_lo:[0,1] neg_hi:[0,1]
	v_pk_add_f32 v[170:171], v[170:171], v[178:179] neg_lo:[0,1] neg_hi:[0,1]
	v_lshlrev_b32_e32 v172, 16, v132
	v_and_b32_e32 v173, 0xffff0000, v132
	v_lshlrev_b32_e32 v174, 16, v133
	v_and_b32_e32 v175, 0xffff0000, v133
	v_lshlrev_b32_e32 v176, 16, v134
	v_and_b32_e32 v177, 0xffff0000, v134
	v_lshlrev_b32_e32 v178, 16, v135
	v_and_b32_e32 v179, 0xffff0000, v135
	v_pk_add_f32 v[164:165], v[164:165], v[172:173]
	v_pk_add_f32 v[166:167], v[166:167], v[174:175]
; __device__ __forceinline__ float bf_lo(u32 v) { return __uint_as_float(v << 16); }
; __device__ __forceinline__ float bf_hi(u32 v) { return __uint_as_float(v & 0xffff0000u); }
; #define POOL_ACC(v, sgn) do { acc0 += sgn bf_lo(v.x); acc1 += sgn bf_hi(v.x); acc2 += sgn bf_lo(v.y); acc3 += sgn bf_hi(v.y); \
;     acc4 += sgn bf_lo(v.z); acc5 += sgn bf_hi(v.z); acc6 += sgn bf_lo(v.w); acc7 += sgn bf_hi(v.w); } while (0)
; template <int WIN>
; __device__ __forceinline__ void pool_run(const u16* U, u16* PL, int tok_s, int c0) {
;   const int pos_s = tok_s & (SEQ - 1);
;   float acc0 = 0.f, acc1 = 0.f, acc2 = 0.f, acc3 = 0.f, acc4 = 0.f, acc5 = 0.f, acc6 = 0.f, acc7 = 0.f;
;   #pragma unroll
;   for (int w = 1; w < WIN; ++w) {
;     if (pos_s - w >= 0) { const uint4 v = *(const uint4*)(U + (long)(tok_s - w) * LD0 + c0); POOL_ACC(v, +); }
;   }
;   #pragma unroll
;   for (int tt = 0; tt < 16; ++tt) {
;     const int tok = tok_s + tt, pos = pos_s + tt;
;     const uint4 cur = *(const uint4*)(U + (long)tok * LD0 + c0);
;     POOL_ACC(cur, +);
;     const float ic = 1.0f / (float)min(WIN, pos + 1);
;     uint4 pk;
;     pk.x = pack2(acc0 * ic - bf_lo(cur.x), acc1 * ic - bf_hi(cur.x));
;     pk.y = pack2(acc2 * ic - bf_lo(cur.y), acc3 * ic - bf_hi(cur.y));
;     pk.z = pack2(acc4 * ic - bf_lo(cur.z), acc5 * ic - bf_hi(cur.z));
;     pk.w = pack2(acc6 * ic - bf_lo(cur.w), acc7 * ic - bf_hi(cur.w));
;     *(uint4*)(PL + (long)tok * 2048 + c0) = pk;
;     if (pos - (WIN - 1) >= 0) { const uint4 old = *(const uint4*)(U + (long)(tok - (WIN - 1)) * LD0 + c0); POOL_ACC(old, -); }
;   }
; }
	v_pk_add_f32 v[168:169], v[168:169], v[176:177]
	v_pk_add_f32 v[170:171], v[170:171], v[178:179]
	v_pk_fma_f32 v[180:181], v[164:165], v[192:193], v[172:173] neg_lo:[0,0,1] neg_hi:[0,0,1]
	v_pk_fma_f32 v[182:183], v[166:167], v[192:193], v[174:175] neg_lo:[0,0,1] neg_hi:[0,0,1]
	v_pk_fma_f32 v[184:185], v[168:169], v[192:193], v[176:177] neg_lo:[0,0,1] neg_hi:[0,0,1]
	v_pk_fma_f32 v[186:187], v[170:171], v[192:193], v[178:179] neg_lo:[0,0,1] neg_hi:[0,0,1]
	v_cvt_pk_bf16_f32 v188, v180, v181
	v_cvt_pk_bf16_f32 v189, v182, v183
	v_cvt_pk_bf16_f32 v190, v184, v185
	v_cvt_pk_bf16_f32 v191, v186, v187
	s_nop 0
	global_store_dwordx4 v[196:197], v[188:191], off
	v_add_co_u32_e32 v196, vcc, 0x1000, v196
	s_nop 1
	v_addc_co_u32_e32 v197, vcc, 0, v197, vcc
	v_lshlrev_b32_e32 v172, 16, v72
	v_and_b32_e32 v173, 0xffff0000, v72
	v_lshlrev_b32_e32 v174, 16, v73
	v_and_b32_e32 v175, 0xffff0000, v73
	v_lshlrev_b32_e32 v176, 16, v74
	v_and_b32_e32 v177, 0xffff0000, v74
	v_lshlrev_b32_e32 v178, 16, v75
	v_and_b32_e32 v179, 0xffff0000, v75
	v_pk_add_f32 v[164:165], v[164:165], v[172:173] neg_lo:[0,1] neg_hi:[0,1]
	v_pk_add_f32 v[166:167], v[166:167], v[174:175] neg_lo:[0,1] neg_hi:[0,1]
	v_pk_add_f32 v[168:169], v[168:169], v[176:177] neg_lo:[0,1] neg_hi:[0,1]
	v_pk_add_f32 v[170:171], v[170:171], v[178:179] neg_lo:[0,1] neg_hi:[0,1]
	v_lshlrev_b32_e32 v172, 16, v136
	v_and_b32_e32 v173, 0xffff0000, v136
	v_lshlrev_b32_e32 v174, 16, v137
	v_and_b32_e32 v175, 0xffff0000, v137
	v_lshlrev_b32_e32 v176, 16, v138
	v_and_b32_e32 v177, 0xffff0000, v138
	v_lshlrev_b32_e32 v178, 16, v139
	v_and_b32_e32 v179, 0xffff0000, v139
	v_pk_add_f32 v[164:165], v[164:165], v[172:173]
	v_pk_add_f32 v[166:167], v[166:167], v[174:175]
	v_pk_add_f32 v[168:169], v[168:169], v[176:177]
	v_pk_add_f32 v[170:171], v[170:171], v[178:179]
	v_pk_fma_f32 v[180:181], v[164:165], v[192:193], v[172:173] neg_lo:[0,0,1] neg_hi:[0,0,1]
	v_pk_fma_f32 v[182:183], v[166:167], v[192:193], v[174:175] neg_lo:[0,0,1] neg_hi:[0,0,1]
	v_pk_fma_f32 v[184:185], v[168:169], v[192:193], v[176:177] neg_lo:[0,0,1] neg_hi:[0,0,1]
	v_pk_fma_f32 v[186:187], v[170:171], v[192:193], v[178:179] neg_lo:[0,0,1] neg_hi:[0,0,1]
	v_cvt_pk_bf16_f32 v200, v180, v181
	v_cvt_pk_bf16_f32 v201, v182, v183
	v_cvt_pk_bf16_f32 v202, v184, v185
	v_cvt_pk_bf16_f32 v203, v186, v187
	s_nop 0
	global_store_dwordx4 v[196:197], v[200:203], off
	v_add_co_u32_e32 v196, vcc, 0x1000, v196
	s_nop 1
	v_addc_co_u32_e32 v197, vcc, 0, v197, vcc
	v_lshlrev_b32_e32 v172, 16, v76
	v_and_b32_e32 v173, 0xffff0000, v76
	v_lshlrev_b32_e32 v174, 16, v77
	v_and_b32_e32 v175, 0xffff0000, v77
	v_lshlrev_b32_e32 v176, 16, v78
	v_and_b32_e32 v177, 0xffff0000, v78
	v_lshlrev_b32_e32 v178, 16, v79
	v_and_b32_e32 v179, 0xffff0000, v79
	v_pk_add_f32 v[164:165], v[164:165], v[172:173] neg_lo:[0,1] neg_hi:[0,1]
	v_pk_add_f32 v[166:167], v[166:167], v[174:175] neg_lo:[0,1] neg_hi:[0,1]
	v_pk_add_f32 v[168:169], v[168:169], v[176:177] neg_lo:[0,1] neg_hi:[0,1]
	v_pk_add_f32 v[170:171], v[170:171], v[178:179] neg_lo:[0,1] neg_hi:[0,1]
	v_lshlrev_b32_e32 v172, 16, v144
	v_and_b32_e32 v173, 0xffff0000, v144
	v_lshlrev_b32_e32 v174, 16, v145
	v_and_b32_e32 v175, 0xffff0000, v145
	v_lshlrev_b32_e32 v176, 16, v146
	v_and_b32_e32 v177, 0xffff0000, v146
	v_lshlrev_b32_e32 v178, 16, v147
	v_and_b32_e32 v179, 0xffff0000, v147
	v_pk_add_f32 v[164:165], v[164:165], v[172:173]
	v_pk_add_f32 v[166:167], v[166:167], v[174:175]
	v_pk_add_f32 v[168:169], v[168:169], v[176:177]
	v_pk_add_f32 v[170:171], v[170:171], v[178:179]
	v_pk_fma_f32 v[180:181], v[164:165], v[192:193], v[172:173] neg_lo:[0,0,1] neg_hi:[0,0,1]
	v_pk_fma_f32 v[182:183], v[166:167], v[192:193], v[174:175] neg_lo:[0,0,1] neg_hi:[0,0,1]
	v_pk_fma_f32 v[184:185], v[168:169], v[192:193], v[176:177] neg_lo:[0,0,1] neg_hi:[0,0,1]
	v_pk_fma_f32 v[186:187], v[170:171], v[192:193], v[178:179] neg_lo:[0,0,1] neg_hi:[0,0,1]
	v_cvt_pk_bf16_f32 v188, v180, v181
	v_cvt_pk_bf16_f32 v189, v182, v183
	v_cvt_pk_bf16_f32 v190, v184, v185
	v_cvt_pk_bf16_f32 v191, v186, v187
	s_nop 0
	global_store_dwordx4 v[196:197], v[188:191], off
	v_add_co_u32_e32 v196, vcc, 0x1000, v196
	s_nop 1
	v_addc_co_u32_e32 v197, vcc, 0, v197, vcc
	v_lshlrev_b32_e32 v172, 16, v80
	v_and_b32_e32 v173, 0xffff0000, v80
	v_lshlrev_b32_e32 v174, 16, v81
	v_and_b32_e32 v175, 0xffff0000, v81
	v_lshlrev_b32_e32 v176, 16, v82
	v_and_b32_e32 v177, 0xffff0000, v82
	v_lshlrev_b32_e32 v178, 16, v83
	v_and_b32_e32 v179, 0xffff0000, v83
	v_pk_add_f32 v[164:165], v[164:165], v[172:173] neg_lo:[0,1] neg_hi:[0,1]
	v_pk_add_f32 v[166:167], v[166:167], v[174:175] neg_lo:[0,1] neg_hi:[0,1]
	v_pk_add_f32 v[168:169], v[168:169], v[176:177] neg_lo:[0,1] neg_hi:[0,1]
	v_pk_add_f32 v[170:171], v[170:171], v[178:179] neg_lo:[0,1] neg_hi:[0,1]
	v_lshlrev_b32_e32 v172, 16, v148
	v_and_b32_e32 v173, 0xffff0000, v148
	v_lshlrev_b32_e32 v174, 16, v149
	v_and_b32_e32 v175, 0xffff0000, v149
	v_lshlrev_b32_e32 v176, 16, v150
	v_and_b32_e32 v177, 0xffff0000, v150
	v_lshlrev_b32_e32 v178, 16, v151
	v_and_b32_e32 v179, 0xffff0000, v151
	v_pk_add_f32 v[164:165], v[164:165], v[172:173]
	v_pk_add_f32 v[166:167], v[166:167], v[174:175]
	v_pk_add_f32 v[168:169], v[168:169], v[176:177]
	v_pk_add_f32 v[170:171], v[170:171], v[178:179]
	v_pk_fma_f32 v[180:181], v[164:165], v[192:193], v[172:173] neg_lo:[0,0,1] neg_hi:[0,0,1]
	v_pk_fma_f32 v[182:183], v[166:167], v[192:193], v[174:175] neg_lo:[0,0,1] neg_hi:[0,0,1]
	v_pk_fma_f32 v[184:185], v[168:169], v[192:193], v[176:177] neg_lo:[0,0,1] neg_hi:[0,0,1]
	v_pk_fma_f32 v[186:187], v[170:171], v[192:193], v[178:179] neg_lo:[0,0,1] neg_hi:[0,0,1]
	v_cvt_pk_bf16_f32 v200, v180, v181
	v_cvt_pk_bf16_f32 v201, v182, v183
	v_cvt_pk_bf16_f32 v202, v184, v185
	v_cvt_pk_bf16_f32 v203, v186, v187
	s_nop 0
	global_store_dwordx4 v[196:197], v[200:203], off
	s_branch .LBB0_333
; __device__ __forceinline__ float bf_lo(u32 v) { return __uint_as_float(v << 16); }
; __device__ __forceinline__ float bf_hi(u32 v) { return __uint_as_float(v & 0xffff0000u); }
; #define POOL_ACC(v, sgn) do { acc0 += sgn bf_lo(v.x); acc1 += sgn bf_hi(v.x); acc2 += sgn bf_lo(v.y); acc3 += sgn bf_hi(v.y); \
;     acc4 += sgn bf_lo(v.z); acc5 += sgn bf_hi(v.z); acc6 += sgn bf_lo(v.w); acc7 += sgn bf_hi(v.w); } while (0)
; template <int WIN>
; __device__ __forceinline__ void pool_run(const u16* U, u16* PL, int tok_s, int c0) {
;   const int pos_s = tok_s & (SEQ - 1);
;   float acc0 = 0.f, acc1 = 0.f, acc2 = 0.f, acc3 = 0.f, acc4 = 0.f, acc5 = 0.f, acc6 = 0.f, acc7 = 0.f;
;   #pragma unroll
;   for (int w = 1; w < WIN; ++w) {
;     if (pos_s - w >= 0) { const uint4 v = *(const uint4*)(U + (long)(tok_s - w) * LD0 + c0); POOL_ACC(v, +); }
;   }
;   #pragma unroll
;   for (int tt = 0; tt < 16; ++tt) {
;     const int tok = tok_s + tt, pos = pos_s + tt;
;     const uint4 cur = *(const uint4*)(U + (long)tok * LD0 + c0);
;     POOL_ACC(cur, +);
;     const float ic = 1.0f / (float)min(WIN, pos + 1);
;     uint4 pk;
;     pk.x = pack2(acc0 * ic - bf_lo(cur.x), acc1 * ic - bf_hi(cur.x));
;     pk.y = pack2(acc2 * ic - bf_lo(cur.y), acc3 * ic - bf_hi(cur.y));
;     pk.z = pack2(acc4 * ic - bf_lo(cur.z), acc5 * ic - bf_hi(cur.z));
;     pk.w = pack2(acc6 * ic - bf_lo(cur.w), acc7 * ic - bf_hi(cur.w));
;     *(uint4*)(PL + (long)tok * 2048 + c0) = pk;
;     if (pos - (WIN - 1) >= 0) { const uint4 old = *(const uint4*)(U + (long)(tok - (WIN - 1)) * LD0 + c0); POOL_ACC(old, -); }
;   }
; }
; __device__ __forceinline__ void pool_item(const Params& p, int item, const int wv) {
;   const u16* U = (const u16*)(p.ws + OFF_PB0) + 4096;
;   u16* PL = (u16*)(p.ws + OFF_PL);
;   const int tid = opaque_tid(wv), ch = tid & 255, half = tid >> 8;
;   const int c0 = ch * 8;
;   const int tok_s = item * 32 + half * 16;
.Lpool_w8:
	v_readlane_b32 s0, v255, 20
	v_readlane_b32 s1, v255, 21
	v_lshlrev_b32_e32 v140, 1, v22
	v_add_u32_e32 v0, -7, v16
	s_nop 3
	v_lshl_add_u64 v[18:19], s[0:1], 0, v[140:141]
	v_readlane_b32 s0, v255, 22
	v_readlane_b32 s1, v255, 23
	v_ashrrev_i32_e32 v17, 31, v16
	v_lshlrev_b64 v[12:13], 12, v[16:17]
	s_nop 3
	v_lshl_add_u64 v[20:21], s[0:1], 0, v[140:141]
	v_mad_i64_i32 v[194:195], s[0:1], v0, s13, v[18:19]
	v_lshl_add_u64 v[196:197], v[20:21], 0, v[12:13]
	global_load_dwordx4 v[24:27], v[194:195], off
	v_add_co_u32_e32 v194, vcc, 0x5000, v194
	s_nop 1
	v_addc_co_u32_e32 v195, vcc, 0, v195, vcc
	global_load_dwordx4 v[28:31], v[194:195], off
	v_add_co_u32_e32 v194, vcc, 0x5000, v194
	s_nop 1
	v_addc_co_u32_e32 v195, vcc, 0, v195, vcc
	global_load_dwordx4 v[32:35], v[194:195], off
	v_add_co_u32_e32 v194, vcc, 0x5000, v194
	s_nop 1
	v_addc_co_u32_e32 v195, vcc, 0, v195, vcc
	global_load_dwordx4 v[36:39], v[194:195], off
	v_add_co_u32_e32 v194, vcc, 0x5000, v194
	s_nop 1
	v_addc_co_u32_e32 v195, vcc, 0, v195, vcc
	global_load_dwordx4 v[40:43], v[194:195], off
	v_add_co_u32_e32 v194, vcc, 0x5000, v194
	s_nop 1
	v_addc_co_u32_e32 v195, vcc, 0, v195, vcc
	global_load_dwordx4 v[44:47], v[194:195], off
	v_add_co_u32_e32 v194, vcc, 0x5000, v194
	s_nop 1
	v_addc_co_u32_e32 v195, vcc, 0, v195, vcc
	global_load_dwordx4 v[48:51], v[194:195], off
	v_add_co_u32_e32 v194, vcc, 0x5000, v194
	s_nop 1
	v_addc_co_u32_e32 v195, vcc, 0, v195, vcc
	global_load_dwordx4 v[52:55], v[194:195], off
	v_add_co_u32_e32 v194, vcc, 0x5000, v194
	s_nop 1
	v_addc_co_u32_e32 v195, vcc, 0, v195, vcc
	global_load_dwordx4 v[56:59], v[194:195], off
	v_add_co_u32_e32 v194, vcc, 0x5000, v194
	s_nop 1
	v_addc_co_u32_e32 v195, vcc, 0, v195, vcc
	global_load_dwordx4 v[60:63], v[194:195], off
	v_add_co_u32_e32 v194, vcc, 0x5000, v194
	s_nop 1
	v_addc_co_u32_e32 v195, vcc, 0, v195, vcc
	global_load_dwordx4 v[64:67], v[194:195], off
	v_add_co_u32_e32 v194, vcc, 0x5000, v194
	s_nop 1
	v_addc_co_u32_e32 v195, vcc, 0, v195, vcc
	global_load_dwordx4 v[68:71], v[194:195], off
	v_add_co_u32_e32 v194, vcc, 0x5000, v194
	s_nop 1
	v_addc_co_u32_e32 v195, vcc, 0, v195, vcc
	global_load_dwordx4 v[72:75], v[194:195], off
	v_add_co_u32_e32 v194, vcc, 0x5000, v194
	s_nop 1
	v_addc_co_u32_e32 v195, vcc, 0, v195, vcc
	global_load_dwordx4 v[76:79], v[194:195], off
	v_add_co_u32_e32 v194, vcc, 0x5000, v194
	s_nop 1
	v_addc_co_u32_e32 v195, vcc, 0, v195, vcc
	global_load_dwordx4 v[80:83], v[194:195], off
	v_add_co_u32_e32 v194, vcc, 0x5000, v194
	s_nop 1
	v_addc_co_u32_e32 v195, vcc, 0, v195, vcc
	global_load_dwordx4 v[84:87], v[194:195], off
	v_add_co_u32_e32 v194, vcc, 0x5000, v194
	s_nop 1
	v_addc_co_u32_e32 v195, vcc, 0, v195, vcc
	global_load_dwordx4 v[88:91], v[194:195], off
	v_add_co_u32_e32 v194, vcc, 0x5000, v194
	s_nop 1
	v_addc_co_u32_e32 v195, vcc, 0, v195, vcc
	global_load_dwordx4 v[92:95], v[194:195], off
	v_add_co_u32_e32 v194, vcc, 0x5000, v194
	s_nop 1
	v_addc_co_u32_e32 v195, vcc, 0, v195, vcc
	global_load_dwordx4 v[96:99], v[194:195], off
	v_add_co_u32_e32 v194, vcc, 0x5000, v194
	s_nop 1
	v_addc_co_u32_e32 v195, vcc, 0, v195, vcc
	global_load_dwordx4 v[100:103], v[194:195], off
	v_add_co_u32_e32 v194, vcc, 0x5000, v194
	s_nop 1
	v_addc_co_u32_e32 v195, vcc, 0, v195, vcc
	global_load_dwordx4 v[104:107], v[194:195], off
	v_add_co_u32_e32 v194, vcc, 0x5000, v194
	s_nop 1
	v_addc_co_u32_e32 v195, vcc, 0, v195, vcc
	global_load_dwordx4 v[108:111], v[194:195], off
	v_add_co_u32_e32 v194, vcc, 0x5000, v194
	s_nop 1
	v_addc_co_u32_e32 v195, vcc, 0, v195, vcc
	global_load_dwordx4 v[112:115], v[194:195], off
	v_mov_b32_e32 v192, 0x3e000000
	v_mov_b32_e32 v193, 0x3e000000
	v_mov_b32_e32 v164, 0
	v_mov_b32_e32 v165, 0
	v_mov_b32_e32 v166, 0
	v_mov_b32_e32 v167, 0
	v_mov_b32_e32 v168, 0
	v_mov_b32_e32 v169, 0
	v_mov_b32_e32 v170, 0
	v_mov_b32_e32 v171, 0
	s_waitcnt vmcnt(0)
	v_lshlrev_b32_e32 v172, 16, v48
	v_and_b32_e32 v173, 0xffff0000, v48
	v_lshlrev_b32_e32 v174, 16, v49
	v_and_b32_e32 v175, 0xffff0000, v49
	v_lshlrev_b32_e32 v176, 16, v50
	v_and_b32_e32 v177, 0xffff0000, v50
	v_lshlrev_b32_e32 v178, 16, v51
	v_and_b32_e32 v179, 0xffff0000, v51
	v_pk_add_f32 v[164:165], v[164:165], v[172:173]
	v_pk_add_f32 v[166:167], v[166:167], v[174:175]
	v_pk_add_f32 v[168:169], v[168:169], v[176:177]
	v_pk_add_f32 v[170:171], v[170:171], v[178:179]
	v_lshlrev_b32_e32 v172, 16, v44
	v_and_b32_e32 v173, 0xffff0000, v44
	v_lshlrev_b32_e32 v174, 16, v45
	v_and_b32_e32 v175, 0xffff0000, v45
	v_lshlrev_b32_e32 v176, 16, v46
	v_and_b32_e32 v177, 0xffff0000, v46
	v_lshlrev_b32_e32 v178, 16, v47
	v_and_b32_e32 v179, 0xffff0000, v47
	v_pk_add_f32 v[164:165], v[164:165], v[172:173]
	v_pk_add_f32 v[166:167], v[166:167], v[174:175]
	v_pk_add_f32 v[168:169], v[168:169], v[176:177]
	v_pk_add_f32 v[170:171], v[170:171], v[178:179]
	v_lshlrev_b32_e32 v172, 16, v40
	v_and_b32_e32 v173, 0xffff0000, v40
	v_lshlrev_b32_e32 v174, 16, v41
	v_and_b32_e32 v175, 0xffff0000, v41
	v_lshlrev_b32_e32 v176, 16, v42
	v_and_b32_e32 v177, 0xffff0000, v42
	v_lshlrev_b32_e32 v178, 16, v43
	v_and_b32_e32 v179, 0xffff0000, v43
	v_pk_add_f32 v[164:165], v[164:165], v[172:173]
	v_pk_add_f32 v[166:167], v[166:167], v[174:175]
	v_pk_add_f32 v[168:169], v[168:169], v[176:177]
	v_pk_add_f32 v[170:171], v[170:171], v[178:179]
	v_lshlrev_b32_e32 v172, 16, v36
	v_and_b32_e32 v173, 0xffff0000, v36
	v_lshlrev_b32_e32 v174, 16, v37
	v_and_b32_e32 v175, 0xffff0000, v37
	v_lshlrev_b32_e32 v176, 16, v38
	v_and_b32_e32 v177, 0xffff0000, v38
	v_lshlrev_b32_e32 v178, 16, v39
	v_and_b32_e32 v179, 0xffff0000, v39
	v_pk_add_f32 v[164:165], v[164:165], v[172:173]
; __device__ __forceinline__ float bf_lo(u32 v) { return __uint_as_float(v << 16); }
; __device__ __forceinline__ float bf_hi(u32 v) { return __uint_as_float(v & 0xffff0000u); }
; #define POOL_ACC(v, sgn) do { acc0 += sgn bf_lo(v.x); acc1 += sgn bf_hi(v.x); acc2 += sgn bf_lo(v.y); acc3 += sgn bf_hi(v.y); \
;     acc4 += sgn bf_lo(v.z); acc5 += sgn bf_hi(v.z); acc6 += sgn bf_lo(v.w); acc7 += sgn bf_hi(v.w); } while (0)
; template <int WIN>
; __device__ __forceinline__ void pool_run(const u16* U, u16* PL, int tok_s, int c0) {
;   const int pos_s = tok_s & (SEQ - 1);
;   float acc0 = 0.f, acc1 = 0.f, acc2 = 0.f, acc3 = 0.f, acc4 = 0.f, acc5 = 0.f, acc6 = 0.f, acc7 = 0.f;
;   #pragma unroll
;   for (int w = 1; w < WIN; ++w) {
;     if (pos_s - w >= 0) { const uint4 v = *(const uint4*)(U + (long)(tok_s - w) * LD0 + c0); POOL_ACC(v, +); }
;   }
;   #pragma unroll
;   for (int tt = 0; tt < 16; ++tt) {
;     const int tok = tok_s + tt, pos = pos_s + tt;
;     const uint4 cur = *(const uint4*)(U + (long)tok * LD0 + c0);
;     POOL_ACC(cur, +);
;     const float ic = 1.0f / (float)min(WIN, pos + 1);
;     uint4 pk;
;     pk.x = pack2(acc0 * ic - bf_lo(cur.x), acc1 * ic - bf_hi(cur.x));
;     pk.y = pack2(acc2 * ic - bf_lo(cur.y), acc3 * ic - bf_hi(cur.y));
;     pk.z = pack2(acc4 * ic - bf_lo(cur.z), acc5 * ic - bf_hi(cur.z));
;     pk.w = pack2(acc6 * ic - bf_lo(cur.w), acc7 * ic - bf_hi(cur.w));
;     *(uint4*)(PL + (long)tok * 2048 + c0) = pk;
;     if (pos - (WIN - 1) >= 0) { const uint4 old = *(const uint4*)(U + (long)(tok - (WIN - 1)) * LD0 + c0); POOL_ACC(old, -); }
;   }
; }
	v_pk_add_f32 v[166:167], v[166:167], v[174:175]
	v_pk_add_f32 v[168:169], v[168:169], v[176:177]
	v_pk_add_f32 v[170:171], v[170:171], v[178:179]
	v_lshlrev_b32_e32 v172, 16, v32
	v_and_b32_e32 v173, 0xffff0000, v32
	v_lshlrev_b32_e32 v174, 16, v33
	v_and_b32_e32 v175, 0xffff0000, v33
	v_lshlrev_b32_e32 v176, 16, v34
	v_and_b32_e32 v177, 0xffff0000, v34
	v_lshlrev_b32_e32 v178, 16, v35
	v_and_b32_e32 v179, 0xffff0000, v35
	v_pk_add_f32 v[164:165], v[164:165], v[172:173]
	v_pk_add_f32 v[166:167], v[166:167], v[174:175]
	v_pk_add_f32 v[168:169], v[168:169], v[176:177]
	v_pk_add_f32 v[170:171], v[170:171], v[178:179]
	v_lshlrev_b32_e32 v172, 16, v28
	v_and_b32_e32 v173, 0xffff0000, v28
	v_lshlrev_b32_e32 v174, 16, v29
	v_and_b32_e32 v175, 0xffff0000, v29
	v_lshlrev_b32_e32 v176, 16, v30
	v_and_b32_e32 v177, 0xffff0000, v30
	v_lshlrev_b32_e32 v178, 16, v31
	v_and_b32_e32 v179, 0xffff0000, v31
	v_pk_add_f32 v[164:165], v[164:165], v[172:173]
	v_pk_add_f32 v[166:167], v[166:167], v[174:175]
	v_pk_add_f32 v[168:169], v[168:169], v[176:177]
	v_pk_add_f32 v[170:171], v[170:171], v[178:179]
	v_lshlrev_b32_e32 v172, 16, v24
	v_and_b32_e32 v173, 0xffff0000, v24
	v_lshlrev_b32_e32 v174, 16, v25
	v_and_b32_e32 v175, 0xffff0000, v25
	v_lshlrev_b32_e32 v176, 16, v26
	v_and_b32_e32 v177, 0xffff0000, v26
	v_lshlrev_b32_e32 v178, 16, v27
	v_and_b32_e32 v179, 0xffff0000, v27
	v_pk_add_f32 v[164:165], v[164:165], v[172:173]
	v_pk_add_f32 v[166:167], v[166:167], v[174:175]
	v_pk_add_f32 v[168:169], v[168:169], v[176:177]
	v_pk_add_f32 v[170:171], v[170:171], v[178:179]
	v_lshlrev_b32_e32 v172, 16, v52
	v_and_b32_e32 v173, 0xffff0000, v52
	v_lshlrev_b32_e32 v174, 16, v53
	v_and_b32_e32 v175, 0xffff0000, v53
	v_lshlrev_b32_e32 v176, 16, v54
	v_and_b32_e32 v177, 0xffff0000, v54
	v_lshlrev_b32_e32 v178, 16, v55
	v_and_b32_e32 v179, 0xffff0000, v55
	v_pk_add_f32 v[164:165], v[164:165], v[172:173]
	v_pk_add_f32 v[166:167], v[166:167], v[174:175]
	v_pk_add_f32 v[168:169], v[168:169], v[176:177]
	v_pk_add_f32 v[170:171], v[170:171], v[178:179]
	v_pk_fma_f32 v[180:181], v[164:165], v[192:193], v[172:173] neg_lo:[0,0,1] neg_hi:[0,0,1]
	v_pk_fma_f32 v[182:183], v[166:167], v[192:193], v[174:175] neg_lo:[0,0,1] neg_hi:[0,0,1]
	v_pk_fma_f32 v[184:185], v[168:169], v[192:193], v[176:177] neg_lo:[0,0,1] neg_hi:[0,0,1]
	v_pk_fma_f32 v[186:187], v[170:171], v[192:193], v[178:179] neg_lo:[0,0,1] neg_hi:[0,0,1]
	v_cvt_pk_bf16_f32 v188, v180, v181
	v_cvt_pk_bf16_f32 v189, v182, v183
	v_cvt_pk_bf16_f32 v190, v184, v185
	v_cvt_pk_bf16_f32 v191, v186, v187
	s_nop 0
	global_store_dwordx4 v[196:197], v[188:191], off
	v_add_co_u32_e32 v196, vcc, 0x1000, v196
	s_nop 1
	v_addc_co_u32_e32 v197, vcc, 0, v197, vcc
	v_lshlrev_b32_e32 v172, 16, v24
	v_and_b32_e32 v173, 0xffff0000, v24
	v_lshlrev_b32_e32 v174, 16, v25
	v_and_b32_e32 v175, 0xffff0000, v25
	v_lshlrev_b32_e32 v176, 16, v26
	v_and_b32_e32 v177, 0xffff0000, v26
	v_lshlrev_b32_e32 v178, 16, v27
	v_and_b32_e32 v179, 0xffff0000, v27
	v_pk_add_f32 v[164:165], v[164:165], v[172:173] neg_lo:[0,1] neg_hi:[0,1]
	v_pk_add_f32 v[166:167], v[166:167], v[174:175] neg_lo:[0,1] neg_hi:[0,1]
	v_pk_add_f32 v[168:169], v[168:169], v[176:177] neg_lo:[0,1] neg_hi:[0,1]
	v_pk_add_f32 v[170:171], v[170:171], v[178:179] neg_lo:[0,1] neg_hi:[0,1]
	v_lshlrev_b32_e32 v172, 16, v56
	v_and_b32_e32 v173, 0xffff0000, v56
	v_lshlrev_b32_e32 v174, 16, v57
	v_and_b32_e32 v175, 0xffff0000, v57
	v_lshlrev_b32_e32 v176, 16, v58
	v_and_b32_e32 v177, 0xffff0000, v58
	v_lshlrev_b32_e32 v178, 16, v59
	v_and_b32_e32 v179, 0xffff0000, v59
	v_pk_add_f32 v[164:165], v[164:165], v[172:173]
	v_pk_add_f32 v[166:167], v[166:167], v[174:175]
	v_pk_add_f32 v[168:169], v[168:169], v[176:177]
	v_pk_add_f32 v[170:171], v[170:171], v[178:179]
	v_pk_fma_f32 v[180:181], v[164:165], v[192:193], v[172:173] neg_lo:[0,0,1] neg_hi:[0,0,1]
	v_pk_fma_f32 v[182:183], v[166:167], v[192:193], v[174:175] neg_lo:[0,0,1] neg_hi:[0,0,1]
	v_pk_fma_f32 v[184:185], v[168:169], v[192:193], v[176:177] neg_lo:[0,0,1] neg_hi:[0,0,1]
	v_pk_fma_f32 v[186:187], v[170:171], v[192:193], v[178:179] neg_lo:[0,0,1] neg_hi:[0,0,1]
	v_cvt_pk_bf16_f32 v200, v180, v181
	v_cvt_pk_bf16_f32 v201, v182, v183
	v_cvt_pk_bf16_f32 v202, v184, v185
	v_cvt_pk_bf16_f32 v203, v186, v187
	s_nop 0
	global_store_dwordx4 v[196:197], v[200:203], off
	v_add_co_u32_e32 v196, vcc, 0x1000, v196
	s_nop 1
	v_addc_co_u32_e32 v197, vcc, 0, v197, vcc
	v_lshlrev_b32_e32 v172, 16, v28
	v_and_b32_e32 v173, 0xffff0000, v28
	v_lshlrev_b32_e32 v174, 16, v29
	v_and_b32_e32 v175, 0xffff0000, v29
	v_lshlrev_b32_e32 v176, 16, v30
	v_and_b32_e32 v177, 0xffff0000, v30
	v_lshlrev_b32_e32 v178, 16, v31
	v_and_b32_e32 v179, 0xffff0000, v31
	v_pk_add_f32 v[164:165], v[164:165], v[172:173] neg_lo:[0,1] neg_hi:[0,1]
	v_pk_add_f32 v[166:167], v[166:167], v[174:175] neg_lo:[0,1] neg_hi:[0,1]
	v_pk_add_f32 v[168:169], v[168:169], v[176:177] neg_lo:[0,1] neg_hi:[0,1]
	v_pk_add_f32 v[170:171], v[170:171], v[178:179] neg_lo:[0,1] neg_hi:[0,1]
	v_lshlrev_b32_e32 v172, 16, v60
	v_and_b32_e32 v173, 0xffff0000, v60
	v_lshlrev_b32_e32 v174, 16, v61
	v_and_b32_e32 v175, 0xffff0000, v61
	v_lshlrev_b32_e32 v176, 16, v62
	v_and_b32_e32 v177, 0xffff0000, v62
	v_lshlrev_b32_e32 v178, 16, v63
	v_and_b32_e32 v179, 0xffff0000, v63
	v_pk_add_f32 v[164:165], v[164:165], v[172:173]
	v_pk_add_f32 v[166:167], v[166:167], v[174:175]
	v_pk_add_f32 v[168:169], v[168:169], v[176:177]
	v_pk_add_f32 v[170:171], v[170:171], v[178:179]
	v_pk_fma_f32 v[180:181], v[164:165], v[192:193], v[172:173] neg_lo:[0,0,1] neg_hi:[0,0,1]
	v_pk_fma_f32 v[182:183], v[166:167], v[192:193], v[174:175] neg_lo:[0,0,1] neg_hi:[0,0,1]
; __device__ __forceinline__ float bf_lo(u32 v) { return __uint_as_float(v << 16); }
; __device__ __forceinline__ float bf_hi(u32 v) { return __uint_as_float(v & 0xffff0000u); }
; #define POOL_ACC(v, sgn) do { acc0 += sgn bf_lo(v.x); acc1 += sgn bf_hi(v.x); acc2 += sgn bf_lo(v.y); acc3 += sgn bf_hi(v.y); \
;     acc4 += sgn bf_lo(v.z); acc5 += sgn bf_hi(v.z); acc6 += sgn bf_lo(v.w); acc7 += sgn bf_hi(v.w); } while (0)
; template <int WIN>
; __device__ __forceinline__ void pool_run(const u16* U, u16* PL, int tok_s, int c0) {
;   const int pos_s = tok_s & (SEQ - 1);
;   float acc0 = 0.f, acc1 = 0.f, acc2 = 0.f, acc3 = 0.f, acc4 = 0.f, acc5 = 0.f, acc6 = 0.f, acc7 = 0.f;
;   #pragma unroll
;   for (int w = 1; w < WIN; ++w) {
;     if (pos_s - w >= 0) { const uint4 v = *(const uint4*)(U + (long)(tok_s - w) * LD0 + c0); POOL_ACC(v, +); }
;   }
;   #pragma unroll
;   for (int tt = 0; tt < 16; ++tt) {
;     const int tok = tok_s + tt, pos = pos_s + tt;
;     const uint4 cur = *(const uint4*)(U + (long)tok * LD0 + c0);
;     POOL_ACC(cur, +);
;     const float ic = 1.0f / (float)min(WIN, pos + 1);
;     uint4 pk;
;     pk.x = pack2(acc0 * ic - bf_lo(cur.x), acc1 * ic - bf_hi(cur.x));
;     pk.y = pack2(acc2 * ic - bf_lo(cur.y), acc3 * ic - bf_hi(cur.y));
;     pk.z = pack2(acc4 * ic - bf_lo(cur.z), acc5 * ic - bf_hi(cur.z));
;     pk.w = pack2(acc6 * ic - bf_lo(cur.w), acc7 * ic - bf_hi(cur.w));
;     *(uint4*)(PL + (long)tok * 2048 + c0) = pk;
;     if (pos - (WIN - 1) >= 0) { const uint4 old = *(const uint4*)(U + (long)(tok - (WIN - 1)) * LD0 + c0); POOL_ACC(old, -); }
;   }
; }
	v_pk_fma_f32 v[184:185], v[168:169], v[192:193], v[176:177] neg_lo:[0,0,1] neg_hi:[0,0,1]
	v_pk_fma_f32 v[186:187], v[170:171], v[192:193], v[178:179] neg_lo:[0,0,1] neg_hi:[0,0,1]
	v_cvt_pk_bf16_f32 v188, v180, v181
	v_cvt_pk_bf16_f32 v189, v182, v183
	v_cvt_pk_bf16_f32 v190, v184, v185
	v_cvt_pk_bf16_f32 v191, v186, v187
	s_nop 0
	global_store_dwordx4 v[196:197], v[188:191], off
	v_add_co_u32_e32 v196, vcc, 0x1000, v196
	s_nop 1
	v_addc_co_u32_e32 v197, vcc, 0, v197, vcc
	v_lshlrev_b32_e32 v172, 16, v32
	v_and_b32_e32 v173, 0xffff0000, v32
	v_lshlrev_b32_e32 v174, 16, v33
	v_and_b32_e32 v175, 0xffff0000, v33
	v_lshlrev_b32_e32 v176, 16, v34
	v_and_b32_e32 v177, 0xffff0000, v34
	v_lshlrev_b32_e32 v178, 16, v35
	v_and_b32_e32 v179, 0xffff0000, v35
	v_pk_add_f32 v[164:165], v[164:165], v[172:173] neg_lo:[0,1] neg_hi:[0,1]
	v_pk_add_f32 v[166:167], v[166:167], v[174:175] neg_lo:[0,1] neg_hi:[0,1]
	v_pk_add_f32 v[168:169], v[168:169], v[176:177] neg_lo:[0,1] neg_hi:[0,1]
	v_pk_add_f32 v[170:171], v[170:171], v[178:179] neg_lo:[0,1] neg_hi:[0,1]
	v_lshlrev_b32_e32 v172, 16, v64
	v_and_b32_e32 v173, 0xffff0000, v64
	v_lshlrev_b32_e32 v174, 16, v65
	v_and_b32_e32 v175, 0xffff0000, v65
	v_lshlrev_b32_e32 v176, 16, v66
	v_and_b32_e32 v177, 0xffff0000, v66
	v_lshlrev_b32_e32 v178, 16, v67
	v_and_b32_e32 v179, 0xffff0000, v67
	v_pk_add_f32 v[164:165], v[164:165], v[172:173]
	v_pk_add_f32 v[166:167], v[166:167], v[174:175]
	v_pk_add_f32 v[168:169], v[168:169], v[176:177]
	v_pk_add_f32 v[170:171], v[170:171], v[178:179]
	v_pk_fma_f32 v[180:181], v[164:165], v[192:193], v[172:173] neg_lo:[0,0,1] neg_hi:[0,0,1]
	v_pk_fma_f32 v[182:183], v[166:167], v[192:193], v[174:175] neg_lo:[0,0,1] neg_hi:[0,0,1]
	v_pk_fma_f32 v[184:185], v[168:169], v[192:193], v[176:177] neg_lo:[0,0,1] neg_hi:[0,0,1]
	v_pk_fma_f32 v[186:187], v[170:171], v[192:193], v[178:179] neg_lo:[0,0,1] neg_hi:[0,0,1]
	v_cvt_pk_bf16_f32 v200, v180, v181
	v_cvt_pk_bf16_f32 v201, v182, v183
	v_cvt_pk_bf16_f32 v202, v184, v185
	v_cvt_pk_bf16_f32 v203, v186, v187
	s_nop 0
	global_store_dwordx4 v[196:197], v[200:203], off
	v_add_co_u32_e32 v196, vcc, 0x1000, v196
	s_nop 1
	v_addc_co_u32_e32 v197, vcc, 0, v197, vcc
	v_lshlrev_b32_e32 v172, 16, v36
	v_and_b32_e32 v173, 0xffff0000, v36
	v_lshlrev_b32_e32 v174, 16, v37
	v_and_b32_e32 v175, 0xffff0000, v37
	v_lshlrev_b32_e32 v176, 16, v38
	v_and_b32_e32 v177, 0xffff0000, v38
	v_lshlrev_b32_e32 v178, 16, v39
	v_and_b32_e32 v179, 0xffff0000, v39
	v_pk_add_f32 v[164:165], v[164:165], v[172:173] neg_lo:[0,1] neg_hi:[0,1]
	v_pk_add_f32 v[166:167], v[166:167], v[174:175] neg_lo:[0,1] neg_hi:[0,1]
	v_pk_add_f32 v[168:169], v[168:169], v[176:177] neg_lo:[0,1] neg_hi:[0,1]
	v_pk_add_f32 v[170:171], v[170:171], v[178:179] neg_lo:[0,1] neg_hi:[0,1]
	v_lshlrev_b32_e32 v172, 16, v68
	v_and_b32_e32 v173, 0xffff0000, v68
	v_lshlrev_b32_e32 v174, 16, v69
	v_and_b32_e32 v175, 0xffff0000, v69
	v_lshlrev_b32_e32 v176, 16, v70
	v_and_b32_e32 v177, 0xffff0000, v70
	v_lshlrev_b32_e32 v178, 16, v71
	v_and_b32_e32 v179, 0xffff0000, v71
	v_pk_add_f32 v[164:165], v[164:165], v[172:173]
	v_pk_add_f32 v[166:167], v[166:167], v[174:175]
	v_pk_add_f32 v[168:169], v[168:169], v[176:177]
	v_pk_add_f32 v[170:171], v[170:171], v[178:179]
	v_pk_fma_f32 v[180:181], v[164:165], v[192:193], v[172:173] neg_lo:[0,0,1] neg_hi:[0,0,1]
	v_pk_fma_f32 v[182:183], v[166:167], v[192:193], v[174:175] neg_lo:[0,0,1] neg_hi:[0,0,1]
	v_pk_fma_f32 v[184:185], v[168:169], v[192:193], v[176:177] neg_lo:[0,0,1] neg_hi:[0,0,1]
	v_pk_fma_f32 v[186:187], v[170:171], v[192:193], v[178:179] neg_lo:[0,0,1] neg_hi:[0,0,1]
	v_cvt_pk_bf16_f32 v188, v180, v181
	v_cvt_pk_bf16_f32 v189, v182, v183
	v_cvt_pk_bf16_f32 v190, v184, v185
	v_cvt_pk_bf16_f32 v191, v186, v187
	s_nop 0
	global_store_dwordx4 v[196:197], v[188:191], off
	v_add_co_u32_e32 v196, vcc, 0x1000, v196
	s_nop 1
	v_addc_co_u32_e32 v197, vcc, 0, v197, vcc
	v_lshlrev_b32_e32 v172, 16, v40
	v_and_b32_e32 v173, 0xffff0000, v40
	v_lshlrev_b32_e32 v174, 16, v41
	v_and_b32_e32 v175, 0xffff0000, v41
	v_lshlrev_b32_e32 v176, 16, v42
	v_and_b32_e32 v177, 0xffff0000, v42
	v_lshlrev_b32_e32 v178, 16, v43
	v_and_b32_e32 v179, 0xffff0000, v43
	v_pk_add_f32 v[164:165], v[164:165], v[172:173] neg_lo:[0,1] neg_hi:[0,1]
	v_pk_add_f32 v[166:167], v[166:167], v[174:175] neg_lo:[0,1] neg_hi:[0,1]
	v_pk_add_f32 v[168:169], v[168:169], v[176:177] neg_lo:[0,1] neg_hi:[0,1]
	v_pk_add_f32 v[170:171], v[170:171], v[178:179] neg_lo:[0,1] neg_hi:[0,1]
	v_lshlrev_b32_e32 v172, 16, v72
	v_and_b32_e32 v173, 0xffff0000, v72
	v_lshlrev_b32_e32 v174, 16, v73
	v_and_b32_e32 v175, 0xffff0000, v73
	v_lshlrev_b32_e32 v176, 16, v74
	v_and_b32_e32 v177, 0xffff0000, v74
	v_lshlrev_b32_e32 v178, 16, v75
	v_and_b32_e32 v179, 0xffff0000, v75
	v_pk_add_f32 v[164:165], v[164:165], v[172:173]
	v_pk_add_f32 v[166:167], v[166:167], v[174:175]
	v_pk_add_f32 v[168:169], v[168:169], v[176:177]
	v_pk_add_f32 v[170:171], v[170:171], v[178:179]
	v_pk_fma_f32 v[180:181], v[164:165], v[192:193], v[172:173] neg_lo:[0,0,1] neg_hi:[0,0,1]
	v_pk_fma_f32 v[182:183], v[166:167], v[192:193], v[174:175] neg_lo:[0,0,1] neg_hi:[0,0,1]
	v_pk_fma_f32 v[184:185], v[168:169], v[192:193], v[176:177] neg_lo:[0,0,1] neg_hi:[0,0,1]
	v_pk_fma_f32 v[186:187], v[170:171], v[192:193], v[178:179] neg_lo:[0,0,1] neg_hi:[0,0,1]
	v_cvt_pk_bf16_f32 v200, v180, v181
	v_cvt_pk_bf16_f32 v201, v182, v183
	v_cvt_pk_bf16_f32 v202, v184, v185
	v_cvt_pk_bf16_f32 v203, v186, v187
	s_nop 0
	global_store_dwordx4 v[196:197], v[200:203], off
	v_add_co_u32_e32 v196, vcc, 0x1000, v196
	s_nop 1
	v_addc_co_u32_e32 v197, vcc, 0, v197, vcc
; __device__ __forceinline__ float bf_lo(u32 v) { return __uint_as_float(v << 16); }
; __device__ __forceinline__ float bf_hi(u32 v) { return __uint_as_float(v & 0xffff0000u); }
; #define POOL_ACC(v, sgn) do { acc0 += sgn bf_lo(v.x); acc1 += sgn bf_hi(v.x); acc2 += sgn bf_lo(v.y); acc3 += sgn bf_hi(v.y); \
;     acc4 += sgn bf_lo(v.z); acc5 += sgn bf_hi(v.z); acc6 += sgn bf_lo(v.w); acc7 += sgn bf_hi(v.w); } while (0)
; template <int WIN>
; __device__ __forceinline__ void pool_run(const u16* U, u16* PL, int tok_s, int c0) {
;   const int pos_s = tok_s & (SEQ - 1);
;   float acc0 = 0.f, acc1 = 0.f, acc2 = 0.f, acc3 = 0.f, acc4 = 0.f, acc5 = 0.f, acc6 = 0.f, acc7 = 0.f;
;   #pragma unroll
;   for (int w = 1; w < WIN; ++w) {
;     if (pos_s - w >= 0) { const uint4 v = *(const uint4*)(U + (long)(tok_s - w) * LD0 + c0); POOL_ACC(v, +); }
;   }
;   #pragma unroll
;   for (int tt = 0; tt < 16; ++tt) {
;     const int tok = tok_s + tt, pos = pos_s + tt;
;     const uint4 cur = *(const uint4*)(U + (long)tok * LD0 + c0);
;     POOL_ACC(cur, +);
;     const float ic = 1.0f / (float)min(WIN, pos + 1);
;     uint4 pk;
;     pk.x = pack2(acc0 * ic - bf_lo(cur.x), acc1 * ic - bf_hi(cur.x));
;     pk.y = pack2(acc2 * ic - bf_lo(cur.y), acc3 * ic - bf_hi(cur.y));
;     pk.z = pack2(acc4 * ic - bf_lo(cur.z), acc5 * ic - bf_hi(cur.z));
;     pk.w = pack2(acc6 * ic - bf_lo(cur.w), acc7 * ic - bf_hi(cur.w));
;     *(uint4*)(PL + (long)tok * 2048 + c0) = pk;
;     if (pos - (WIN - 1) >= 0) { const uint4 old = *(const uint4*)(U + (long)(tok - (WIN - 1)) * LD0 + c0); POOL_ACC(old, -); }
;   }
; }
	v_lshlrev_b32_e32 v172, 16, v44
	v_and_b32_e32 v173, 0xffff0000, v44
	v_lshlrev_b32_e32 v174, 16, v45
	v_and_b32_e32 v175, 0xffff0000, v45
	v_lshlrev_b32_e32 v176, 16, v46
	v_and_b32_e32 v177, 0xffff0000, v46
	v_lshlrev_b32_e32 v178, 16, v47
	v_and_b32_e32 v179, 0xffff0000, v47
	v_pk_add_f32 v[164:165], v[164:165], v[172:173] neg_lo:[0,1] neg_hi:[0,1]
	v_pk_add_f32 v[166:167], v[166:167], v[174:175] neg_lo:[0,1] neg_hi:[0,1]
	v_pk_add_f32 v[168:169], v[168:169], v[176:177] neg_lo:[0,1] neg_hi:[0,1]
	v_pk_add_f32 v[170:171], v[170:171], v[178:179] neg_lo:[0,1] neg_hi:[0,1]
	v_lshlrev_b32_e32 v172, 16, v76
	v_and_b32_e32 v173, 0xffff0000, v76
	v_lshlrev_b32_e32 v174, 16, v77
	v_and_b32_e32 v175, 0xffff0000, v77
	v_lshlrev_b32_e32 v176, 16, v78
	v_and_b32_e32 v177, 0xffff0000, v78
	v_lshlrev_b32_e32 v178, 16, v79
	v_and_b32_e32 v179, 0xffff0000, v79
	v_pk_add_f32 v[164:165], v[164:165], v[172:173]
	v_pk_add_f32 v[166:167], v[166:167], v[174:175]
	v_pk_add_f32 v[168:169], v[168:169], v[176:177]
	v_pk_add_f32 v[170:171], v[170:171], v[178:179]
	v_pk_fma_f32 v[180:181], v[164:165], v[192:193], v[172:173] neg_lo:[0,0,1] neg_hi:[0,0,1]
	v_pk_fma_f32 v[182:183], v[166:167], v[192:193], v[174:175] neg_lo:[0,0,1] neg_hi:[0,0,1]
	v_pk_fma_f32 v[184:185], v[168:169], v[192:193], v[176:177] neg_lo:[0,0,1] neg_hi:[0,0,1]
	v_pk_fma_f32 v[186:187], v[170:171], v[192:193], v[178:179] neg_lo:[0,0,1] neg_hi:[0,0,1]
	v_cvt_pk_bf16_f32 v188, v180, v181
	v_cvt_pk_bf16_f32 v189, v182, v183
	v_cvt_pk_bf16_f32 v190, v184, v185
	v_cvt_pk_bf16_f32 v191, v186, v187
	s_nop 0
	global_store_dwordx4 v[196:197], v[188:191], off
	v_add_co_u32_e32 v196, vcc, 0x1000, v196
	s_nop 1
	v_addc_co_u32_e32 v197, vcc, 0, v197, vcc
	v_lshlrev_b32_e32 v172, 16, v48
	v_and_b32_e32 v173, 0xffff0000, v48
	v_lshlrev_b32_e32 v174, 16, v49
	v_and_b32_e32 v175, 0xffff0000, v49
	v_lshlrev_b32_e32 v176, 16, v50
	v_and_b32_e32 v177, 0xffff0000, v50
	v_lshlrev_b32_e32 v178, 16, v51
	v_and_b32_e32 v179, 0xffff0000, v51
	v_pk_add_f32 v[164:165], v[164:165], v[172:173] neg_lo:[0,1] neg_hi:[0,1]
	v_pk_add_f32 v[166:167], v[166:167], v[174:175] neg_lo:[0,1] neg_hi:[0,1]
	v_pk_add_f32 v[168:169], v[168:169], v[176:177] neg_lo:[0,1] neg_hi:[0,1]
	v_pk_add_f32 v[170:171], v[170:171], v[178:179] neg_lo:[0,1] neg_hi:[0,1]
	v_lshlrev_b32_e32 v172, 16, v80
	v_and_b32_e32 v173, 0xffff0000, v80
	v_lshlrev_b32_e32 v174, 16, v81
	v_and_b32_e32 v175, 0xffff0000, v81
	v_lshlrev_b32_e32 v176, 16, v82
	v_and_b32_e32 v177, 0xffff0000, v82
	v_lshlrev_b32_e32 v178, 16, v83
	v_and_b32_e32 v179, 0xffff0000, v83
	v_pk_add_f32 v[164:165], v[164:165], v[172:173]
	v_pk_add_f32 v[166:167], v[166:167], v[174:175]
	v_pk_add_f32 v[168:169], v[168:169], v[176:177]
	v_pk_add_f32 v[170:171], v[170:171], v[178:179]
	v_pk_fma_f32 v[180:181], v[164:165], v[192:193], v[172:173] neg_lo:[0,0,1] neg_hi:[0,0,1]
	v_pk_fma_f32 v[182:183], v[166:167], v[192:193], v[174:175] neg_lo:[0,0,1] neg_hi:[0,0,1]
	v_pk_fma_f32 v[184:185], v[168:169], v[192:193], v[176:177] neg_lo:[0,0,1] neg_hi:[0,0,1]
	v_pk_fma_f32 v[186:187], v[170:171], v[192:193], v[178:179] neg_lo:[0,0,1] neg_hi:[0,0,1]
	v_cvt_pk_bf16_f32 v200, v180, v181
	v_cvt_pk_bf16_f32 v201, v182, v183
	v_cvt_pk_bf16_f32 v202, v184, v185
	v_cvt_pk_bf16_f32 v203, v186, v187
	s_nop 0
	global_store_dwordx4 v[196:197], v[200:203], off
	v_add_co_u32_e32 v196, vcc, 0x1000, v196
	s_nop 1
	v_addc_co_u32_e32 v197, vcc, 0, v197, vcc
	v_lshlrev_b32_e32 v172, 16, v52
	v_and_b32_e32 v173, 0xffff0000, v52
	v_lshlrev_b32_e32 v174, 16, v53
	v_and_b32_e32 v175, 0xffff0000, v53
	v_lshlrev_b32_e32 v176, 16, v54
	v_and_b32_e32 v177, 0xffff0000, v54
	v_lshlrev_b32_e32 v178, 16, v55
	v_and_b32_e32 v179, 0xffff0000, v55
	v_pk_add_f32 v[164:165], v[164:165], v[172:173] neg_lo:[0,1] neg_hi:[0,1]
	v_pk_add_f32 v[166:167], v[166:167], v[174:175] neg_lo:[0,1] neg_hi:[0,1]
	v_pk_add_f32 v[168:169], v[168:169], v[176:177] neg_lo:[0,1] neg_hi:[0,1]
	v_pk_add_f32 v[170:171], v[170:171], v[178:179] neg_lo:[0,1] neg_hi:[0,1]
	v_lshlrev_b32_e32 v172, 16, v84
	v_and_b32_e32 v173, 0xffff0000, v84
	v_lshlrev_b32_e32 v174, 16, v85
	v_and_b32_e32 v175, 0xffff0000, v85
	v_lshlrev_b32_e32 v176, 16, v86
	v_and_b32_e32 v177, 0xffff0000, v86
	v_lshlrev_b32_e32 v178, 16, v87
	v_and_b32_e32 v179, 0xffff0000, v87
	v_pk_add_f32 v[164:165], v[164:165], v[172:173]
	v_pk_add_f32 v[166:167], v[166:167], v[174:175]
	v_pk_add_f32 v[168:169], v[168:169], v[176:177]
	v_pk_add_f32 v[170:171], v[170:171], v[178:179]
	v_pk_fma_f32 v[180:181], v[164:165], v[192:193], v[172:173] neg_lo:[0,0,1] neg_hi:[0,0,1]
	v_pk_fma_f32 v[182:183], v[166:167], v[192:193], v[174:175] neg_lo:[0,0,1] neg_hi:[0,0,1]
	v_pk_fma_f32 v[184:185], v[168:169], v[192:193], v[176:177] neg_lo:[0,0,1] neg_hi:[0,0,1]
	v_pk_fma_f32 v[186:187], v[170:171], v[192:193], v[178:179] neg_lo:[0,0,1] neg_hi:[0,0,1]
	v_cvt_pk_bf16_f32 v188, v180, v181
	v_cvt_pk_bf16_f32 v189, v182, v183
	v_cvt_pk_bf16_f32 v190, v184, v185
	v_cvt_pk_bf16_f32 v191, v186, v187
	s_nop 0
	global_store_dwordx4 v[196:197], v[188:191], off
	v_add_co_u32_e32 v196, vcc, 0x1000, v196
	s_nop 1
	v_addc_co_u32_e32 v197, vcc, 0, v197, vcc
	v_lshlrev_b32_e32 v172, 16, v56
	v_and_b32_e32 v173, 0xffff0000, v56
	v_lshlrev_b32_e32 v174, 16, v57
	v_and_b32_e32 v175, 0xffff0000, v57
	v_lshlrev_b32_e32 v176, 16, v58
	v_and_b32_e32 v177, 0xffff0000, v58
	v_lshlrev_b32_e32 v178, 16, v59
	v_and_b32_e32 v179, 0xffff0000, v59
	v_pk_add_f32 v[164:165], v[164:165], v[172:173] neg_lo:[0,1] neg_hi:[0,1]
	v_pk_add_f32 v[166:167], v[166:167], v[174:175] neg_lo:[0,1] neg_hi:[0,1]
	v_pk_add_f32 v[168:169], v[168:169], v[176:177] neg_lo:[0,1] neg_hi:[0,1]
; __device__ __forceinline__ float bf_lo(u32 v) { return __uint_as_float(v << 16); }
; __device__ __forceinline__ float bf_hi(u32 v) { return __uint_as_float(v & 0xffff0000u); }
; #define POOL_ACC(v, sgn) do { acc0 += sgn bf_lo(v.x); acc1 += sgn bf_hi(v.x); acc2 += sgn bf_lo(v.y); acc3 += sgn bf_hi(v.y); \
;     acc4 += sgn bf_lo(v.z); acc5 += sgn bf_hi(v.z); acc6 += sgn bf_lo(v.w); acc7 += sgn bf_hi(v.w); } while (0)
; template <int WIN>
; __device__ __forceinline__ void pool_run(const u16* U, u16* PL, int tok_s, int c0) {
;   const int pos_s = tok_s & (SEQ - 1);
;   float acc0 = 0.f, acc1 = 0.f, acc2 = 0.f, acc3 = 0.f, acc4 = 0.f, acc5 = 0.f, acc6 = 0.f, acc7 = 0.f;
;   #pragma unroll
;   for (int w = 1; w < WIN; ++w) {
;     if (pos_s - w >= 0) { const uint4 v = *(const uint4*)(U + (long)(tok_s - w) * LD0 + c0); POOL_ACC(v, +); }
;   }
;   #pragma unroll
;   for (int tt = 0; tt < 16; ++tt) {
;     const int tok = tok_s + tt, pos = pos_s + tt;
;     const uint4 cur = *(const uint4*)(U + (long)tok * LD0 + c0);
;     POOL_ACC(cur, +);
;     const float ic = 1.0f / (float)min(WIN, pos + 1);
;     uint4 pk;
;     pk.x = pack2(acc0 * ic - bf_lo(cur.x), acc1 * ic - bf_hi(cur.x));
;     pk.y = pack2(acc2 * ic - bf_lo(cur.y), acc3 * ic - bf_hi(cur.y));
;     pk.z = pack2(acc4 * ic - bf_lo(cur.z), acc5 * ic - bf_hi(cur.z));
;     pk.w = pack2(acc6 * ic - bf_lo(cur.w), acc7 * ic - bf_hi(cur.w));
;     *(uint4*)(PL + (long)tok * 2048 + c0) = pk;
;     if (pos - (WIN - 1) >= 0) { const uint4 old = *(const uint4*)(U + (long)(tok - (WIN - 1)) * LD0 + c0); POOL_ACC(old, -); }
;   }
; }
	v_pk_add_f32 v[170:171], v[170:171], v[178:179] neg_lo:[0,1] neg_hi:[0,1]
	v_lshlrev_b32_e32 v172, 16, v88
	v_and_b32_e32 v173, 0xffff0000, v88
	v_lshlrev_b32_e32 v174, 16, v89
	v_and_b32_e32 v175, 0xffff0000, v89
	v_lshlrev_b32_e32 v176, 16, v90
	v_and_b32_e32 v177, 0xffff0000, v90
	v_lshlrev_b32_e32 v178, 16, v91
	v_and_b32_e32 v179, 0xffff0000, v91
	v_pk_add_f32 v[164:165], v[164:165], v[172:173]
	v_pk_add_f32 v[166:167], v[166:167], v[174:175]
	v_pk_add_f32 v[168:169], v[168:169], v[176:177]
	v_pk_add_f32 v[170:171], v[170:171], v[178:179]
	v_pk_fma_f32 v[180:181], v[164:165], v[192:193], v[172:173] neg_lo:[0,0,1] neg_hi:[0,0,1]
	v_pk_fma_f32 v[182:183], v[166:167], v[192:193], v[174:175] neg_lo:[0,0,1] neg_hi:[0,0,1]
	v_pk_fma_f32 v[184:185], v[168:169], v[192:193], v[176:177] neg_lo:[0,0,1] neg_hi:[0,0,1]
	v_pk_fma_f32 v[186:187], v[170:171], v[192:193], v[178:179] neg_lo:[0,0,1] neg_hi:[0,0,1]
	v_cvt_pk_bf16_f32 v200, v180, v181
	v_cvt_pk_bf16_f32 v201, v182, v183
	v_cvt_pk_bf16_f32 v202, v184, v185
	v_cvt_pk_bf16_f32 v203, v186, v187
	s_nop 0
	global_store_dwordx4 v[196:197], v[200:203], off
	v_add_co_u32_e32 v196, vcc, 0x1000, v196
	s_nop 1
	v_addc_co_u32_e32 v197, vcc, 0, v197, vcc
	v_lshlrev_b32_e32 v172, 16, v60
	v_and_b32_e32 v173, 0xffff0000, v60
	v_lshlrev_b32_e32 v174, 16, v61
	v_and_b32_e32 v175, 0xffff0000, v61
	v_lshlrev_b32_e32 v176, 16, v62
	v_and_b32_e32 v177, 0xffff0000, v62
	v_lshlrev_b32_e32 v178, 16, v63
	v_and_b32_e32 v179, 0xffff0000, v63
	v_pk_add_f32 v[164:165], v[164:165], v[172:173] neg_lo:[0,1] neg_hi:[0,1]
	v_pk_add_f32 v[166:167], v[166:167], v[174:175] neg_lo:[0,1] neg_hi:[0,1]
	v_pk_add_f32 v[168:169], v[168:169], v[176:177] neg_lo:[0,1] neg_hi:[0,1]
	v_pk_add_f32 v[170:171], v[170:171], v[178:179] neg_lo:[0,1] neg_hi:[0,1]
	v_lshlrev_b32_e32 v172, 16, v92
	v_and_b32_e32 v173, 0xffff0000, v92
	v_lshlrev_b32_e32 v174, 16, v93
	v_and_b32_e32 v175, 0xffff0000, v93
	v_lshlrev_b32_e32 v176, 16, v94
	v_and_b32_e32 v177, 0xffff0000, v94
	v_lshlrev_b32_e32 v178, 16, v95
	v_and_b32_e32 v179, 0xffff0000, v95
	v_pk_add_f32 v[164:165], v[164:165], v[172:173]
	v_pk_add_f32 v[166:167], v[166:167], v[174:175]
	v_pk_add_f32 v[168:169], v[168:169], v[176:177]
	v_pk_add_f32 v[170:171], v[170:171], v[178:179]
	v_pk_fma_f32 v[180:181], v[164:165], v[192:193], v[172:173] neg_lo:[0,0,1] neg_hi:[0,0,1]
	v_pk_fma_f32 v[182:183], v[166:167], v[192:193], v[174:175] neg_lo:[0,0,1] neg_hi:[0,0,1]
	v_pk_fma_f32 v[184:185], v[168:169], v[192:193], v[176:177] neg_lo:[0,0,1] neg_hi:[0,0,1]
	v_pk_fma_f32 v[186:187], v[170:171], v[192:193], v[178:179] neg_lo:[0,0,1] neg_hi:[0,0,1]
	v_cvt_pk_bf16_f32 v188, v180, v181
	v_cvt_pk_bf16_f32 v189, v182, v183
	v_cvt_pk_bf16_f32 v190, v184, v185
	v_cvt_pk_bf16_f32 v191, v186, v187
	s_nop 0
	global_store_dwordx4 v[196:197], v[188:191], off
	v_add_co_u32_e32 v196, vcc, 0x1000, v196
	s_nop 1
	v_addc_co_u32_e32 v197, vcc, 0, v197, vcc
	v_lshlrev_b32_e32 v172, 16, v64
	v_and_b32_e32 v173, 0xffff0000, v64
	v_lshlrev_b32_e32 v174, 16, v65
	v_and_b32_e32 v175, 0xffff0000, v65
	v_lshlrev_b32_e32 v176, 16, v66
	v_and_b32_e32 v177, 0xffff0000, v66
	v_lshlrev_b32_e32 v178, 16, v67
	v_and_b32_e32 v179, 0xffff0000, v67
	v_pk_add_f32 v[164:165], v[164:165], v[172:173] neg_lo:[0,1] neg_hi:[0,1]
	v_pk_add_f32 v[166:167], v[166:167], v[174:175] neg_lo:[0,1] neg_hi:[0,1]
	v_pk_add_f32 v[168:169], v[168:169], v[176:177] neg_lo:[0,1] neg_hi:[0,1]
	v_pk_add_f32 v[170:171], v[170:171], v[178:179] neg_lo:[0,1] neg_hi:[0,1]
	v_lshlrev_b32_e32 v172, 16, v96
	v_and_b32_e32 v173, 0xffff0000, v96
	v_lshlrev_b32_e32 v174, 16, v97
	v_and_b32_e32 v175, 0xffff0000, v97
	v_lshlrev_b32_e32 v176, 16, v98
	v_and_b32_e32 v177, 0xffff0000, v98
	v_lshlrev_b32_e32 v178, 16, v99
	v_and_b32_e32 v179, 0xffff0000, v99
	v_pk_add_f32 v[164:165], v[164:165], v[172:173]
	v_pk_add_f32 v[166:167], v[166:167], v[174:175]
	v_pk_add_f32 v[168:169], v[168:169], v[176:177]
	v_pk_add_f32 v[170:171], v[170:171], v[178:179]
	v_pk_fma_f32 v[180:181], v[164:165], v[192:193], v[172:173] neg_lo:[0,0,1] neg_hi:[0,0,1]
	v_pk_fma_f32 v[182:183], v[166:167], v[192:193], v[174:175] neg_lo:[0,0,1] neg_hi:[0,0,1]
	v_pk_fma_f32 v[184:185], v[168:169], v[192:193], v[176:177] neg_lo:[0,0,1] neg_hi:[0,0,1]
	v_pk_fma_f32 v[186:187], v[170:171], v[192:193], v[178:179] neg_lo:[0,0,1] neg_hi:[0,0,1]
	v_cvt_pk_bf16_f32 v200, v180, v181
	v_cvt_pk_bf16_f32 v201, v182, v183
	v_cvt_pk_bf16_f32 v202, v184, v185
	v_cvt_pk_bf16_f32 v203, v186, v187
	s_nop 0
	global_store_dwordx4 v[196:197], v[200:203], off
	v_add_co_u32_e32 v196, vcc, 0x1000, v196
	s_nop 1
	v_addc_co_u32_e32 v197, vcc, 0, v197, vcc
	v_lshlrev_b32_e32 v172, 16, v68
	v_and_b32_e32 v173, 0xffff0000, v68
	v_lshlrev_b32_e32 v174, 16, v69
	v_and_b32_e32 v175, 0xffff0000, v69
	v_lshlrev_b32_e32 v176, 16, v70
	v_and_b32_e32 v177, 0xffff0000, v70
	v_lshlrev_b32_e32 v178, 16, v71
	v_and_b32_e32 v179, 0xffff0000, v71
	v_pk_add_f32 v[164:165], v[164:165], v[172:173] neg_lo:[0,1] neg_hi:[0,1]
	v_pk_add_f32 v[166:167], v[166:167], v[174:175] neg_lo:[0,1] neg_hi:[0,1]
	v_pk_add_f32 v[168:169], v[168:169], v[176:177] neg_lo:[0,1] neg_hi:[0,1]
	v_pk_add_f32 v[170:171], v[170:171], v[178:179] neg_lo:[0,1] neg_hi:[0,1]
	v_lshlrev_b32_e32 v172, 16, v100
	v_and_b32_e32 v173, 0xffff0000, v100
	v_lshlrev_b32_e32 v174, 16, v101
	v_and_b32_e32 v175, 0xffff0000, v101
	v_lshlrev_b32_e32 v176, 16, v102
	v_and_b32_e32 v177, 0xffff0000, v102
	v_lshlrev_b32_e32 v178, 16, v103
	v_and_b32_e32 v179, 0xffff0000, v103
	v_pk_add_f32 v[164:165], v[164:165], v[172:173]
	v_pk_add_f32 v[166:167], v[166:167], v[174:175]
	v_pk_add_f32 v[168:169], v[168:169], v[176:177]
; __device__ __forceinline__ float bf_lo(u32 v) { return __uint_as_float(v << 16); }
; __device__ __forceinline__ float bf_hi(u32 v) { return __uint_as_float(v & 0xffff0000u); }
; #define POOL_ACC(v, sgn) do { acc0 += sgn bf_lo(v.x); acc1 += sgn bf_hi(v.x); acc2 += sgn bf_lo(v.y); acc3 += sgn bf_hi(v.y); \
;     acc4 += sgn bf_lo(v.z); acc5 += sgn bf_hi(v.z); acc6 += sgn bf_lo(v.w); acc7 += sgn bf_hi(v.w); } while (0)
; template <int WIN>
; __device__ __forceinline__ void pool_run(const u16* U, u16* PL, int tok_s, int c0) {
;   const int pos_s = tok_s & (SEQ - 1);
;   float acc0 = 0.f, acc1 = 0.f, acc2 = 0.f, acc3 = 0.f, acc4 = 0.f, acc5 = 0.f, acc6 = 0.f, acc7 = 0.f;
;   #pragma unroll
;   for (int w = 1; w < WIN; ++w) {
;     if (pos_s - w >= 0) { const uint4 v = *(const uint4*)(U + (long)(tok_s - w) * LD0 + c0); POOL_ACC(v, +); }
;   }
;   #pragma unroll
;   for (int tt = 0; tt < 16; ++tt) {
;     const int tok = tok_s + tt, pos = pos_s + tt;
;     const uint4 cur = *(const uint4*)(U + (long)tok * LD0 + c0);
;     POOL_ACC(cur, +);
;     const float ic = 1.0f / (float)min(WIN, pos + 1);
;     uint4 pk;
;     pk.x = pack2(acc0 * ic - bf_lo(cur.x), acc1 * ic - bf_hi(cur.x));
;     pk.y = pack2(acc2 * ic - bf_lo(cur.y), acc3 * ic - bf_hi(cur.y));
;     pk.z = pack2(acc4 * ic - bf_lo(cur.z), acc5 * ic - bf_hi(cur.z));
;     pk.w = pack2(acc6 * ic - bf_lo(cur.w), acc7 * ic - bf_hi(cur.w));
;     *(uint4*)(PL + (long)tok * 2048 + c0) = pk;
;     if (pos - (WIN - 1) >= 0) { const uint4 old = *(const uint4*)(U + (long)(tok - (WIN - 1)) * LD0 + c0); POOL_ACC(old, -); }
;   }
; }
	v_pk_add_f32 v[170:171], v[170:171], v[178:179]
	v_pk_fma_f32 v[180:181], v[164:165], v[192:193], v[172:173] neg_lo:[0,0,1] neg_hi:[0,0,1]
	v_pk_fma_f32 v[182:183], v[166:167], v[192:193], v[174:175] neg_lo:[0,0,1] neg_hi:[0,0,1]
	v_pk_fma_f32 v[184:185], v[168:169], v[192:193], v[176:177] neg_lo:[0,0,1] neg_hi:[0,0,1]
	v_pk_fma_f32 v[186:187], v[170:171], v[192:193], v[178:179] neg_lo:[0,0,1] neg_hi:[0,0,1]
	v_cvt_pk_bf16_f32 v188, v180, v181
	v_cvt_pk_bf16_f32 v189, v182, v183
	v_cvt_pk_bf16_f32 v190, v184, v185
	v_cvt_pk_bf16_f32 v191, v186, v187
	s_nop 0
	global_store_dwordx4 v[196:197], v[188:191], off
	v_add_co_u32_e32 v196, vcc, 0x1000, v196
	s_nop 1
	v_addc_co_u32_e32 v197, vcc, 0, v197, vcc
	v_lshlrev_b32_e32 v172, 16, v72
	v_and_b32_e32 v173, 0xffff0000, v72
	v_lshlrev_b32_e32 v174, 16, v73
	v_and_b32_e32 v175, 0xffff0000, v73
	v_lshlrev_b32_e32 v176, 16, v74
	v_and_b32_e32 v177, 0xffff0000, v74
	v_lshlrev_b32_e32 v178, 16, v75
	v_and_b32_e32 v179, 0xffff0000, v75
	v_pk_add_f32 v[164:165], v[164:165], v[172:173] neg_lo:[0,1] neg_hi:[0,1]
	v_pk_add_f32 v[166:167], v[166:167], v[174:175] neg_lo:[0,1] neg_hi:[0,1]
	v_pk_add_f32 v[168:169], v[168:169], v[176:177] neg_lo:[0,1] neg_hi:[0,1]
	v_pk_add_f32 v[170:171], v[170:171], v[178:179] neg_lo:[0,1] neg_hi:[0,1]
	v_lshlrev_b32_e32 v172, 16, v104
	v_and_b32_e32 v173, 0xffff0000, v104
	v_lshlrev_b32_e32 v174, 16, v105
	v_and_b32_e32 v175, 0xffff0000, v105
	v_lshlrev_b32_e32 v176, 16, v106
	v_and_b32_e32 v177, 0xffff0000, v106
	v_lshlrev_b32_e32 v178, 16, v107
	v_and_b32_e32 v179, 0xffff0000, v107
	v_pk_add_f32 v[164:165], v[164:165], v[172:173]
	v_pk_add_f32 v[166:167], v[166:167], v[174:175]
	v_pk_add_f32 v[168:169], v[168:169], v[176:177]
	v_pk_add_f32 v[170:171], v[170:171], v[178:179]
	v_pk_fma_f32 v[180:181], v[164:165], v[192:193], v[172:173] neg_lo:[0,0,1] neg_hi:[0,0,1]
	v_pk_fma_f32 v[182:183], v[166:167], v[192:193], v[174:175] neg_lo:[0,0,1] neg_hi:[0,0,1]
	v_pk_fma_f32 v[184:185], v[168:169], v[192:193], v[176:177] neg_lo:[0,0,1] neg_hi:[0,0,1]
	v_pk_fma_f32 v[186:187], v[170:171], v[192:193], v[178:179] neg_lo:[0,0,1] neg_hi:[0,0,1]
	v_cvt_pk_bf16_f32 v200, v180, v181
	v_cvt_pk_bf16_f32 v201, v182, v183
	v_cvt_pk_bf16_f32 v202, v184, v185
	v_cvt_pk_bf16_f32 v203, v186, v187
	s_nop 0
	global_store_dwordx4 v[196:197], v[200:203], off
	v_add_co_u32_e32 v196, vcc, 0x1000, v196
	s_nop 1
	v_addc_co_u32_e32 v197, vcc, 0, v197, vcc
	v_lshlrev_b32_e32 v172, 16, v76
	v_and_b32_e32 v173, 0xffff0000, v76
	v_lshlrev_b32_e32 v174, 16, v77
	v_and_b32_e32 v175, 0xffff0000, v77
	v_lshlrev_b32_e32 v176, 16, v78
	v_and_b32_e32 v177, 0xffff0000, v78
	v_lshlrev_b32_e32 v178, 16, v79
	v_and_b32_e32 v179, 0xffff0000, v79
	v_pk_add_f32 v[164:165], v[164:165], v[172:173] neg_lo:[0,1] neg_hi:[0,1]
	v_pk_add_f32 v[166:167], v[166:167], v[174:175] neg_lo:[0,1] neg_hi:[0,1]
	v_pk_add_f32 v[168:169], v[168:169], v[176:177] neg_lo:[0,1] neg_hi:[0,1]
	v_pk_add_f32 v[170:171], v[170:171], v[178:179] neg_lo:[0,1] neg_hi:[0,1]
	v_lshlrev_b32_e32 v172, 16, v108
	v_and_b32_e32 v173, 0xffff0000, v108
	v_lshlrev_b32_e32 v174, 16, v109
	v_and_b32_e32 v175, 0xffff0000, v109
	v_lshlrev_b32_e32 v176, 16, v110
	v_and_b32_e32 v177, 0xffff0000, v110
	v_lshlrev_b32_e32 v178, 16, v111
	v_and_b32_e32 v179, 0xffff0000, v111
	v_pk_add_f32 v[164:165], v[164:165], v[172:173]
	v_pk_add_f32 v[166:167], v[166:167], v[174:175]
	v_pk_add_f32 v[168:169], v[168:169], v[176:177]
	v_pk_add_f32 v[170:171], v[170:171], v[178:179]
	v_pk_fma_f32 v[180:181], v[164:165], v[192:193], v[172:173] neg_lo:[0,0,1] neg_hi:[0,0,1]
	v_pk_fma_f32 v[182:183], v[166:167], v[192:193], v[174:175] neg_lo:[0,0,1] neg_hi:[0,0,1]
	v_pk_fma_f32 v[184:185], v[168:169], v[192:193], v[176:177] neg_lo:[0,0,1] neg_hi:[0,0,1]
	v_pk_fma_f32 v[186:187], v[170:171], v[192:193], v[178:179] neg_lo:[0,0,1] neg_hi:[0,0,1]
	v_cvt_pk_bf16_f32 v188, v180, v181
	v_cvt_pk_bf16_f32 v189, v182, v183
	v_cvt_pk_bf16_f32 v190, v184, v185
	v_cvt_pk_bf16_f32 v191, v186, v187
	s_nop 0
	global_store_dwordx4 v[196:197], v[188:191], off
	v_add_co_u32_e32 v196, vcc, 0x1000, v196
	s_nop 1
	v_addc_co_u32_e32 v197, vcc, 0, v197, vcc
	v_lshlrev_b32_e32 v172, 16, v80
	v_and_b32_e32 v173, 0xffff0000, v80
	v_lshlrev_b32_e32 v174, 16, v81
	v_and_b32_e32 v175, 0xffff0000, v81
	v_lshlrev_b32_e32 v176, 16, v82
	v_and_b32_e32 v177, 0xffff0000, v82
	v_lshlrev_b32_e32 v178, 16, v83
	v_and_b32_e32 v179, 0xffff0000, v83
	v_pk_add_f32 v[164:165], v[164:165], v[172:173] neg_lo:[0,1] neg_hi:[0,1]
	v_pk_add_f32 v[166:167], v[166:167], v[174:175] neg_lo:[0,1] neg_hi:[0,1]
	v_pk_add_f32 v[168:169], v[168:169], v[176:177] neg_lo:[0,1] neg_hi:[0,1]
	v_pk_add_f32 v[170:171], v[170:171], v[178:179] neg_lo:[0,1] neg_hi:[0,1]
	v_lshlrev_b32_e32 v172, 16, v112
	v_and_b32_e32 v173, 0xffff0000, v112
	v_lshlrev_b32_e32 v174, 16, v113
	v_and_b32_e32 v175, 0xffff0000, v113
	v_lshlrev_b32_e32 v176, 16, v114
	v_and_b32_e32 v177, 0xffff0000, v114
	v_lshlrev_b32_e32 v178, 16, v115
	v_and_b32_e32 v179, 0xffff0000, v115
	v_pk_add_f32 v[164:165], v[164:165], v[172:173]
	v_pk_add_f32 v[166:167], v[166:167], v[174:175]
	v_pk_add_f32 v[168:169], v[168:169], v[176:177]
	v_pk_add_f32 v[170:171], v[170:171], v[178:179]
	v_pk_fma_f32 v[180:181], v[164:165], v[192:193], v[172:173] neg_lo:[0,0,1] neg_hi:[0,0,1]
	v_pk_fma_f32 v[182:183], v[166:167], v[192:193], v[174:175] neg_lo:[0,0,1] neg_hi:[0,0,1]
	v_pk_fma_f32 v[184:185], v[168:169], v[192:193], v[176:177] neg_lo:[0,0,1] neg_hi:[0,0,1]
	v_pk_fma_f32 v[186:187], v[170:171], v[192:193], v[178:179] neg_lo:[0,0,1] neg_hi:[0,0,1]
	v_cvt_pk_bf16_f32 v200, v180, v181
	v_cvt_pk_bf16_f32 v201, v182, v183
	v_cvt_pk_bf16_f32 v202, v184, v185
	v_cvt_pk_bf16_f32 v203, v186, v187
	s_nop 0
	global_store_dwordx4 v[196:197], v[200:203], off
	s_branch .LBB0_333
; __device__ __forceinline__ float bf_lo(u32 v) { return __uint_as_float(v << 16); }
; __device__ __forceinline__ float bf_hi(u32 v) { return __uint_as_float(v & 0xffff0000u); }
; #define POOL_ACC(v, sgn) do { acc0 += sgn bf_lo(v.x); acc1 += sgn bf_hi(v.x); acc2 += sgn bf_lo(v.y); acc3 += sgn bf_hi(v.y); \
;     acc4 += sgn bf_lo(v.z); acc5 += sgn bf_hi(v.z); acc6 += sgn bf_lo(v.w); acc7 += sgn bf_hi(v.w); } while (0)
; template <int WIN>
; __device__ __forceinline__ void pool_run(const u16* U, u16* PL, int tok_s, int c0) {
;   const int pos_s = tok_s & (SEQ - 1);
;   float acc0 = 0.f, acc1 = 0.f, acc2 = 0.f, acc3 = 0.f, acc4 = 0.f, acc5 = 0.f, acc6 = 0.f, acc7 = 0.f;
;   #pragma unroll
;   for (int w = 1; w < WIN; ++w) {
;     if (pos_s - w >= 0) { const uint4 v = *(const uint4*)(U + (long)(tok_s - w) * LD0 + c0); POOL_ACC(v, +); }
;   }
;   #pragma unroll
;   for (int tt = 0; tt < 16; ++tt) {
;     const int tok = tok_s + tt, pos = pos_s + tt;
;     const uint4 cur = *(const uint4*)(U + (long)tok * LD0 + c0);
;     POOL_ACC(cur, +);
;     const float ic = 1.0f / (float)min(WIN, pos + 1);
;     uint4 pk;
;     pk.x = pack2(acc0 * ic - bf_lo(cur.x), acc1 * ic - bf_hi(cur.x));
;     pk.y = pack2(acc2 * ic - bf_lo(cur.y), acc3 * ic - bf_hi(cur.y));
;     pk.z = pack2(acc4 * ic - bf_lo(cur.z), acc5 * ic - bf_hi(cur.z));
;     pk.w = pack2(acc6 * ic - bf_lo(cur.w), acc7 * ic - bf_hi(cur.w));
;     *(uint4*)(PL + (long)tok * 2048 + c0) = pk;
;     if (pos - (WIN - 1) >= 0) { const uint4 old = *(const uint4*)(U + (long)(tok - (WIN - 1)) * LD0 + c0); POOL_ACC(old, -); }
;   }
; }
; __device__ __forceinline__ void pool_item(const Params& p, int item, const int wv) {
;   const u16* U = (const u16*)(p.ws + OFF_PB0) + 4096;
;   u16* PL = (u16*)(p.ws + OFF_PL);
;   const int tid = opaque_tid(wv), ch = tid & 255, half = tid >> 8;
;   const int c0 = ch * 8;
;   const int tok_s = item * 32 + half * 16;
.Lpool_w4:
	v_readlane_b32 s0, v255, 20
	v_readlane_b32 s1, v255, 21
	v_lshlrev_b32_e32 v140, 1, v22
	v_add_u32_e32 v0, -3, v16
	s_nop 3
	v_lshl_add_u64 v[18:19], s[0:1], 0, v[140:141]
	v_readlane_b32 s0, v255, 22
	v_readlane_b32 s1, v255, 23
	v_ashrrev_i32_e32 v17, 31, v16
	v_lshlrev_b64 v[12:13], 12, v[16:17]
	s_nop 3
	v_lshl_add_u64 v[20:21], s[0:1], 0, v[140:141]
	v_mad_i64_i32 v[194:195], s[0:1], v0, s13, v[18:19]
	v_lshl_add_u64 v[196:197], v[20:21], 0, v[12:13]
	global_load_dwordx4 v[24:27], v[194:195], off
	v_add_co_u32_e32 v194, vcc, 0x5000, v194
	s_nop 1
	v_addc_co_u32_e32 v195, vcc, 0, v195, vcc
	global_load_dwordx4 v[28:31], v[194:195], off
	v_add_co_u32_e32 v194, vcc, 0x5000, v194
	s_nop 1
	v_addc_co_u32_e32 v195, vcc, 0, v195, vcc
	global_load_dwordx4 v[32:35], v[194:195], off
	v_add_co_u32_e32 v194, vcc, 0x5000, v194
	s_nop 1
	v_addc_co_u32_e32 v195, vcc, 0, v195, vcc
	global_load_dwordx4 v[36:39], v[194:195], off
	v_add_co_u32_e32 v194, vcc, 0x5000, v194
	s_nop 1
	v_addc_co_u32_e32 v195, vcc, 0, v195, vcc
	global_load_dwordx4 v[40:43], v[194:195], off
	v_add_co_u32_e32 v194, vcc, 0x5000, v194
	s_nop 1
	v_addc_co_u32_e32 v195, vcc, 0, v195, vcc
	global_load_dwordx4 v[44:47], v[194:195], off
	v_add_co_u32_e32 v194, vcc, 0x5000, v194
	s_nop 1
	v_addc_co_u32_e32 v195, vcc, 0, v195, vcc
	global_load_dwordx4 v[48:51], v[194:195], off
	v_add_co_u32_e32 v194, vcc, 0x5000, v194
	s_nop 1
	v_addc_co_u32_e32 v195, vcc, 0, v195, vcc
	global_load_dwordx4 v[52:55], v[194:195], off
	v_add_co_u32_e32 v194, vcc, 0x5000, v194
	s_nop 1
	v_addc_co_u32_e32 v195, vcc, 0, v195, vcc
	global_load_dwordx4 v[56:59], v[194:195], off
	v_add_co_u32_e32 v194, vcc, 0x5000, v194
	s_nop 1
	v_addc_co_u32_e32 v195, vcc, 0, v195, vcc
	global_load_dwordx4 v[60:63], v[194:195], off
	v_add_co_u32_e32 v194, vcc, 0x5000, v194
	s_nop 1
	v_addc_co_u32_e32 v195, vcc, 0, v195, vcc
	global_load_dwordx4 v[64:67], v[194:195], off
	v_add_co_u32_e32 v194, vcc, 0x5000, v194
	s_nop 1
	v_addc_co_u32_e32 v195, vcc, 0, v195, vcc
	global_load_dwordx4 v[68:71], v[194:195], off
	v_add_co_u32_e32 v194, vcc, 0x5000, v194
	s_nop 1
	v_addc_co_u32_e32 v195, vcc, 0, v195, vcc
	global_load_dwordx4 v[72:75], v[194:195], off
	v_add_co_u32_e32 v194, vcc, 0x5000, v194
	s_nop 1
	v_addc_co_u32_e32 v195, vcc, 0, v195, vcc
	global_load_dwordx4 v[76:79], v[194:195], off
	v_add_co_u32_e32 v194, vcc, 0x5000, v194
	s_nop 1
	v_addc_co_u32_e32 v195, vcc, 0, v195, vcc
	global_load_dwordx4 v[80:83], v[194:195], off
	v_add_co_u32_e32 v194, vcc, 0x5000, v194
	s_nop 1
	v_addc_co_u32_e32 v195, vcc, 0, v195, vcc
	global_load_dwordx4 v[84:87], v[194:195], off
	v_add_co_u32_e32 v194, vcc, 0x5000, v194
	s_nop 1
	v_addc_co_u32_e32 v195, vcc, 0, v195, vcc
	global_load_dwordx4 v[88:91], v[194:195], off
	v_add_co_u32_e32 v194, vcc, 0x5000, v194
	s_nop 1
	v_addc_co_u32_e32 v195, vcc, 0, v195, vcc
	global_load_dwordx4 v[92:95], v[194:195], off
	v_add_co_u32_e32 v194, vcc, 0x5000, v194
	s_nop 1
	v_addc_co_u32_e32 v195, vcc, 0, v195, vcc
	global_load_dwordx4 v[96:99], v[194:195], off
	v_mov_b32_e32 v192, 0x3e800000
	v_mov_b32_e32 v193, 0x3e800000
	v_mov_b32_e32 v164, 0
	v_mov_b32_e32 v165, 0
	v_mov_b32_e32 v166, 0
	v_mov_b32_e32 v167, 0
	v_mov_b32_e32 v168, 0
	v_mov_b32_e32 v169, 0
	v_mov_b32_e32 v170, 0
	v_mov_b32_e32 v171, 0
	s_waitcnt vmcnt(0)
	v_lshlrev_b32_e32 v172, 16, v32
	v_and_b32_e32 v173, 0xffff0000, v32
	v_lshlrev_b32_e32 v174, 16, v33
	v_and_b32_e32 v175, 0xffff0000, v33
	v_lshlrev_b32_e32 v176, 16, v34
	v_and_b32_e32 v177, 0xffff0000, v34
	v_lshlrev_b32_e32 v178, 16, v35
	v_and_b32_e32 v179, 0xffff0000, v35
	v_pk_add_f32 v[164:165], v[164:165], v[172:173]
	v_pk_add_f32 v[166:167], v[166:167], v[174:175]
	v_pk_add_f32 v[168:169], v[168:169], v[176:177]
	v_pk_add_f32 v[170:171], v[170:171], v[178:179]
	v_lshlrev_b32_e32 v172, 16, v28
	v_and_b32_e32 v173, 0xffff0000, v28
	v_lshlrev_b32_e32 v174, 16, v29
	v_and_b32_e32 v175, 0xffff0000, v29
	v_lshlrev_b32_e32 v176, 16, v30
	v_and_b32_e32 v177, 0xffff0000, v30
	v_lshlrev_b32_e32 v178, 16, v31
	v_and_b32_e32 v179, 0xffff0000, v31
	v_pk_add_f32 v[164:165], v[164:165], v[172:173]
	v_pk_add_f32 v[166:167], v[166:167], v[174:175]
	v_pk_add_f32 v[168:169], v[168:169], v[176:177]
	v_pk_add_f32 v[170:171], v[170:171], v[178:179]
	v_lshlrev_b32_e32 v172, 16, v24
	v_and_b32_e32 v173, 0xffff0000, v24
	v_lshlrev_b32_e32 v174, 16, v25
	v_and_b32_e32 v175, 0xffff0000, v25
	v_lshlrev_b32_e32 v176, 16, v26
	v_and_b32_e32 v177, 0xffff0000, v26
	v_lshlrev_b32_e32 v178, 16, v27
	v_and_b32_e32 v179, 0xffff0000, v27
	v_pk_add_f32 v[164:165], v[164:165], v[172:173]
	v_pk_add_f32 v[166:167], v[166:167], v[174:175]
	v_pk_add_f32 v[168:169], v[168:169], v[176:177]
	v_pk_add_f32 v[170:171], v[170:171], v[178:179]
	v_lshlrev_b32_e32 v172, 16, v36
	v_and_b32_e32 v173, 0xffff0000, v36
	v_lshlrev_b32_e32 v174, 16, v37
	v_and_b32_e32 v175, 0xffff0000, v37
	v_lshlrev_b32_e32 v176, 16, v38
	v_and_b32_e32 v177, 0xffff0000, v38
	v_lshlrev_b32_e32 v178, 16, v39
	v_and_b32_e32 v179, 0xffff0000, v39
	v_pk_add_f32 v[164:165], v[164:165], v[172:173]
	v_pk_add_f32 v[166:167], v[166:167], v[174:175]
	v_pk_add_f32 v[168:169], v[168:169], v[176:177]
	v_pk_add_f32 v[170:171], v[170:171], v[178:179]
	v_pk_fma_f32 v[180:181], v[164:165], v[192:193], v[172:173] neg_lo:[0,0,1] neg_hi:[0,0,1]
	v_pk_fma_f32 v[182:183], v[166:167], v[192:193], v[174:175] neg_lo:[0,0,1] neg_hi:[0,0,1]
	v_pk_fma_f32 v[184:185], v[168:169], v[192:193], v[176:177] neg_lo:[0,0,1] neg_hi:[0,0,1]
	v_pk_fma_f32 v[186:187], v[170:171], v[192:193], v[178:179] neg_lo:[0,0,1] neg_hi:[0,0,1]
	v_cvt_pk_bf16_f32 v188, v180, v181
; __device__ __forceinline__ float bf_lo(u32 v) { return __uint_as_float(v << 16); }
; __device__ __forceinline__ float bf_hi(u32 v) { return __uint_as_float(v & 0xffff0000u); }
; #define POOL_ACC(v, sgn) do { acc0 += sgn bf_lo(v.x); acc1 += sgn bf_hi(v.x); acc2 += sgn bf_lo(v.y); acc3 += sgn bf_hi(v.y); \
;     acc4 += sgn bf_lo(v.z); acc5 += sgn bf_hi(v.z); acc6 += sgn bf_lo(v.w); acc7 += sgn bf_hi(v.w); } while (0)
; template <int WIN>
; __device__ __forceinline__ void pool_run(const u16* U, u16* PL, int tok_s, int c0) {
;   const int pos_s = tok_s & (SEQ - 1);
;   float acc0 = 0.f, acc1 = 0.f, acc2 = 0.f, acc3 = 0.f, acc4 = 0.f, acc5 = 0.f, acc6 = 0.f, acc7 = 0.f;
;   #pragma unroll
;   for (int w = 1; w < WIN; ++w) {
;     if (pos_s - w >= 0) { const uint4 v = *(const uint4*)(U + (long)(tok_s - w) * LD0 + c0); POOL_ACC(v, +); }
;   }
;   #pragma unroll
;   for (int tt = 0; tt < 16; ++tt) {
;     const int tok = tok_s + tt, pos = pos_s + tt;
;     const uint4 cur = *(const uint4*)(U + (long)tok * LD0 + c0);
;     POOL_ACC(cur, +);
;     const float ic = 1.0f / (float)min(WIN, pos + 1);
;     uint4 pk;
;     pk.x = pack2(acc0 * ic - bf_lo(cur.x), acc1 * ic - bf_hi(cur.x));
;     pk.y = pack2(acc2 * ic - bf_lo(cur.y), acc3 * ic - bf_hi(cur.y));
;     pk.z = pack2(acc4 * ic - bf_lo(cur.z), acc5 * ic - bf_hi(cur.z));
;     pk.w = pack2(acc6 * ic - bf_lo(cur.w), acc7 * ic - bf_hi(cur.w));
;     *(uint4*)(PL + (long)tok * 2048 + c0) = pk;
;     if (pos - (WIN - 1) >= 0) { const uint4 old = *(const uint4*)(U + (long)(tok - (WIN - 1)) * LD0 + c0); POOL_ACC(old, -); }
;   }
; }
	v_cvt_pk_bf16_f32 v189, v182, v183
	v_cvt_pk_bf16_f32 v190, v184, v185
	v_cvt_pk_bf16_f32 v191, v186, v187
	s_nop 0
	global_store_dwordx4 v[196:197], v[188:191], off
	v_add_co_u32_e32 v196, vcc, 0x1000, v196
	s_nop 1
	v_addc_co_u32_e32 v197, vcc, 0, v197, vcc
	v_lshlrev_b32_e32 v172, 16, v24
	v_and_b32_e32 v173, 0xffff0000, v24
	v_lshlrev_b32_e32 v174, 16, v25
	v_and_b32_e32 v175, 0xffff0000, v25
	v_lshlrev_b32_e32 v176, 16, v26
	v_and_b32_e32 v177, 0xffff0000, v26
	v_lshlrev_b32_e32 v178, 16, v27
	v_and_b32_e32 v179, 0xffff0000, v27
	v_pk_add_f32 v[164:165], v[164:165], v[172:173] neg_lo:[0,1] neg_hi:[0,1]
	v_pk_add_f32 v[166:167], v[166:167], v[174:175] neg_lo:[0,1] neg_hi:[0,1]
	v_pk_add_f32 v[168:169], v[168:169], v[176:177] neg_lo:[0,1] neg_hi:[0,1]
	v_pk_add_f32 v[170:171], v[170:171], v[178:179] neg_lo:[0,1] neg_hi:[0,1]
	v_lshlrev_b32_e32 v172, 16, v40
	v_and_b32_e32 v173, 0xffff0000, v40
	v_lshlrev_b32_e32 v174, 16, v41
	v_and_b32_e32 v175, 0xffff0000, v41
	v_lshlrev_b32_e32 v176, 16, v42
	v_and_b32_e32 v177, 0xffff0000, v42
	v_lshlrev_b32_e32 v178, 16, v43
	v_and_b32_e32 v179, 0xffff0000, v43
	v_pk_add_f32 v[164:165], v[164:165], v[172:173]
	v_pk_add_f32 v[166:167], v[166:167], v[174:175]
	v_pk_add_f32 v[168:169], v[168:169], v[176:177]
	v_pk_add_f32 v[170:171], v[170:171], v[178:179]
	v_pk_fma_f32 v[180:181], v[164:165], v[192:193], v[172:173] neg_lo:[0,0,1] neg_hi:[0,0,1]
	v_pk_fma_f32 v[182:183], v[166:167], v[192:193], v[174:175] neg_lo:[0,0,1] neg_hi:[0,0,1]
	v_pk_fma_f32 v[184:185], v[168:169], v[192:193], v[176:177] neg_lo:[0,0,1] neg_hi:[0,0,1]
	v_pk_fma_f32 v[186:187], v[170:171], v[192:193], v[178:179] neg_lo:[0,0,1] neg_hi:[0,0,1]
	v_cvt_pk_bf16_f32 v200, v180, v181
	v_cvt_pk_bf16_f32 v201, v182, v183
	v_cvt_pk_bf16_f32 v202, v184, v185
	v_cvt_pk_bf16_f32 v203, v186, v187
	s_nop 0
	global_store_dwordx4 v[196:197], v[200:203], off
	v_add_co_u32_e32 v196, vcc, 0x1000, v196
	s_nop 1
	v_addc_co_u32_e32 v197, vcc, 0, v197, vcc
	v_lshlrev_b32_e32 v172, 16, v28
	v_and_b32_e32 v173, 0xffff0000, v28
	v_lshlrev_b32_e32 v174, 16, v29
	v_and_b32_e32 v175, 0xffff0000, v29
	v_lshlrev_b32_e32 v176, 16, v30
	v_and_b32_e32 v177, 0xffff0000, v30
	v_lshlrev_b32_e32 v178, 16, v31
	v_and_b32_e32 v179, 0xffff0000, v31
	v_pk_add_f32 v[164:165], v[164:165], v[172:173] neg_lo:[0,1] neg_hi:[0,1]
	v_pk_add_f32 v[166:167], v[166:167], v[174:175] neg_lo:[0,1] neg_hi:[0,1]
	v_pk_add_f32 v[168:169], v[168:169], v[176:177] neg_lo:[0,1] neg_hi:[0,1]
	v_pk_add_f32 v[170:171], v[170:171], v[178:179] neg_lo:[0,1] neg_hi:[0,1]
	v_lshlrev_b32_e32 v172, 16, v44
	v_and_b32_e32 v173, 0xffff0000, v44
	v_lshlrev_b32_e32 v174, 16, v45
	v_and_b32_e32 v175, 0xffff0000, v45
	v_lshlrev_b32_e32 v176, 16, v46
	v_and_b32_e32 v177, 0xffff0000, v46
	v_lshlrev_b32_e32 v178, 16, v47
	v_and_b32_e32 v179, 0xffff0000, v47
	v_pk_add_f32 v[164:165], v[164:165], v[172:173]
	v_pk_add_f32 v[166:167], v[166:167], v[174:175]
	v_pk_add_f32 v[168:169], v[168:169], v[176:177]
	v_pk_add_f32 v[170:171], v[170:171], v[178:179]
	v_pk_fma_f32 v[180:181], v[164:165], v[192:193], v[172:173] neg_lo:[0,0,1] neg_hi:[0,0,1]
	v_pk_fma_f32 v[182:183], v[166:167], v[192:193], v[174:175] neg_lo:[0,0,1] neg_hi:[0,0,1]
	v_pk_fma_f32 v[184:185], v[168:169], v[192:193], v[176:177] neg_lo:[0,0,1] neg_hi:[0,0,1]
	v_pk_fma_f32 v[186:187], v[170:171], v[192:193], v[178:179] neg_lo:[0,0,1] neg_hi:[0,0,1]
	v_cvt_pk_bf16_f32 v188, v180, v181
	v_cvt_pk_bf16_f32 v189, v182, v183
	v_cvt_pk_bf16_f32 v190, v184, v185
	v_cvt_pk_bf16_f32 v191, v186, v187
	s_nop 0
	global_store_dwordx4 v[196:197], v[188:191], off
	v_add_co_u32_e32 v196, vcc, 0x1000, v196
	s_nop 1
	v_addc_co_u32_e32 v197, vcc, 0, v197, vcc
	v_lshlrev_b32_e32 v172, 16, v32
	v_and_b32_e32 v173, 0xffff0000, v32
	v_lshlrev_b32_e32 v174, 16, v33
	v_and_b32_e32 v175, 0xffff0000, v33
	v_lshlrev_b32_e32 v176, 16, v34
	v_and_b32_e32 v177, 0xffff0000, v34
	v_lshlrev_b32_e32 v178, 16, v35
	v_and_b32_e32 v179, 0xffff0000, v35
	v_pk_add_f32 v[164:165], v[164:165], v[172:173] neg_lo:[0,1] neg_hi:[0,1]
	v_pk_add_f32 v[166:167], v[166:167], v[174:175] neg_lo:[0,1] neg_hi:[0,1]
	v_pk_add_f32 v[168:169], v[168:169], v[176:177] neg_lo:[0,1] neg_hi:[0,1]
	v_pk_add_f32 v[170:171], v[170:171], v[178:179] neg_lo:[0,1] neg_hi:[0,1]
	v_lshlrev_b32_e32 v172, 16, v48
	v_and_b32_e32 v173, 0xffff0000, v48
	v_lshlrev_b32_e32 v174, 16, v49
	v_and_b32_e32 v175, 0xffff0000, v49
	v_lshlrev_b32_e32 v176, 16, v50
	v_and_b32_e32 v177, 0xffff0000, v50
	v_lshlrev_b32_e32 v178, 16, v51
	v_and_b32_e32 v179, 0xffff0000, v51
	v_pk_add_f32 v[164:165], v[164:165], v[172:173]
	v_pk_add_f32 v[166:167], v[166:167], v[174:175]
	v_pk_add_f32 v[168:169], v[168:169], v[176:177]
	v_pk_add_f32 v[170:171], v[170:171], v[178:179]
	v_pk_fma_f32 v[180:181], v[164:165], v[192:193], v[172:173] neg_lo:[0,0,1] neg_hi:[0,0,1]
	v_pk_fma_f32 v[182:183], v[166:167], v[192:193], v[174:175] neg_lo:[0,0,1] neg_hi:[0,0,1]
	v_pk_fma_f32 v[184:185], v[168:169], v[192:193], v[176:177] neg_lo:[0,0,1] neg_hi:[0,0,1]
	v_pk_fma_f32 v[186:187], v[170:171], v[192:193], v[178:179] neg_lo:[0,0,1] neg_hi:[0,0,1]
	v_cvt_pk_bf16_f32 v200, v180, v181
	v_cvt_pk_bf16_f32 v201, v182, v183
	v_cvt_pk_bf16_f32 v202, v184, v185
	v_cvt_pk_bf16_f32 v203, v186, v187
	s_nop 0
	global_store_dwordx4 v[196:197], v[200:203], off
	v_add_co_u32_e32 v196, vcc, 0x1000, v196
	s_nop 1
	v_addc_co_u32_e32 v197, vcc, 0, v197, vcc
	v_lshlrev_b32_e32 v172, 16, v36
	v_and_b32_e32 v173, 0xffff0000, v36
	v_lshlrev_b32_e32 v174, 16, v37
	v_and_b32_e32 v175, 0xffff0000, v37
	v_lshlrev_b32_e32 v176, 16, v38
	v_and_b32_e32 v177, 0xffff0000, v38
	v_lshlrev_b32_e32 v178, 16, v39
; __device__ __forceinline__ float bf_lo(u32 v) { return __uint_as_float(v << 16); }
; __device__ __forceinline__ float bf_hi(u32 v) { return __uint_as_float(v & 0xffff0000u); }
; #define POOL_ACC(v, sgn) do { acc0 += sgn bf_lo(v.x); acc1 += sgn bf_hi(v.x); acc2 += sgn bf_lo(v.y); acc3 += sgn bf_hi(v.y); \
;     acc4 += sgn bf_lo(v.z); acc5 += sgn bf_hi(v.z); acc6 += sgn bf_lo(v.w); acc7 += sgn bf_hi(v.w); } while (0)
; template <int WIN>
; __device__ __forceinline__ void pool_run(const u16* U, u16* PL, int tok_s, int c0) {
;   const int pos_s = tok_s & (SEQ - 1);
;   float acc0 = 0.f, acc1 = 0.f, acc2 = 0.f, acc3 = 0.f, acc4 = 0.f, acc5 = 0.f, acc6 = 0.f, acc7 = 0.f;
;   #pragma unroll
;   for (int w = 1; w < WIN; ++w) {
;     if (pos_s - w >= 0) { const uint4 v = *(const uint4*)(U + (long)(tok_s - w) * LD0 + c0); POOL_ACC(v, +); }
;   }
;   #pragma unroll
;   for (int tt = 0; tt < 16; ++tt) {
;     const int tok = tok_s + tt, pos = pos_s + tt;
;     const uint4 cur = *(const uint4*)(U + (long)tok * LD0 + c0);
;     POOL_ACC(cur, +);
;     const float ic = 1.0f / (float)min(WIN, pos + 1);
;     uint4 pk;
;     pk.x = pack2(acc0 * ic - bf_lo(cur.x), acc1 * ic - bf_hi(cur.x));
;     pk.y = pack2(acc2 * ic - bf_lo(cur.y), acc3 * ic - bf_hi(cur.y));
;     pk.z = pack2(acc4 * ic - bf_lo(cur.z), acc5 * ic - bf_hi(cur.z));
;     pk.w = pack2(acc6 * ic - bf_lo(cur.w), acc7 * ic - bf_hi(cur.w));
;     *(uint4*)(PL + (long)tok * 2048 + c0) = pk;
;     if (pos - (WIN - 1) >= 0) { const uint4 old = *(const uint4*)(U + (long)(tok - (WIN - 1)) * LD0 + c0); POOL_ACC(old, -); }
;   }
; }
	v_and_b32_e32 v179, 0xffff0000, v39
	v_pk_add_f32 v[164:165], v[164:165], v[172:173] neg_lo:[0,1] neg_hi:[0,1]
	v_pk_add_f32 v[166:167], v[166:167], v[174:175] neg_lo:[0,1] neg_hi:[0,1]
	v_pk_add_f32 v[168:169], v[168:169], v[176:177] neg_lo:[0,1] neg_hi:[0,1]
	v_pk_add_f32 v[170:171], v[170:171], v[178:179] neg_lo:[0,1] neg_hi:[0,1]
	v_lshlrev_b32_e32 v172, 16, v52
	v_and_b32_e32 v173, 0xffff0000, v52
	v_lshlrev_b32_e32 v174, 16, v53
	v_and_b32_e32 v175, 0xffff0000, v53
	v_lshlrev_b32_e32 v176, 16, v54
	v_and_b32_e32 v177, 0xffff0000, v54
	v_lshlrev_b32_e32 v178, 16, v55
	v_and_b32_e32 v179, 0xffff0000, v55
	v_pk_add_f32 v[164:165], v[164:165], v[172:173]
	v_pk_add_f32 v[166:167], v[166:167], v[174:175]
	v_pk_add_f32 v[168:169], v[168:169], v[176:177]
	v_pk_add_f32 v[170:171], v[170:171], v[178:179]
	v_pk_fma_f32 v[180:181], v[164:165], v[192:193], v[172:173] neg_lo:[0,0,1] neg_hi:[0,0,1]
	v_pk_fma_f32 v[182:183], v[166:167], v[192:193], v[174:175] neg_lo:[0,0,1] neg_hi:[0,0,1]
	v_pk_fma_f32 v[184:185], v[168:169], v[192:193], v[176:177] neg_lo:[0,0,1] neg_hi:[0,0,1]
	v_pk_fma_f32 v[186:187], v[170:171], v[192:193], v[178:179] neg_lo:[0,0,1] neg_hi:[0,0,1]
	v_cvt_pk_bf16_f32 v188, v180, v181
	v_cvt_pk_bf16_f32 v189, v182, v183
	v_cvt_pk_bf16_f32 v190, v184, v185
	v_cvt_pk_bf16_f32 v191, v186, v187
	s_nop 0
	global_store_dwordx4 v[196:197], v[188:191], off
	v_add_co_u32_e32 v196, vcc, 0x1000, v196
	s_nop 1
	v_addc_co_u32_e32 v197, vcc, 0, v197, vcc
	v_lshlrev_b32_e32 v172, 16, v40
	v_and_b32_e32 v173, 0xffff0000, v40
	v_lshlrev_b32_e32 v174, 16, v41
	v_and_b32_e32 v175, 0xffff0000, v41
	v_lshlrev_b32_e32 v176, 16, v42
	v_and_b32_e32 v177, 0xffff0000, v42
	v_lshlrev_b32_e32 v178, 16, v43
	v_and_b32_e32 v179, 0xffff0000, v43
	v_pk_add_f32 v[164:165], v[164:165], v[172:173] neg_lo:[0,1] neg_hi:[0,1]
	v_pk_add_f32 v[166:167], v[166:167], v[174:175] neg_lo:[0,1] neg_hi:[0,1]
	v_pk_add_f32 v[168:169], v[168:169], v[176:177] neg_lo:[0,1] neg_hi:[0,1]
	v_pk_add_f32 v[170:171], v[170:171], v[178:179] neg_lo:[0,1] neg_hi:[0,1]
	v_lshlrev_b32_e32 v172, 16, v56
	v_and_b32_e32 v173, 0xffff0000, v56
	v_lshlrev_b32_e32 v174, 16, v57
	v_and_b32_e32 v175, 0xffff0000, v57
	v_lshlrev_b32_e32 v176, 16, v58
	v_and_b32_e32 v177, 0xffff0000, v58
	v_lshlrev_b32_e32 v178, 16, v59
	v_and_b32_e32 v179, 0xffff0000, v59
	v_pk_add_f32 v[164:165], v[164:165], v[172:173]
	v_pk_add_f32 v[166:167], v[166:167], v[174:175]
	v_pk_add_f32 v[168:169], v[168:169], v[176:177]
	v_pk_add_f32 v[170:171], v[170:171], v[178:179]
	v_pk_fma_f32 v[180:181], v[164:165], v[192:193], v[172:173] neg_lo:[0,0,1] neg_hi:[0,0,1]
	v_pk_fma_f32 v[182:183], v[166:167], v[192:193], v[174:175] neg_lo:[0,0,1] neg_hi:[0,0,1]
	v_pk_fma_f32 v[184:185], v[168:169], v[192:193], v[176:177] neg_lo:[0,0,1] neg_hi:[0,0,1]
	v_pk_fma_f32 v[186:187], v[170:171], v[192:193], v[178:179] neg_lo:[0,0,1] neg_hi:[0,0,1]
	v_cvt_pk_bf16_f32 v200, v180, v181
	v_cvt_pk_bf16_f32 v201, v182, v183
	v_cvt_pk_bf16_f32 v202, v184, v185
	v_cvt_pk_bf16_f32 v203, v186, v187
	s_nop 0
	global_store_dwordx4 v[196:197], v[200:203], off
	v_add_co_u32_e32 v196, vcc, 0x1000, v196
	s_nop 1
	v_addc_co_u32_e32 v197, vcc, 0, v197, vcc
	v_lshlrev_b32_e32 v172, 16, v44
	v_and_b32_e32 v173, 0xffff0000, v44
	v_lshlrev_b32_e32 v174, 16, v45
	v_and_b32_e32 v175, 0xffff0000, v45
	v_lshlrev_b32_e32 v176, 16, v46
	v_and_b32_e32 v177, 0xffff0000, v46
	v_lshlrev_b32_e32 v178, 16, v47
	v_and_b32_e32 v179, 0xffff0000, v47
	v_pk_add_f32 v[164:165], v[164:165], v[172:173] neg_lo:[0,1] neg_hi:[0,1]
	v_pk_add_f32 v[166:167], v[166:167], v[174:175] neg_lo:[0,1] neg_hi:[0,1]
	v_pk_add_f32 v[168:169], v[168:169], v[176:177] neg_lo:[0,1] neg_hi:[0,1]
	v_pk_add_f32 v[170:171], v[170:171], v[178:179] neg_lo:[0,1] neg_hi:[0,1]
	v_lshlrev_b32_e32 v172, 16, v60
	v_and_b32_e32 v173, 0xffff0000, v60
	v_lshlrev_b32_e32 v174, 16, v61
	v_and_b32_e32 v175, 0xffff0000, v61
	v_lshlrev_b32_e32 v176, 16, v62
	v_and_b32_e32 v177, 0xffff0000, v62
	v_lshlrev_b32_e32 v178, 16, v63
	v_and_b32_e32 v179, 0xffff0000, v63
	v_pk_add_f32 v[164:165], v[164:165], v[172:173]
	v_pk_add_f32 v[166:167], v[166:167], v[174:175]
	v_pk_add_f32 v[168:169], v[168:169], v[176:177]
	v_pk_add_f32 v[170:171], v[170:171], v[178:179]
	v_pk_fma_f32 v[180:181], v[164:165], v[192:193], v[172:173] neg_lo:[0,0,1] neg_hi:[0,0,1]
	v_pk_fma_f32 v[182:183], v[166:167], v[192:193], v[174:175] neg_lo:[0,0,1] neg_hi:[0,0,1]
	v_pk_fma_f32 v[184:185], v[168:169], v[192:193], v[176:177] neg_lo:[0,0,1] neg_hi:[0,0,1]
	v_pk_fma_f32 v[186:187], v[170:171], v[192:193], v[178:179] neg_lo:[0,0,1] neg_hi:[0,0,1]
	v_cvt_pk_bf16_f32 v188, v180, v181
	v_cvt_pk_bf16_f32 v189, v182, v183
	v_cvt_pk_bf16_f32 v190, v184, v185
	v_cvt_pk_bf16_f32 v191, v186, v187
	s_nop 0
	global_store_dwordx4 v[196:197], v[188:191], off
	v_add_co_u32_e32 v196, vcc, 0x1000, v196
	s_nop 1
	v_addc_co_u32_e32 v197, vcc, 0, v197, vcc
	v_lshlrev_b32_e32 v172, 16, v48
	v_and_b32_e32 v173, 0xffff0000, v48
	v_lshlrev_b32_e32 v174, 16, v49
	v_and_b32_e32 v175, 0xffff0000, v49
	v_lshlrev_b32_e32 v176, 16, v50
	v_and_b32_e32 v177, 0xffff0000, v50
	v_lshlrev_b32_e32 v178, 16, v51
	v_and_b32_e32 v179, 0xffff0000, v51
	v_pk_add_f32 v[164:165], v[164:165], v[172:173] neg_lo:[0,1] neg_hi:[0,1]
	v_pk_add_f32 v[166:167], v[166:167], v[174:175] neg_lo:[0,1] neg_hi:[0,1]
	v_pk_add_f32 v[168:169], v[168:169], v[176:177] neg_lo:[0,1] neg_hi:[0,1]
	v_pk_add_f32 v[170:171], v[170:171], v[178:179] neg_lo:[0,1] neg_hi:[0,1]
	v_lshlrev_b32_e32 v172, 16, v64
	v_and_b32_e32 v173, 0xffff0000, v64
	v_lshlrev_b32_e32 v174, 16, v65
	v_and_b32_e32 v175, 0xffff0000, v65
; __device__ __forceinline__ float bf_lo(u32 v) { return __uint_as_float(v << 16); }
; __device__ __forceinline__ float bf_hi(u32 v) { return __uint_as_float(v & 0xffff0000u); }
; #define POOL_ACC(v, sgn) do { acc0 += sgn bf_lo(v.x); acc1 += sgn bf_hi(v.x); acc2 += sgn bf_lo(v.y); acc3 += sgn bf_hi(v.y); \
;     acc4 += sgn bf_lo(v.z); acc5 += sgn bf_hi(v.z); acc6 += sgn bf_lo(v.w); acc7 += sgn bf_hi(v.w); } while (0)
; template <int WIN>
; __device__ __forceinline__ void pool_run(const u16* U, u16* PL, int tok_s, int c0) {
;   const int pos_s = tok_s & (SEQ - 1);
;   float acc0 = 0.f, acc1 = 0.f, acc2 = 0.f, acc3 = 0.f, acc4 = 0.f, acc5 = 0.f, acc6 = 0.f, acc7 = 0.f;
;   #pragma unroll
;   for (int w = 1; w < WIN; ++w) {
;     if (pos_s - w >= 0) { const uint4 v = *(const uint4*)(U + (long)(tok_s - w) * LD0 + c0); POOL_ACC(v, +); }
;   }
;   #pragma unroll
;   for (int tt = 0; tt < 16; ++tt) {
;     const int tok = tok_s + tt, pos = pos_s + tt;
;     const uint4 cur = *(const uint4*)(U + (long)tok * LD0 + c0);
;     POOL_ACC(cur, +);
;     const float ic = 1.0f / (float)min(WIN, pos + 1);
;     uint4 pk;
;     pk.x = pack2(acc0 * ic - bf_lo(cur.x), acc1 * ic - bf_hi(cur.x));
;     pk.y = pack2(acc2 * ic - bf_lo(cur.y), acc3 * ic - bf_hi(cur.y));
;     pk.z = pack2(acc4 * ic - bf_lo(cur.z), acc5 * ic - bf_hi(cur.z));
;     pk.w = pack2(acc6 * ic - bf_lo(cur.w), acc7 * ic - bf_hi(cur.w));
;     *(uint4*)(PL + (long)tok * 2048 + c0) = pk;
;     if (pos - (WIN - 1) >= 0) { const uint4 old = *(const uint4*)(U + (long)(tok - (WIN - 1)) * LD0 + c0); POOL_ACC(old, -); }
;   }
; }
	v_lshlrev_b32_e32 v176, 16, v66
	v_and_b32_e32 v177, 0xffff0000, v66
	v_lshlrev_b32_e32 v178, 16, v67
	v_and_b32_e32 v179, 0xffff0000, v67
	v_pk_add_f32 v[164:165], v[164:165], v[172:173]
	v_pk_add_f32 v[166:167], v[166:167], v[174:175]
	v_pk_add_f32 v[168:169], v[168:169], v[176:177]
	v_pk_add_f32 v[170:171], v[170:171], v[178:179]
	v_pk_fma_f32 v[180:181], v[164:165], v[192:193], v[172:173] neg_lo:[0,0,1] neg_hi:[0,0,1]
	v_pk_fma_f32 v[182:183], v[166:167], v[192:193], v[174:175] neg_lo:[0,0,1] neg_hi:[0,0,1]
	v_pk_fma_f32 v[184:185], v[168:169], v[192:193], v[176:177] neg_lo:[0,0,1] neg_hi:[0,0,1]
	v_pk_fma_f32 v[186:187], v[170:171], v[192:193], v[178:179] neg_lo:[0,0,1] neg_hi:[0,0,1]
	v_cvt_pk_bf16_f32 v200, v180, v181
	v_cvt_pk_bf16_f32 v201, v182, v183
	v_cvt_pk_bf16_f32 v202, v184, v185
	v_cvt_pk_bf16_f32 v203, v186, v187
	s_nop 0
	global_store_dwordx4 v[196:197], v[200:203], off
	v_add_co_u32_e32 v196, vcc, 0x1000, v196
	s_nop 1
	v_addc_co_u32_e32 v197, vcc, 0, v197, vcc
	v_lshlrev_b32_e32 v172, 16, v52
	v_and_b32_e32 v173, 0xffff0000, v52
	v_lshlrev_b32_e32 v174, 16, v53
	v_and_b32_e32 v175, 0xffff0000, v53
	v_lshlrev_b32_e32 v176, 16, v54
	v_and_b32_e32 v177, 0xffff0000, v54
	v_lshlrev_b32_e32 v178, 16, v55
	v_and_b32_e32 v179, 0xffff0000, v55
	v_pk_add_f32 v[164:165], v[164:165], v[172:173] neg_lo:[0,1] neg_hi:[0,1]
	v_pk_add_f32 v[166:167], v[166:167], v[174:175] neg_lo:[0,1] neg_hi:[0,1]
	v_pk_add_f32 v[168:169], v[168:169], v[176:177] neg_lo:[0,1] neg_hi:[0,1]
	v_pk_add_f32 v[170:171], v[170:171], v[178:179] neg_lo:[0,1] neg_hi:[0,1]
	v_lshlrev_b32_e32 v172, 16, v68
	v_and_b32_e32 v173, 0xffff0000, v68
	v_lshlrev_b32_e32 v174, 16, v69
	v_and_b32_e32 v175, 0xffff0000, v69
	v_lshlrev_b32_e32 v176, 16, v70
	v_and_b32_e32 v177, 0xffff0000, v70
	v_lshlrev_b32_e32 v178, 16, v71
	v_and_b32_e32 v179, 0xffff0000, v71
	v_pk_add_f32 v[164:165], v[164:165], v[172:173]
	v_pk_add_f32 v[166:167], v[166:167], v[174:175]
	v_pk_add_f32 v[168:169], v[168:169], v[176:177]
	v_pk_add_f32 v[170:171], v[170:171], v[178:179]
	v_pk_fma_f32 v[180:181], v[164:165], v[192:193], v[172:173] neg_lo:[0,0,1] neg_hi:[0,0,1]
	v_pk_fma_f32 v[182:183], v[166:167], v[192:193], v[174:175] neg_lo:[0,0,1] neg_hi:[0,0,1]
	v_pk_fma_f32 v[184:185], v[168:169], v[192:193], v[176:177] neg_lo:[0,0,1] neg_hi:[0,0,1]
	v_pk_fma_f32 v[186:187], v[170:171], v[192:193], v[178:179] neg_lo:[0,0,1] neg_hi:[0,0,1]
	v_cvt_pk_bf16_f32 v188, v180, v181
	v_cvt_pk_bf16_f32 v189, v182, v183
	v_cvt_pk_bf16_f32 v190, v184, v185
	v_cvt_pk_bf16_f32 v191, v186, v187
	s_nop 0
	global_store_dwordx4 v[196:197], v[188:191], off
	v_add_co_u32_e32 v196, vcc, 0x1000, v196
	s_nop 1
	v_addc_co_u32_e32 v197, vcc, 0, v197, vcc
	v_lshlrev_b32_e32 v172, 16, v56
	v_and_b32_e32 v173, 0xffff0000, v56
	v_lshlrev_b32_e32 v174, 16, v57
	v_and_b32_e32 v175, 0xffff0000, v57
	v_lshlrev_b32_e32 v176, 16, v58
	v_and_b32_e32 v177, 0xffff0000, v58
	v_lshlrev_b32_e32 v178, 16, v59
	v_and_b32_e32 v179, 0xffff0000, v59
	v_pk_add_f32 v[164:165], v[164:165], v[172:173] neg_lo:[0,1] neg_hi:[0,1]
	v_pk_add_f32 v[166:167], v[166:167], v[174:175] neg_lo:[0,1] neg_hi:[0,1]
	v_pk_add_f32 v[168:169], v[168:169], v[176:177] neg_lo:[0,1] neg_hi:[0,1]
	v_pk_add_f32 v[170:171], v[170:171], v[178:179] neg_lo:[0,1] neg_hi:[0,1]
	v_lshlrev_b32_e32 v172, 16, v72
	v_and_b32_e32 v173, 0xffff0000, v72
	v_lshlrev_b32_e32 v174, 16, v73
	v_and_b32_e32 v175, 0xffff0000, v73
	v_lshlrev_b32_e32 v176, 16, v74
	v_and_b32_e32 v177, 0xffff0000, v74
	v_lshlrev_b32_e32 v178, 16, v75
	v_and_b32_e32 v179, 0xffff0000, v75
	v_pk_add_f32 v[164:165], v[164:165], v[172:173]
	v_pk_add_f32 v[166:167], v[166:167], v[174:175]
	v_pk_add_f32 v[168:169], v[168:169], v[176:177]
	v_pk_add_f32 v[170:171], v[170:171], v[178:179]
	v_pk_fma_f32 v[180:181], v[164:165], v[192:193], v[172:173] neg_lo:[0,0,1] neg_hi:[0,0,1]
	v_pk_fma_f32 v[182:183], v[166:167], v[192:193], v[174:175] neg_lo:[0,0,1] neg_hi:[0,0,1]
	v_pk_fma_f32 v[184:185], v[168:169], v[192:193], v[176:177] neg_lo:[0,0,1] neg_hi:[0,0,1]
	v_pk_fma_f32 v[186:187], v[170:171], v[192:193], v[178:179] neg_lo:[0,0,1] neg_hi:[0,0,1]
	v_cvt_pk_bf16_f32 v200, v180, v181
	v_cvt_pk_bf16_f32 v201, v182, v183
	v_cvt_pk_bf16_f32 v202, v184, v185
	v_cvt_pk_bf16_f32 v203, v186, v187
	s_nop 0
	global_store_dwordx4 v[196:197], v[200:203], off
	v_add_co_u32_e32 v196, vcc, 0x1000, v196
	s_nop 1
	v_addc_co_u32_e32 v197, vcc, 0, v197, vcc
	v_lshlrev_b32_e32 v172, 16, v60
	v_and_b32_e32 v173, 0xffff0000, v60
	v_lshlrev_b32_e32 v174, 16, v61
	v_and_b32_e32 v175, 0xffff0000, v61
	v_lshlrev_b32_e32 v176, 16, v62
	v_and_b32_e32 v177, 0xffff0000, v62
	v_lshlrev_b32_e32 v178, 16, v63
	v_and_b32_e32 v179, 0xffff0000, v63
	v_pk_add_f32 v[164:165], v[164:165], v[172:173] neg_lo:[0,1] neg_hi:[0,1]
	v_pk_add_f32 v[166:167], v[166:167], v[174:175] neg_lo:[0,1] neg_hi:[0,1]
	v_pk_add_f32 v[168:169], v[168:169], v[176:177] neg_lo:[0,1] neg_hi:[0,1]
	v_pk_add_f32 v[170:171], v[170:171], v[178:179] neg_lo:[0,1] neg_hi:[0,1]
	v_lshlrev_b32_e32 v172, 16, v76
	v_and_b32_e32 v173, 0xffff0000, v76
	v_lshlrev_b32_e32 v174, 16, v77
	v_and_b32_e32 v175, 0xffff0000, v77
	v_lshlrev_b32_e32 v176, 16, v78
	v_and_b32_e32 v177, 0xffff0000, v78
	v_lshlrev_b32_e32 v178, 16, v79
	v_and_b32_e32 v179, 0xffff0000, v79
	v_pk_add_f32 v[164:165], v[164:165], v[172:173]
	v_pk_add_f32 v[166:167], v[166:167], v[174:175]
	v_pk_add_f32 v[168:169], v[168:169], v[176:177]
	v_pk_add_f32 v[170:171], v[170:171], v[178:179]
	v_pk_fma_f32 v[180:181], v[164:165], v[192:193], v[172:173] neg_lo:[0,0,1] neg_hi:[0,0,1]
	v_pk_fma_f32 v[182:183], v[166:167], v[192:193], v[174:175] neg_lo:[0,0,1] neg_hi:[0,0,1]
; __device__ __forceinline__ float bf_lo(u32 v) { return __uint_as_float(v << 16); }
; __device__ __forceinline__ float bf_hi(u32 v) { return __uint_as_float(v & 0xffff0000u); }
; #define POOL_ACC(v, sgn) do { acc0 += sgn bf_lo(v.x); acc1 += sgn bf_hi(v.x); acc2 += sgn bf_lo(v.y); acc3 += sgn bf_hi(v.y); \
;     acc4 += sgn bf_lo(v.z); acc5 += sgn bf_hi(v.z); acc6 += sgn bf_lo(v.w); acc7 += sgn bf_hi(v.w); } while (0)
; template <int WIN>
; __device__ __forceinline__ void pool_run(const u16* U, u16* PL, int tok_s, int c0) {
;   const int pos_s = tok_s & (SEQ - 1);
;   float acc0 = 0.f, acc1 = 0.f, acc2 = 0.f, acc3 = 0.f, acc4 = 0.f, acc5 = 0.f, acc6 = 0.f, acc7 = 0.f;
;   #pragma unroll
;   for (int w = 1; w < WIN; ++w) {
;     if (pos_s - w >= 0) { const uint4 v = *(const uint4*)(U + (long)(tok_s - w) * LD0 + c0); POOL_ACC(v, +); }
;   }
;   #pragma unroll
;   for (int tt = 0; tt < 16; ++tt) {
;     const int tok = tok_s + tt, pos = pos_s + tt;
;     const uint4 cur = *(const uint4*)(U + (long)tok * LD0 + c0);
;     POOL_ACC(cur, +);
;     const float ic = 1.0f / (float)min(WIN, pos + 1);
;     uint4 pk;
;     pk.x = pack2(acc0 * ic - bf_lo(cur.x), acc1 * ic - bf_hi(cur.x));
;     pk.y = pack2(acc2 * ic - bf_lo(cur.y), acc3 * ic - bf_hi(cur.y));
;     pk.z = pack2(acc4 * ic - bf_lo(cur.z), acc5 * ic - bf_hi(cur.z));
;     pk.w = pack2(acc6 * ic - bf_lo(cur.w), acc7 * ic - bf_hi(cur.w));
;     *(uint4*)(PL + (long)tok * 2048 + c0) = pk;
;     if (pos - (WIN - 1) >= 0) { const uint4 old = *(const uint4*)(U + (long)(tok - (WIN - 1)) * LD0 + c0); POOL_ACC(old, -); }
;   }
; }
	v_pk_fma_f32 v[184:185], v[168:169], v[192:193], v[176:177] neg_lo:[0,0,1] neg_hi:[0,0,1]
	v_pk_fma_f32 v[186:187], v[170:171], v[192:193], v[178:179] neg_lo:[0,0,1] neg_hi:[0,0,1]
	v_cvt_pk_bf16_f32 v188, v180, v181
	v_cvt_pk_bf16_f32 v189, v182, v183
	v_cvt_pk_bf16_f32 v190, v184, v185
	v_cvt_pk_bf16_f32 v191, v186, v187
	s_nop 0
	global_store_dwordx4 v[196:197], v[188:191], off
	v_add_co_u32_e32 v196, vcc, 0x1000, v196
	s_nop 1
	v_addc_co_u32_e32 v197, vcc, 0, v197, vcc
	v_lshlrev_b32_e32 v172, 16, v64
	v_and_b32_e32 v173, 0xffff0000, v64
	v_lshlrev_b32_e32 v174, 16, v65
	v_and_b32_e32 v175, 0xffff0000, v65
	v_lshlrev_b32_e32 v176, 16, v66
	v_and_b32_e32 v177, 0xffff0000, v66
	v_lshlrev_b32_e32 v178, 16, v67
	v_and_b32_e32 v179, 0xffff0000, v67
	v_pk_add_f32 v[164:165], v[164:165], v[172:173] neg_lo:[0,1] neg_hi:[0,1]
	v_pk_add_f32 v[166:167], v[166:167], v[174:175] neg_lo:[0,1] neg_hi:[0,1]
	v_pk_add_f32 v[168:169], v[168:169], v[176:177] neg_lo:[0,1] neg_hi:[0,1]
	v_pk_add_f32 v[170:171], v[170:171], v[178:179] neg_lo:[0,1] neg_hi:[0,1]
	v_lshlrev_b32_e32 v172, 16, v80
	v_and_b32_e32 v173, 0xffff0000, v80
	v_lshlrev_b32_e32 v174, 16, v81
	v_and_b32_e32 v175, 0xffff0000, v81
	v_lshlrev_b32_e32 v176, 16, v82
	v_and_b32_e32 v177, 0xffff0000, v82
	v_lshlrev_b32_e32 v178, 16, v83
	v_and_b32_e32 v179, 0xffff0000, v83
	v_pk_add_f32 v[164:165], v[164:165], v[172:173]
	v_pk_add_f32 v[166:167], v[166:167], v[174:175]
	v_pk_add_f32 v[168:169], v[168:169], v[176:177]
	v_pk_add_f32 v[170:171], v[170:171], v[178:179]
	v_pk_fma_f32 v[180:181], v[164:165], v[192:193], v[172:173] neg_lo:[0,0,1] neg_hi:[0,0,1]
	v_pk_fma_f32 v[182:183], v[166:167], v[192:193], v[174:175] neg_lo:[0,0,1] neg_hi:[0,0,1]
	v_pk_fma_f32 v[184:185], v[168:169], v[192:193], v[176:177] neg_lo:[0,0,1] neg_hi:[0,0,1]
	v_pk_fma_f32 v[186:187], v[170:171], v[192:193], v[178:179] neg_lo:[0,0,1] neg_hi:[0,0,1]
	v_cvt_pk_bf16_f32 v200, v180, v181
	v_cvt_pk_bf16_f32 v201, v182, v183
	v_cvt_pk_bf16_f32 v202, v184, v185
	v_cvt_pk_bf16_f32 v203, v186, v187
	s_nop 0
	global_store_dwordx4 v[196:197], v[200:203], off
	v_add_co_u32_e32 v196, vcc, 0x1000, v196
	s_nop 1
	v_addc_co_u32_e32 v197, vcc, 0, v197, vcc
	v_lshlrev_b32_e32 v172, 16, v68
	v_and_b32_e32 v173, 0xffff0000, v68
	v_lshlrev_b32_e32 v174, 16, v69
	v_and_b32_e32 v175, 0xffff0000, v69
	v_lshlrev_b32_e32 v176, 16, v70
	v_and_b32_e32 v177, 0xffff0000, v70
	v_lshlrev_b32_e32 v178, 16, v71
	v_and_b32_e32 v179, 0xffff0000, v71
	v_pk_add_f32 v[164:165], v[164:165], v[172:173] neg_lo:[0,1] neg_hi:[0,1]
	v_pk_add_f32 v[166:167], v[166:167], v[174:175] neg_lo:[0,1] neg_hi:[0,1]
	v_pk_add_f32 v[168:169], v[168:169], v[176:177] neg_lo:[0,1] neg_hi:[0,1]
	v_pk_add_f32 v[170:171], v[170:171], v[178:179] neg_lo:[0,1] neg_hi:[0,1]
	v_lshlrev_b32_e32 v172, 16, v84
	v_and_b32_e32 v173, 0xffff0000, v84
	v_lshlrev_b32_e32 v174, 16, v85
	v_and_b32_e32 v175, 0xffff0000, v85
	v_lshlrev_b32_e32 v176, 16, v86
	v_and_b32_e32 v177, 0xffff0000, v86
	v_lshlrev_b32_e32 v178, 16, v87
	v_and_b32_e32 v179, 0xffff0000, v87
	v_pk_add_f32 v[164:165], v[164:165], v[172:173]
	v_pk_add_f32 v[166:167], v[166:167], v[174:175]
	v_pk_add_f32 v[168:169], v[168:169], v[176:177]
	v_pk_add_f32 v[170:171], v[170:171], v[178:179]
	v_pk_fma_f32 v[180:181], v[164:165], v[192:193], v[172:173] neg_lo:[0,0,1] neg_hi:[0,0,1]
	v_pk_fma_f32 v[182:183], v[166:167], v[192:193], v[174:175] neg_lo:[0,0,1] neg_hi:[0,0,1]
	v_pk_fma_f32 v[184:185], v[168:169], v[192:193], v[176:177] neg_lo:[0,0,1] neg_hi:[0,0,1]
	v_pk_fma_f32 v[186:187], v[170:171], v[192:193], v[178:179] neg_lo:[0,0,1] neg_hi:[0,0,1]
	v_cvt_pk_bf16_f32 v188, v180, v181
	v_cvt_pk_bf16_f32 v189, v182, v183
	v_cvt_pk_bf16_f32 v190, v184, v185
	v_cvt_pk_bf16_f32 v191, v186, v187
	s_nop 0
	global_store_dwordx4 v[196:197], v[188:191], off
	v_add_co_u32_e32 v196, vcc, 0x1000, v196
	s_nop 1
	v_addc_co_u32_e32 v197, vcc, 0, v197, vcc
	v_lshlrev_b32_e32 v172, 16, v72
	v_and_b32_e32 v173, 0xffff0000, v72
	v_lshlrev_b32_e32 v174, 16, v73
	v_and_b32_e32 v175, 0xffff0000, v73
	v_lshlrev_b32_e32 v176, 16, v74
	v_and_b32_e32 v177, 0xffff0000, v74
	v_lshlrev_b32_e32 v178, 16, v75
	v_and_b32_e32 v179, 0xffff0000, v75
	v_pk_add_f32 v[164:165], v[164:165], v[172:173] neg_lo:[0,1] neg_hi:[0,1]
	v_pk_add_f32 v[166:167], v[166:167], v[174:175] neg_lo:[0,1] neg_hi:[0,1]
	v_pk_add_f32 v[168:169], v[168:169], v[176:177] neg_lo:[0,1] neg_hi:[0,1]
	v_pk_add_f32 v[170:171], v[170:171], v[178:179] neg_lo:[0,1] neg_hi:[0,1]
	v_lshlrev_b32_e32 v172, 16, v88
	v_and_b32_e32 v173, 0xffff0000, v88
	v_lshlrev_b32_e32 v174, 16, v89
	v_and_b32_e32 v175, 0xffff0000, v89
	v_lshlrev_b32_e32 v176, 16, v90
	v_and_b32_e32 v177, 0xffff0000, v90
	v_lshlrev_b32_e32 v178, 16, v91
	v_and_b32_e32 v179, 0xffff0000, v91
	v_pk_add_f32 v[164:165], v[164:165], v[172:173]
	v_pk_add_f32 v[166:167], v[166:167], v[174:175]
	v_pk_add_f32 v[168:169], v[168:169], v[176:177]
	v_pk_add_f32 v[170:171], v[170:171], v[178:179]
	v_pk_fma_f32 v[180:181], v[164:165], v[192:193], v[172:173] neg_lo:[0,0,1] neg_hi:[0,0,1]
	v_pk_fma_f32 v[182:183], v[166:167], v[192:193], v[174:175] neg_lo:[0,0,1] neg_hi:[0,0,1]
	v_pk_fma_f32 v[184:185], v[168:169], v[192:193], v[176:177] neg_lo:[0,0,1] neg_hi:[0,0,1]
	v_pk_fma_f32 v[186:187], v[170:171], v[192:193], v[178:179] neg_lo:[0,0,1] neg_hi:[0,0,1]
	v_cvt_pk_bf16_f32 v200, v180, v181
	v_cvt_pk_bf16_f32 v201, v182, v183
	v_cvt_pk_bf16_f32 v202, v184, v185
	v_cvt_pk_bf16_f32 v203, v186, v187
	s_nop 0
	global_store_dwordx4 v[196:197], v[200:203], off
	v_add_co_u32_e32 v196, vcc, 0x1000, v196
	s_nop 1
	v_addc_co_u32_e32 v197, vcc, 0, v197, vcc
; __device__ __forceinline__ float bf_lo(u32 v) { return __uint_as_float(v << 16); }
; __device__ __forceinline__ float bf_hi(u32 v) { return __uint_as_float(v & 0xffff0000u); }
; #define POOL_ACC(v, sgn) do { acc0 += sgn bf_lo(v.x); acc1 += sgn bf_hi(v.x); acc2 += sgn bf_lo(v.y); acc3 += sgn bf_hi(v.y); \
;     acc4 += sgn bf_lo(v.z); acc5 += sgn bf_hi(v.z); acc6 += sgn bf_lo(v.w); acc7 += sgn bf_hi(v.w); } while (0)
; template <int WIN>
; __device__ __forceinline__ void pool_run(const u16* U, u16* PL, int tok_s, int c0) {
;   const int pos_s = tok_s & (SEQ - 1);
;   float acc0 = 0.f, acc1 = 0.f, acc2 = 0.f, acc3 = 0.f, acc4 = 0.f, acc5 = 0.f, acc6 = 0.f, acc7 = 0.f;
;   #pragma unroll
;   for (int w = 1; w < WIN; ++w) {
;     if (pos_s - w >= 0) { const uint4 v = *(const uint4*)(U + (long)(tok_s - w) * LD0 + c0); POOL_ACC(v, +); }
;   }
;   #pragma unroll
;   for (int tt = 0; tt < 16; ++tt) {
;     const int tok = tok_s + tt, pos = pos_s + tt;
;     const uint4 cur = *(const uint4*)(U + (long)tok * LD0 + c0);
;     POOL_ACC(cur, +);
;     const float ic = 1.0f / (float)min(WIN, pos + 1);
;     uint4 pk;
;     pk.x = pack2(acc0 * ic - bf_lo(cur.x), acc1 * ic - bf_hi(cur.x));
;     pk.y = pack2(acc2 * ic - bf_lo(cur.y), acc3 * ic - bf_hi(cur.y));
;     pk.z = pack2(acc4 * ic - bf_lo(cur.z), acc5 * ic - bf_hi(cur.z));
;     pk.w = pack2(acc6 * ic - bf_lo(cur.w), acc7 * ic - bf_hi(cur.w));
;     *(uint4*)(PL + (long)tok * 2048 + c0) = pk;
;     if (pos - (WIN - 1) >= 0) { const uint4 old = *(const uint4*)(U + (long)(tok - (WIN - 1)) * LD0 + c0); POOL_ACC(old, -); }
;   }
; }
; __device__ __forceinline__ void pool_item(const Params& p, int item, const int wv) {
;   const u16* U = (const u16*)(p.ws + OFF_PB0) + 4096;
;   u16* PL = (u16*)(p.ws + OFF_PL);
;   const int tid = opaque_tid(wv), ch = tid & 255, half = tid >> 8;
;   const int c0 = ch * 8;
;   const int tok_s = item * 32 + half * 16;
	v_lshlrev_b32_e32 v172, 16, v76
	v_and_b32_e32 v173, 0xffff0000, v76
	v_lshlrev_b32_e32 v174, 16, v77
	v_and_b32_e32 v175, 0xffff0000, v77
	v_lshlrev_b32_e32 v176, 16, v78
	v_and_b32_e32 v177, 0xffff0000, v78
	v_lshlrev_b32_e32 v178, 16, v79
	v_and_b32_e32 v179, 0xffff0000, v79
	v_pk_add_f32 v[164:165], v[164:165], v[172:173] neg_lo:[0,1] neg_hi:[0,1]
	v_pk_add_f32 v[166:167], v[166:167], v[174:175] neg_lo:[0,1] neg_hi:[0,1]
	v_pk_add_f32 v[168:169], v[168:169], v[176:177] neg_lo:[0,1] neg_hi:[0,1]
	v_pk_add_f32 v[170:171], v[170:171], v[178:179] neg_lo:[0,1] neg_hi:[0,1]
	v_lshlrev_b32_e32 v172, 16, v92
	v_and_b32_e32 v173, 0xffff0000, v92
	v_lshlrev_b32_e32 v174, 16, v93
	v_and_b32_e32 v175, 0xffff0000, v93
	v_lshlrev_b32_e32 v176, 16, v94
	v_and_b32_e32 v177, 0xffff0000, v94
	v_lshlrev_b32_e32 v178, 16, v95
	v_and_b32_e32 v179, 0xffff0000, v95
	v_pk_add_f32 v[164:165], v[164:165], v[172:173]
	v_pk_add_f32 v[166:167], v[166:167], v[174:175]
	v_pk_add_f32 v[168:169], v[168:169], v[176:177]
	v_pk_add_f32 v[170:171], v[170:171], v[178:179]
	v_pk_fma_f32 v[180:181], v[164:165], v[192:193], v[172:173] neg_lo:[0,0,1] neg_hi:[0,0,1]
	v_pk_fma_f32 v[182:183], v[166:167], v[192:193], v[174:175] neg_lo:[0,0,1] neg_hi:[0,0,1]
	v_pk_fma_f32 v[184:185], v[168:169], v[192:193], v[176:177] neg_lo:[0,0,1] neg_hi:[0,0,1]
	v_pk_fma_f32 v[186:187], v[170:171], v[192:193], v[178:179] neg_lo:[0,0,1] neg_hi:[0,0,1]
	v_cvt_pk_bf16_f32 v188, v180, v181
	v_cvt_pk_bf16_f32 v189, v182, v183
	v_cvt_pk_bf16_f32 v190, v184, v185
	v_cvt_pk_bf16_f32 v191, v186, v187
	s_nop 0
	global_store_dwordx4 v[196:197], v[188:191], off
	v_add_co_u32_e32 v196, vcc, 0x1000, v196
	s_nop 1
	v_addc_co_u32_e32 v197, vcc, 0, v197, vcc
	v_lshlrev_b32_e32 v172, 16, v80
	v_and_b32_e32 v173, 0xffff0000, v80
	v_lshlrev_b32_e32 v174, 16, v81
	v_and_b32_e32 v175, 0xffff0000, v81
	v_lshlrev_b32_e32 v176, 16, v82
	v_and_b32_e32 v177, 0xffff0000, v82
	v_lshlrev_b32_e32 v178, 16, v83
	v_and_b32_e32 v179, 0xffff0000, v83
	v_pk_add_f32 v[164:165], v[164:165], v[172:173] neg_lo:[0,1] neg_hi:[0,1]
	v_pk_add_f32 v[166:167], v[166:167], v[174:175] neg_lo:[0,1] neg_hi:[0,1]
	v_pk_add_f32 v[168:169], v[168:169], v[176:177] neg_lo:[0,1] neg_hi:[0,1]
	v_pk_add_f32 v[170:171], v[170:171], v[178:179] neg_lo:[0,1] neg_hi:[0,1]
	v_lshlrev_b32_e32 v172, 16, v96
	v_and_b32_e32 v173, 0xffff0000, v96
	v_lshlrev_b32_e32 v174, 16, v97
	v_and_b32_e32 v175, 0xffff0000, v97
	v_lshlrev_b32_e32 v176, 16, v98
	v_and_b32_e32 v177, 0xffff0000, v98
	v_lshlrev_b32_e32 v178, 16, v99
	v_and_b32_e32 v179, 0xffff0000, v99
	v_pk_add_f32 v[164:165], v[164:165], v[172:173]
	v_pk_add_f32 v[166:167], v[166:167], v[174:175]
	v_pk_add_f32 v[168:169], v[168:169], v[176:177]
	v_pk_add_f32 v[170:171], v[170:171], v[178:179]
	v_pk_fma_f32 v[180:181], v[164:165], v[192:193], v[172:173] neg_lo:[0,0,1] neg_hi:[0,0,1]
	v_pk_fma_f32 v[182:183], v[166:167], v[192:193], v[174:175] neg_lo:[0,0,1] neg_hi:[0,0,1]
	v_pk_fma_f32 v[184:185], v[168:169], v[192:193], v[176:177] neg_lo:[0,0,1] neg_hi:[0,0,1]
	v_pk_fma_f32 v[186:187], v[170:171], v[192:193], v[178:179] neg_lo:[0,0,1] neg_hi:[0,0,1]
	v_cvt_pk_bf16_f32 v200, v180, v181
	v_cvt_pk_bf16_f32 v201, v182, v183
	v_cvt_pk_bf16_f32 v202, v184, v185
	v_cvt_pk_bf16_f32 v203, v186, v187
	s_nop 0
	global_store_dwordx4 v[196:197], v[200:203], off
	s_branch .LBB0_333
.Lpool_w2:
	v_readlane_b32 s0, v255, 20
	v_readlane_b32 s1, v255, 21
	v_lshlrev_b32_e32 v140, 1, v22
	v_add_u32_e32 v0, -1, v16
	s_nop 3
	v_lshl_add_u64 v[18:19], s[0:1], 0, v[140:141]
	v_readlane_b32 s0, v255, 22
	v_readlane_b32 s1, v255, 23
	v_ashrrev_i32_e32 v17, 31, v16
	v_lshlrev_b64 v[12:13], 12, v[16:17]
	s_nop 3
	v_lshl_add_u64 v[20:21], s[0:1], 0, v[140:141]
	v_mad_i64_i32 v[194:195], s[0:1], v0, s13, v[18:19]
	v_lshl_add_u64 v[196:197], v[20:21], 0, v[12:13]
	global_load_dwordx4 v[24:27], v[194:195], off
	v_add_co_u32_e32 v194, vcc, 0x5000, v194
	s_nop 1
	v_addc_co_u32_e32 v195, vcc, 0, v195, vcc
	global_load_dwordx4 v[28:31], v[194:195], off
	v_add_co_u32_e32 v194, vcc, 0x5000, v194
	s_nop 1
	v_addc_co_u32_e32 v195, vcc, 0, v195, vcc
	global_load_dwordx4 v[32:35], v[194:195], off
	v_add_co_u32_e32 v194, vcc, 0x5000, v194
	s_nop 1
	v_addc_co_u32_e32 v195, vcc, 0, v195, vcc
	global_load_dwordx4 v[36:39], v[194:195], off
	v_add_co_u32_e32 v194, vcc, 0x5000, v194
	s_nop 1
	v_addc_co_u32_e32 v195, vcc, 0, v195, vcc
	global_load_dwordx4 v[40:43], v[194:195], off
	v_add_co_u32_e32 v194, vcc, 0x5000, v194
	s_nop 1
	v_addc_co_u32_e32 v195, vcc, 0, v195, vcc
	global_load_dwordx4 v[44:47], v[194:195], off
	v_add_co_u32_e32 v194, vcc, 0x5000, v194
	s_nop 1
	v_addc_co_u32_e32 v195, vcc, 0, v195, vcc
	global_load_dwordx4 v[48:51], v[194:195], off
	v_add_co_u32_e32 v194, vcc, 0x5000, v194
	s_nop 1
	v_addc_co_u32_e32 v195, vcc, 0, v195, vcc
	global_load_dwordx4 v[52:55], v[194:195], off
	v_add_co_u32_e32 v194, vcc, 0x5000, v194
	s_nop 1
	v_addc_co_u32_e32 v195, vcc, 0, v195, vcc
	global_load_dwordx4 v[56:59], v[194:195], off
	v_add_co_u32_e32 v194, vcc, 0x5000, v194
	s_nop 1
	v_addc_co_u32_e32 v195, vcc, 0, v195, vcc
	global_load_dwordx4 v[60:63], v[194:195], off
	v_add_co_u32_e32 v194, vcc, 0x5000, v194
	s_nop 1
	v_addc_co_u32_e32 v195, vcc, 0, v195, vcc
	global_load_dwordx4 v[64:67], v[194:195], off
	v_add_co_u32_e32 v194, vcc, 0x5000, v194
	s_nop 1
	v_addc_co_u32_e32 v195, vcc, 0, v195, vcc
	global_load_dwordx4 v[68:71], v[194:195], off
	v_add_co_u32_e32 v194, vcc, 0x5000, v194
	s_nop 1
	v_addc_co_u32_e32 v195, vcc, 0, v195, vcc
	global_load_dwordx4 v[72:75], v[194:195], off
	v_add_co_u32_e32 v194, vcc, 0x5000, v194
	s_nop 1
	v_addc_co_u32_e32 v195, vcc, 0, v195, vcc
	global_load_dwordx4 v[76:79], v[194:195], off
	v_add_co_u32_e32 v194, vcc, 0x5000, v194
	s_nop 1
	v_addc_co_u32_e32 v195, vcc, 0, v195, vcc
	global_load_dwordx4 v[80:83], v[194:195], off
	v_add_co_u32_e32 v194, vcc, 0x5000, v194
	s_nop 1
	v_addc_co_u32_e32 v195, vcc, 0, v195, vcc
	global_load_dwordx4 v[84:87], v[194:195], off
	v_add_co_u32_e32 v194, vcc, 0x5000, v194
	s_nop 1
	v_addc_co_u32_e32 v195, vcc, 0, v195, vcc
	global_load_dwordx4 v[88:91], v[194:195], off
	v_mov_b32_e32 v192, 0x3f000000
	v_mov_b32_e32 v193, 0x3f000000
	v_mov_b32_e32 v164, 0
	v_mov_b32_e32 v165, 0
	v_mov_b32_e32 v166, 0
	v_mov_b32_e32 v167, 0
	v_mov_b32_e32 v168, 0
	v_mov_b32_e32 v169, 0
	v_mov_b32_e32 v170, 0
	v_mov_b32_e32 v171, 0
	s_waitcnt vmcnt(0)
; __device__ __forceinline__ float bf_lo(u32 v) { return __uint_as_float(v << 16); }
; __device__ __forceinline__ float bf_hi(u32 v) { return __uint_as_float(v & 0xffff0000u); }
; #define POOL_ACC(v, sgn) do { acc0 += sgn bf_lo(v.x); acc1 += sgn bf_hi(v.x); acc2 += sgn bf_lo(v.y); acc3 += sgn bf_hi(v.y); \
;     acc4 += sgn bf_lo(v.z); acc5 += sgn bf_hi(v.z); acc6 += sgn bf_lo(v.w); acc7 += sgn bf_hi(v.w); } while (0)
; template <int WIN>
; __device__ __forceinline__ void pool_run(const u16* U, u16* PL, int tok_s, int c0) {
;   const int pos_s = tok_s & (SEQ - 1);
;   float acc0 = 0.f, acc1 = 0.f, acc2 = 0.f, acc3 = 0.f, acc4 = 0.f, acc5 = 0.f, acc6 = 0.f, acc7 = 0.f;
;   #pragma unroll
;   for (int w = 1; w < WIN; ++w) {
;     if (pos_s - w >= 0) { const uint4 v = *(const uint4*)(U + (long)(tok_s - w) * LD0 + c0); POOL_ACC(v, +); }
;   }
;   #pragma unroll
;   for (int tt = 0; tt < 16; ++tt) {
;     const int tok = tok_s + tt, pos = pos_s + tt;
;     const uint4 cur = *(const uint4*)(U + (long)tok * LD0 + c0);
;     POOL_ACC(cur, +);
;     const float ic = 1.0f / (float)min(WIN, pos + 1);
;     uint4 pk;
;     pk.x = pack2(acc0 * ic - bf_lo(cur.x), acc1 * ic - bf_hi(cur.x));
;     pk.y = pack2(acc2 * ic - bf_lo(cur.y), acc3 * ic - bf_hi(cur.y));
;     pk.z = pack2(acc4 * ic - bf_lo(cur.z), acc5 * ic - bf_hi(cur.z));
;     pk.w = pack2(acc6 * ic - bf_lo(cur.w), acc7 * ic - bf_hi(cur.w));
;     *(uint4*)(PL + (long)tok * 2048 + c0) = pk;
;     if (pos - (WIN - 1) >= 0) { const uint4 old = *(const uint4*)(U + (long)(tok - (WIN - 1)) * LD0 + c0); POOL_ACC(old, -); }
;   }
; }
	v_lshlrev_b32_e32 v172, 16, v24
	v_and_b32_e32 v173, 0xffff0000, v24
	v_lshlrev_b32_e32 v174, 16, v25
	v_and_b32_e32 v175, 0xffff0000, v25
	v_lshlrev_b32_e32 v176, 16, v26
	v_and_b32_e32 v177, 0xffff0000, v26
	v_lshlrev_b32_e32 v178, 16, v27
	v_and_b32_e32 v179, 0xffff0000, v27
	v_pk_add_f32 v[164:165], v[164:165], v[172:173]
	v_pk_add_f32 v[166:167], v[166:167], v[174:175]
	v_pk_add_f32 v[168:169], v[168:169], v[176:177]
	v_pk_add_f32 v[170:171], v[170:171], v[178:179]
	v_lshlrev_b32_e32 v172, 16, v28
	v_and_b32_e32 v173, 0xffff0000, v28
	v_lshlrev_b32_e32 v174, 16, v29
	v_and_b32_e32 v175, 0xffff0000, v29
	v_lshlrev_b32_e32 v176, 16, v30
	v_and_b32_e32 v177, 0xffff0000, v30
	v_lshlrev_b32_e32 v178, 16, v31
	v_and_b32_e32 v179, 0xffff0000, v31
	v_pk_add_f32 v[164:165], v[164:165], v[172:173]
	v_pk_add_f32 v[166:167], v[166:167], v[174:175]
	v_pk_add_f32 v[168:169], v[168:169], v[176:177]
	v_pk_add_f32 v[170:171], v[170:171], v[178:179]
	v_pk_fma_f32 v[180:181], v[164:165], v[192:193], v[172:173] neg_lo:[0,0,1] neg_hi:[0,0,1]
	v_pk_fma_f32 v[182:183], v[166:167], v[192:193], v[174:175] neg_lo:[0,0,1] neg_hi:[0,0,1]
	v_pk_fma_f32 v[184:185], v[168:169], v[192:193], v[176:177] neg_lo:[0,0,1] neg_hi:[0,0,1]
	v_pk_fma_f32 v[186:187], v[170:171], v[192:193], v[178:179] neg_lo:[0,0,1] neg_hi:[0,0,1]
	v_cvt_pk_bf16_f32 v188, v180, v181
	v_cvt_pk_bf16_f32 v189, v182, v183
	v_cvt_pk_bf16_f32 v190, v184, v185
	v_cvt_pk_bf16_f32 v191, v186, v187
	s_nop 0
	global_store_dwordx4 v[196:197], v[188:191], off
	v_add_co_u32_e32 v196, vcc, 0x1000, v196
	s_nop 1
	v_addc_co_u32_e32 v197, vcc, 0, v197, vcc
	v_lshlrev_b32_e32 v172, 16, v24
	v_and_b32_e32 v173, 0xffff0000, v24
	v_lshlrev_b32_e32 v174, 16, v25
	v_and_b32_e32 v175, 0xffff0000, v25
	v_lshlrev_b32_e32 v176, 16, v26
	v_and_b32_e32 v177, 0xffff0000, v26
	v_lshlrev_b32_e32 v178, 16, v27
	v_and_b32_e32 v179, 0xffff0000, v27
	v_pk_add_f32 v[164:165], v[164:165], v[172:173] neg_lo:[0,1] neg_hi:[0,1]
	v_pk_add_f32 v[166:167], v[166:167], v[174:175] neg_lo:[0,1] neg_hi:[0,1]
	v_pk_add_f32 v[168:169], v[168:169], v[176:177] neg_lo:[0,1] neg_hi:[0,1]
	v_pk_add_f32 v[170:171], v[170:171], v[178:179] neg_lo:[0,1] neg_hi:[0,1]
	v_lshlrev_b32_e32 v172, 16, v32
	v_and_b32_e32 v173, 0xffff0000, v32
	v_lshlrev_b32_e32 v174, 16, v33
	v_and_b32_e32 v175, 0xffff0000, v33
	v_lshlrev_b32_e32 v176, 16, v34
	v_and_b32_e32 v177, 0xffff0000, v34
	v_lshlrev_b32_e32 v178, 16, v35
	v_and_b32_e32 v179, 0xffff0000, v35
	v_pk_add_f32 v[164:165], v[164:165], v[172:173]
	v_pk_add_f32 v[166:167], v[166:167], v[174:175]
	v_pk_add_f32 v[168:169], v[168:169], v[176:177]
	v_pk_add_f32 v[170:171], v[170:171], v[178:179]
	v_pk_fma_f32 v[180:181], v[164:165], v[192:193], v[172:173] neg_lo:[0,0,1] neg_hi:[0,0,1]
	v_pk_fma_f32 v[182:183], v[166:167], v[192:193], v[174:175] neg_lo:[0,0,1] neg_hi:[0,0,1]
	v_pk_fma_f32 v[184:185], v[168:169], v[192:193], v[176:177] neg_lo:[0,0,1] neg_hi:[0,0,1]
	v_pk_fma_f32 v[186:187], v[170:171], v[192:193], v[178:179] neg_lo:[0,0,1] neg_hi:[0,0,1]
	v_cvt_pk_bf16_f32 v200, v180, v181
	v_cvt_pk_bf16_f32 v201, v182, v183
	v_cvt_pk_bf16_f32 v202, v184, v185
	v_cvt_pk_bf16_f32 v203, v186, v187
	s_nop 0
	global_store_dwordx4 v[196:197], v[200:203], off
	v_add_co_u32_e32 v196, vcc, 0x1000, v196
	s_nop 1
	v_addc_co_u32_e32 v197, vcc, 0, v197, vcc
	v_lshlrev_b32_e32 v172, 16, v28
	v_and_b32_e32 v173, 0xffff0000, v28
	v_lshlrev_b32_e32 v174, 16, v29
	v_and_b32_e32 v175, 0xffff0000, v29
	v_lshlrev_b32_e32 v176, 16, v30
	v_and_b32_e32 v177, 0xffff0000, v30
	v_lshlrev_b32_e32 v178, 16, v31
	v_and_b32_e32 v179, 0xffff0000, v31
	v_pk_add_f32 v[164:165], v[164:165], v[172:173] neg_lo:[0,1] neg_hi:[0,1]
	v_pk_add_f32 v[166:167], v[166:167], v[174:175] neg_lo:[0,1] neg_hi:[0,1]
	v_pk_add_f32 v[168:169], v[168:169], v[176:177] neg_lo:[0,1] neg_hi:[0,1]
	v_pk_add_f32 v[170:171], v[170:171], v[178:179] neg_lo:[0,1] neg_hi:[0,1]
	v_lshlrev_b32_e32 v172, 16, v36
	v_and_b32_e32 v173, 0xffff0000, v36
	v_lshlrev_b32_e32 v174, 16, v37
	v_and_b32_e32 v175, 0xffff0000, v37
	v_lshlrev_b32_e32 v176, 16, v38
	v_and_b32_e32 v177, 0xffff0000, v38
	v_lshlrev_b32_e32 v178, 16, v39
	v_and_b32_e32 v179, 0xffff0000, v39
	v_pk_add_f32 v[164:165], v[164:165], v[172:173]
	v_pk_add_f32 v[166:167], v[166:167], v[174:175]
	v_pk_add_f32 v[168:169], v[168:169], v[176:177]
	v_pk_add_f32 v[170:171], v[170:171], v[178:179]
	v_pk_fma_f32 v[180:181], v[164:165], v[192:193], v[172:173] neg_lo:[0,0,1] neg_hi:[0,0,1]
	v_pk_fma_f32 v[182:183], v[166:167], v[192:193], v[174:175] neg_lo:[0,0,1] neg_hi:[0,0,1]
	v_pk_fma_f32 v[184:185], v[168:169], v[192:193], v[176:177] neg_lo:[0,0,1] neg_hi:[0,0,1]
	v_pk_fma_f32 v[186:187], v[170:171], v[192:193], v[178:179] neg_lo:[0,0,1] neg_hi:[0,0,1]
	v_cvt_pk_bf16_f32 v188, v180, v181
	v_cvt_pk_bf16_f32 v189, v182, v183
	v_cvt_pk_bf16_f32 v190, v184, v185
	v_cvt_pk_bf16_f32 v191, v186, v187
	s_nop 0
	global_store_dwordx4 v[196:197], v[188:191], off
	v_add_co_u32_e32 v196, vcc, 0x1000, v196
	s_nop 1
	v_addc_co_u32_e32 v197, vcc, 0, v197, vcc
	v_lshlrev_b32_e32 v172, 16, v32
	v_and_b32_e32 v173, 0xffff0000, v32
	v_lshlrev_b32_e32 v174, 16, v33
	v_and_b32_e32 v175, 0xffff0000, v33
	v_lshlrev_b32_e32 v176, 16, v34
	v_and_b32_e32 v177, 0xffff0000, v34
	v_lshlrev_b32_e32 v178, 16, v35
	v_and_b32_e32 v179, 0xffff0000, v35
	v_pk_add_f32 v[164:165], v[164:165], v[172:173] neg_lo:[0,1] neg_hi:[0,1]
	v_pk_add_f32 v[166:167], v[166:167], v[174:175] neg_lo:[0,1] neg_hi:[0,1]
	v_pk_add_f32 v[168:169], v[168:169], v[176:177] neg_lo:[0,1] neg_hi:[0,1]
	v_pk_add_f32 v[170:171], v[170:171], v[178:179] neg_lo:[0,1] neg_hi:[0,1]
; __device__ __forceinline__ float bf_lo(u32 v) { return __uint_as_float(v << 16); }
; __device__ __forceinline__ float bf_hi(u32 v) { return __uint_as_float(v & 0xffff0000u); }
; #define POOL_ACC(v, sgn) do { acc0 += sgn bf_lo(v.x); acc1 += sgn bf_hi(v.x); acc2 += sgn bf_lo(v.y); acc3 += sgn bf_hi(v.y); \
;     acc4 += sgn bf_lo(v.z); acc5 += sgn bf_hi(v.z); acc6 += sgn bf_lo(v.w); acc7 += sgn bf_hi(v.w); } while (0)
; template <int WIN>
; __device__ __forceinline__ void pool_run(const u16* U, u16* PL, int tok_s, int c0) {
;   const int pos_s = tok_s & (SEQ - 1);
;   float acc0 = 0.f, acc1 = 0.f, acc2 = 0.f, acc3 = 0.f, acc4 = 0.f, acc5 = 0.f, acc6 = 0.f, acc7 = 0.f;
;   #pragma unroll
;   for (int w = 1; w < WIN; ++w) {
;     if (pos_s - w >= 0) { const uint4 v = *(const uint4*)(U + (long)(tok_s - w) * LD0 + c0); POOL_ACC(v, +); }
;   }
;   #pragma unroll
;   for (int tt = 0; tt < 16; ++tt) {
;     const int tok = tok_s + tt, pos = pos_s + tt;
;     const uint4 cur = *(const uint4*)(U + (long)tok * LD0 + c0);
;     POOL_ACC(cur, +);
;     const float ic = 1.0f / (float)min(WIN, pos + 1);
;     uint4 pk;
;     pk.x = pack2(acc0 * ic - bf_lo(cur.x), acc1 * ic - bf_hi(cur.x));
;     pk.y = pack2(acc2 * ic - bf_lo(cur.y), acc3 * ic - bf_hi(cur.y));
;     pk.z = pack2(acc4 * ic - bf_lo(cur.z), acc5 * ic - bf_hi(cur.z));
;     pk.w = pack2(acc6 * ic - bf_lo(cur.w), acc7 * ic - bf_hi(cur.w));
;     *(uint4*)(PL + (long)tok * 2048 + c0) = pk;
;     if (pos - (WIN - 1) >= 0) { const uint4 old = *(const uint4*)(U + (long)(tok - (WIN - 1)) * LD0 + c0); POOL_ACC(old, -); }
;   }
; }
	v_lshlrev_b32_e32 v172, 16, v40
	v_and_b32_e32 v173, 0xffff0000, v40
	v_lshlrev_b32_e32 v174, 16, v41
	v_and_b32_e32 v175, 0xffff0000, v41
	v_lshlrev_b32_e32 v176, 16, v42
	v_and_b32_e32 v177, 0xffff0000, v42
	v_lshlrev_b32_e32 v178, 16, v43
	v_and_b32_e32 v179, 0xffff0000, v43
	v_pk_add_f32 v[164:165], v[164:165], v[172:173]
	v_pk_add_f32 v[166:167], v[166:167], v[174:175]
	v_pk_add_f32 v[168:169], v[168:169], v[176:177]
	v_pk_add_f32 v[170:171], v[170:171], v[178:179]
	v_pk_fma_f32 v[180:181], v[164:165], v[192:193], v[172:173] neg_lo:[0,0,1] neg_hi:[0,0,1]
	v_pk_fma_f32 v[182:183], v[166:167], v[192:193], v[174:175] neg_lo:[0,0,1] neg_hi:[0,0,1]
	v_pk_fma_f32 v[184:185], v[168:169], v[192:193], v[176:177] neg_lo:[0,0,1] neg_hi:[0,0,1]
	v_pk_fma_f32 v[186:187], v[170:171], v[192:193], v[178:179] neg_lo:[0,0,1] neg_hi:[0,0,1]
	v_cvt_pk_bf16_f32 v200, v180, v181
	v_cvt_pk_bf16_f32 v201, v182, v183
	v_cvt_pk_bf16_f32 v202, v184, v185
	v_cvt_pk_bf16_f32 v203, v186, v187
	s_nop 0
	global_store_dwordx4 v[196:197], v[200:203], off
	v_add_co_u32_e32 v196, vcc, 0x1000, v196
	s_nop 1
	v_addc_co_u32_e32 v197, vcc, 0, v197, vcc
	v_lshlrev_b32_e32 v172, 16, v36
	v_and_b32_e32 v173, 0xffff0000, v36
	v_lshlrev_b32_e32 v174, 16, v37
	v_and_b32_e32 v175, 0xffff0000, v37
	v_lshlrev_b32_e32 v176, 16, v38
	v_and_b32_e32 v177, 0xffff0000, v38
	v_lshlrev_b32_e32 v178, 16, v39
	v_and_b32_e32 v179, 0xffff0000, v39
	v_pk_add_f32 v[164:165], v[164:165], v[172:173] neg_lo:[0,1] neg_hi:[0,1]
	v_pk_add_f32 v[166:167], v[166:167], v[174:175] neg_lo:[0,1] neg_hi:[0,1]
	v_pk_add_f32 v[168:169], v[168:169], v[176:177] neg_lo:[0,1] neg_hi:[0,1]
	v_pk_add_f32 v[170:171], v[170:171], v[178:179] neg_lo:[0,1] neg_hi:[0,1]
	v_lshlrev_b32_e32 v172, 16, v44
	v_and_b32_e32 v173, 0xffff0000, v44
	v_lshlrev_b32_e32 v174, 16, v45
	v_and_b32_e32 v175, 0xffff0000, v45
	v_lshlrev_b32_e32 v176, 16, v46
	v_and_b32_e32 v177, 0xffff0000, v46
	v_lshlrev_b32_e32 v178, 16, v47
	v_and_b32_e32 v179, 0xffff0000, v47
	v_pk_add_f32 v[164:165], v[164:165], v[172:173]
	v_pk_add_f32 v[166:167], v[166:167], v[174:175]
	v_pk_add_f32 v[168:169], v[168:169], v[176:177]
	v_pk_add_f32 v[170:171], v[170:171], v[178:179]
	v_pk_fma_f32 v[180:181], v[164:165], v[192:193], v[172:173] neg_lo:[0,0,1] neg_hi:[0,0,1]
	v_pk_fma_f32 v[182:183], v[166:167], v[192:193], v[174:175] neg_lo:[0,0,1] neg_hi:[0,0,1]
	v_pk_fma_f32 v[184:185], v[168:169], v[192:193], v[176:177] neg_lo:[0,0,1] neg_hi:[0,0,1]
	v_pk_fma_f32 v[186:187], v[170:171], v[192:193], v[178:179] neg_lo:[0,0,1] neg_hi:[0,0,1]
	v_cvt_pk_bf16_f32 v188, v180, v181
	v_cvt_pk_bf16_f32 v189, v182, v183
	v_cvt_pk_bf16_f32 v190, v184, v185
	v_cvt_pk_bf16_f32 v191, v186, v187
	s_nop 0
	global_store_dwordx4 v[196:197], v[188:191], off
	v_add_co_u32_e32 v196, vcc, 0x1000, v196
	s_nop 1
	v_addc_co_u32_e32 v197, vcc, 0, v197, vcc
	v_lshlrev_b32_e32 v172, 16, v40
	v_and_b32_e32 v173, 0xffff0000, v40
	v_lshlrev_b32_e32 v174, 16, v41
	v_and_b32_e32 v175, 0xffff0000, v41
	v_lshlrev_b32_e32 v176, 16, v42
	v_and_b32_e32 v177, 0xffff0000, v42
	v_lshlrev_b32_e32 v178, 16, v43
	v_and_b32_e32 v179, 0xffff0000, v43
	v_pk_add_f32 v[164:165], v[164:165], v[172:173] neg_lo:[0,1] neg_hi:[0,1]
	v_pk_add_f32 v[166:167], v[166:167], v[174:175] neg_lo:[0,1] neg_hi:[0,1]
	v_pk_add_f32 v[168:169], v[168:169], v[176:177] neg_lo:[0,1] neg_hi:[0,1]
	v_pk_add_f32 v[170:171], v[170:171], v[178:179] neg_lo:[0,1] neg_hi:[0,1]
	v_lshlrev_b32_e32 v172, 16, v48
	v_and_b32_e32 v173, 0xffff0000, v48
	v_lshlrev_b32_e32 v174, 16, v49
	v_and_b32_e32 v175, 0xffff0000, v49
	v_lshlrev_b32_e32 v176, 16, v50
	v_and_b32_e32 v177, 0xffff0000, v50
	v_lshlrev_b32_e32 v178, 16, v51
	v_and_b32_e32 v179, 0xffff0000, v51
	v_pk_add_f32 v[164:165], v[164:165], v[172:173]
	v_pk_add_f32 v[166:167], v[166:167], v[174:175]
	v_pk_add_f32 v[168:169], v[168:169], v[176:177]
	v_pk_add_f32 v[170:171], v[170:171], v[178:179]
	v_pk_fma_f32 v[180:181], v[164:165], v[192:193], v[172:173] neg_lo:[0,0,1] neg_hi:[0,0,1]
	v_pk_fma_f32 v[182:183], v[166:167], v[192:193], v[174:175] neg_lo:[0,0,1] neg_hi:[0,0,1]
	v_pk_fma_f32 v[184:185], v[168:169], v[192:193], v[176:177] neg_lo:[0,0,1] neg_hi:[0,0,1]
	v_pk_fma_f32 v[186:187], v[170:171], v[192:193], v[178:179] neg_lo:[0,0,1] neg_hi:[0,0,1]
	v_cvt_pk_bf16_f32 v200, v180, v181
	v_cvt_pk_bf16_f32 v201, v182, v183
	v_cvt_pk_bf16_f32 v202, v184, v185
	v_cvt_pk_bf16_f32 v203, v186, v187
	s_nop 0
	global_store_dwordx4 v[196:197], v[200:203], off
	v_add_co_u32_e32 v196, vcc, 0x1000, v196
	s_nop 1
	v_addc_co_u32_e32 v197, vcc, 0, v197, vcc
	v_lshlrev_b32_e32 v172, 16, v44
	v_and_b32_e32 v173, 0xffff0000, v44
	v_lshlrev_b32_e32 v174, 16, v45
	v_and_b32_e32 v175, 0xffff0000, v45
	v_lshlrev_b32_e32 v176, 16, v46
	v_and_b32_e32 v177, 0xffff0000, v46
	v_lshlrev_b32_e32 v178, 16, v47
	v_and_b32_e32 v179, 0xffff0000, v47
	v_pk_add_f32 v[164:165], v[164:165], v[172:173] neg_lo:[0,1] neg_hi:[0,1]
	v_pk_add_f32 v[166:167], v[166:167], v[174:175] neg_lo:[0,1] neg_hi:[0,1]
	v_pk_add_f32 v[168:169], v[168:169], v[176:177] neg_lo:[0,1] neg_hi:[0,1]
	v_pk_add_f32 v[170:171], v[170:171], v[178:179] neg_lo:[0,1] neg_hi:[0,1]
	v_lshlrev_b32_e32 v172, 16, v52
	v_and_b32_e32 v173, 0xffff0000, v52
	v_lshlrev_b32_e32 v174, 16, v53
	v_and_b32_e32 v175, 0xffff0000, v53
	v_lshlrev_b32_e32 v176, 16, v54
	v_and_b32_e32 v177, 0xffff0000, v54
	v_lshlrev_b32_e32 v178, 16, v55
	v_and_b32_e32 v179, 0xffff0000, v55
	v_pk_add_f32 v[164:165], v[164:165], v[172:173]
	v_pk_add_f32 v[166:167], v[166:167], v[174:175]
	v_pk_add_f32 v[168:169], v[168:169], v[176:177]
	v_pk_add_f32 v[170:171], v[170:171], v[178:179]
; __device__ __forceinline__ float bf_lo(u32 v) { return __uint_as_float(v << 16); }
; __device__ __forceinline__ float bf_hi(u32 v) { return __uint_as_float(v & 0xffff0000u); }
; #define POOL_ACC(v, sgn) do { acc0 += sgn bf_lo(v.x); acc1 += sgn bf_hi(v.x); acc2 += sgn bf_lo(v.y); acc3 += sgn bf_hi(v.y); \
;     acc4 += sgn bf_lo(v.z); acc5 += sgn bf_hi(v.z); acc6 += sgn bf_lo(v.w); acc7 += sgn bf_hi(v.w); } while (0)
; template <int WIN>
; __device__ __forceinline__ void pool_run(const u16* U, u16* PL, int tok_s, int c0) {
;   const int pos_s = tok_s & (SEQ - 1);
;   float acc0 = 0.f, acc1 = 0.f, acc2 = 0.f, acc3 = 0.f, acc4 = 0.f, acc5 = 0.f, acc6 = 0.f, acc7 = 0.f;
;   #pragma unroll
;   for (int w = 1; w < WIN; ++w) {
;     if (pos_s - w >= 0) { const uint4 v = *(const uint4*)(U + (long)(tok_s - w) * LD0 + c0); POOL_ACC(v, +); }
;   }
;   #pragma unroll
;   for (int tt = 0; tt < 16; ++tt) {
;     const int tok = tok_s + tt, pos = pos_s + tt;
;     const uint4 cur = *(const uint4*)(U + (long)tok * LD0 + c0);
;     POOL_ACC(cur, +);
;     const float ic = 1.0f / (float)min(WIN, pos + 1);
;     uint4 pk;
;     pk.x = pack2(acc0 * ic - bf_lo(cur.x), acc1 * ic - bf_hi(cur.x));
;     pk.y = pack2(acc2 * ic - bf_lo(cur.y), acc3 * ic - bf_hi(cur.y));
;     pk.z = pack2(acc4 * ic - bf_lo(cur.z), acc5 * ic - bf_hi(cur.z));
;     pk.w = pack2(acc6 * ic - bf_lo(cur.w), acc7 * ic - bf_hi(cur.w));
;     *(uint4*)(PL + (long)tok * 2048 + c0) = pk;
;     if (pos - (WIN - 1) >= 0) { const uint4 old = *(const uint4*)(U + (long)(tok - (WIN - 1)) * LD0 + c0); POOL_ACC(old, -); }
;   }
; }
	v_pk_fma_f32 v[180:181], v[164:165], v[192:193], v[172:173] neg_lo:[0,0,1] neg_hi:[0,0,1]
	v_pk_fma_f32 v[182:183], v[166:167], v[192:193], v[174:175] neg_lo:[0,0,1] neg_hi:[0,0,1]
	v_pk_fma_f32 v[184:185], v[168:169], v[192:193], v[176:177] neg_lo:[0,0,1] neg_hi:[0,0,1]
	v_pk_fma_f32 v[186:187], v[170:171], v[192:193], v[178:179] neg_lo:[0,0,1] neg_hi:[0,0,1]
	v_cvt_pk_bf16_f32 v188, v180, v181
	v_cvt_pk_bf16_f32 v189, v182, v183
	v_cvt_pk_bf16_f32 v190, v184, v185
	v_cvt_pk_bf16_f32 v191, v186, v187
	s_nop 0
	global_store_dwordx4 v[196:197], v[188:191], off
	v_add_co_u32_e32 v196, vcc, 0x1000, v196
	s_nop 1
	v_addc_co_u32_e32 v197, vcc, 0, v197, vcc
	v_lshlrev_b32_e32 v172, 16, v48
	v_and_b32_e32 v173, 0xffff0000, v48
	v_lshlrev_b32_e32 v174, 16, v49
	v_and_b32_e32 v175, 0xffff0000, v49
	v_lshlrev_b32_e32 v176, 16, v50
	v_and_b32_e32 v177, 0xffff0000, v50
	v_lshlrev_b32_e32 v178, 16, v51
	v_and_b32_e32 v179, 0xffff0000, v51
	v_pk_add_f32 v[164:165], v[164:165], v[172:173] neg_lo:[0,1] neg_hi:[0,1]
	v_pk_add_f32 v[166:167], v[166:167], v[174:175] neg_lo:[0,1] neg_hi:[0,1]
	v_pk_add_f32 v[168:169], v[168:169], v[176:177] neg_lo:[0,1] neg_hi:[0,1]
	v_pk_add_f32 v[170:171], v[170:171], v[178:179] neg_lo:[0,1] neg_hi:[0,1]
	v_lshlrev_b32_e32 v172, 16, v56
	v_and_b32_e32 v173, 0xffff0000, v56
	v_lshlrev_b32_e32 v174, 16, v57
	v_and_b32_e32 v175, 0xffff0000, v57
	v_lshlrev_b32_e32 v176, 16, v58
	v_and_b32_e32 v177, 0xffff0000, v58
	v_lshlrev_b32_e32 v178, 16, v59
	v_and_b32_e32 v179, 0xffff0000, v59
	v_pk_add_f32 v[164:165], v[164:165], v[172:173]
	v_pk_add_f32 v[166:167], v[166:167], v[174:175]
	v_pk_add_f32 v[168:169], v[168:169], v[176:177]
	v_pk_add_f32 v[170:171], v[170:171], v[178:179]
	v_pk_fma_f32 v[180:181], v[164:165], v[192:193], v[172:173] neg_lo:[0,0,1] neg_hi:[0,0,1]
	v_pk_fma_f32 v[182:183], v[166:167], v[192:193], v[174:175] neg_lo:[0,0,1] neg_hi:[0,0,1]
	v_pk_fma_f32 v[184:185], v[168:169], v[192:193], v[176:177] neg_lo:[0,0,1] neg_hi:[0,0,1]
	v_pk_fma_f32 v[186:187], v[170:171], v[192:193], v[178:179] neg_lo:[0,0,1] neg_hi:[0,0,1]
	v_cvt_pk_bf16_f32 v200, v180, v181
	v_cvt_pk_bf16_f32 v201, v182, v183
	v_cvt_pk_bf16_f32 v202, v184, v185
	v_cvt_pk_bf16_f32 v203, v186, v187
	s_nop 0
	global_store_dwordx4 v[196:197], v[200:203], off
	v_add_co_u32_e32 v196, vcc, 0x1000, v196
	s_nop 1
	v_addc_co_u32_e32 v197, vcc, 0, v197, vcc
	v_lshlrev_b32_e32 v172, 16, v52
	v_and_b32_e32 v173, 0xffff0000, v52
	v_lshlrev_b32_e32 v174, 16, v53
	v_and_b32_e32 v175, 0xffff0000, v53
	v_lshlrev_b32_e32 v176, 16, v54
	v_and_b32_e32 v177, 0xffff0000, v54
	v_lshlrev_b32_e32 v178, 16, v55
	v_and_b32_e32 v179, 0xffff0000, v55
	v_pk_add_f32 v[164:165], v[164:165], v[172:173] neg_lo:[0,1] neg_hi:[0,1]
	v_pk_add_f32 v[166:167], v[166:167], v[174:175] neg_lo:[0,1] neg_hi:[0,1]
	v_pk_add_f32 v[168:169], v[168:169], v[176:177] neg_lo:[0,1] neg_hi:[0,1]
	v_pk_add_f32 v[170:171], v[170:171], v[178:179] neg_lo:[0,1] neg_hi:[0,1]
	v_lshlrev_b32_e32 v172, 16, v60
	v_and_b32_e32 v173, 0xffff0000, v60
	v_lshlrev_b32_e32 v174, 16, v61
	v_and_b32_e32 v175, 0xffff0000, v61
	v_lshlrev_b32_e32 v176, 16, v62
	v_and_b32_e32 v177, 0xffff0000, v62
	v_lshlrev_b32_e32 v178, 16, v63
	v_and_b32_e32 v179, 0xffff0000, v63
	v_pk_add_f32 v[164:165], v[164:165], v[172:173]
	v_pk_add_f32 v[166:167], v[166:167], v[174:175]
	v_pk_add_f32 v[168:169], v[168:169], v[176:177]
	v_pk_add_f32 v[170:171], v[170:171], v[178:179]
	v_pk_fma_f32 v[180:181], v[164:165], v[192:193], v[172:173] neg_lo:[0,0,1] neg_hi:[0,0,1]
	v_pk_fma_f32 v[182:183], v[166:167], v[192:193], v[174:175] neg_lo:[0,0,1] neg_hi:[0,0,1]
	v_pk_fma_f32 v[184:185], v[168:169], v[192:193], v[176:177] neg_lo:[0,0,1] neg_hi:[0,0,1]
	v_pk_fma_f32 v[186:187], v[170:171], v[192:193], v[178:179] neg_lo:[0,0,1] neg_hi:[0,0,1]
	v_cvt_pk_bf16_f32 v188, v180, v181
	v_cvt_pk_bf16_f32 v189, v182, v183
	v_cvt_pk_bf16_f32 v190, v184, v185
	v_cvt_pk_bf16_f32 v191, v186, v187
	s_nop 0
	global_store_dwordx4 v[196:197], v[188:191], off
	v_add_co_u32_e32 v196, vcc, 0x1000, v196
	s_nop 1
	v_addc_co_u32_e32 v197, vcc, 0, v197, vcc
	v_lshlrev_b32_e32 v172, 16, v56
	v_and_b32_e32 v173, 0xffff0000, v56
	v_lshlrev_b32_e32 v174, 16, v57
	v_and_b32_e32 v175, 0xffff0000, v57
	v_lshlrev_b32_e32 v176, 16, v58
	v_and_b32_e32 v177, 0xffff0000, v58
	v_lshlrev_b32_e32 v178, 16, v59
	v_and_b32_e32 v179, 0xffff0000, v59
	v_pk_add_f32 v[164:165], v[164:165], v[172:173] neg_lo:[0,1] neg_hi:[0,1]
	v_pk_add_f32 v[166:167], v[166:167], v[174:175] neg_lo:[0,1] neg_hi:[0,1]
	v_pk_add_f32 v[168:169], v[168:169], v[176:177] neg_lo:[0,1] neg_hi:[0,1]
	v_pk_add_f32 v[170:171], v[170:171], v[178:179] neg_lo:[0,1] neg_hi:[0,1]
	v_lshlrev_b32_e32 v172, 16, v64
	v_and_b32_e32 v173, 0xffff0000, v64
	v_lshlrev_b32_e32 v174, 16, v65
	v_and_b32_e32 v175, 0xffff0000, v65
	v_lshlrev_b32_e32 v176, 16, v66
	v_and_b32_e32 v177, 0xffff0000, v66
	v_lshlrev_b32_e32 v178, 16, v67
	v_and_b32_e32 v179, 0xffff0000, v67
	v_pk_add_f32 v[164:165], v[164:165], v[172:173]
	v_pk_add_f32 v[166:167], v[166:167], v[174:175]
	v_pk_add_f32 v[168:169], v[168:169], v[176:177]
	v_pk_add_f32 v[170:171], v[170:171], v[178:179]
	v_pk_fma_f32 v[180:181], v[164:165], v[192:193], v[172:173] neg_lo:[0,0,1] neg_hi:[0,0,1]
	v_pk_fma_f32 v[182:183], v[166:167], v[192:193], v[174:175] neg_lo:[0,0,1] neg_hi:[0,0,1]
	v_pk_fma_f32 v[184:185], v[168:169], v[192:193], v[176:177] neg_lo:[0,0,1] neg_hi:[0,0,1]
	v_pk_fma_f32 v[186:187], v[170:171], v[192:193], v[178:179] neg_lo:[0,0,1] neg_hi:[0,0,1]
	v_cvt_pk_bf16_f32 v200, v180, v181
	v_cvt_pk_bf16_f32 v201, v182, v183
	v_cvt_pk_bf16_f32 v202, v184, v185
; __device__ __forceinline__ float bf_lo(u32 v) { return __uint_as_float(v << 16); }
; __device__ __forceinline__ float bf_hi(u32 v) { return __uint_as_float(v & 0xffff0000u); }
; #define POOL_ACC(v, sgn) do { acc0 += sgn bf_lo(v.x); acc1 += sgn bf_hi(v.x); acc2 += sgn bf_lo(v.y); acc3 += sgn bf_hi(v.y); \
;     acc4 += sgn bf_lo(v.z); acc5 += sgn bf_hi(v.z); acc6 += sgn bf_lo(v.w); acc7 += sgn bf_hi(v.w); } while (0)
; template <int WIN>
; __device__ __forceinline__ void pool_run(const u16* U, u16* PL, int tok_s, int c0) {
;   const int pos_s = tok_s & (SEQ - 1);
;   float acc0 = 0.f, acc1 = 0.f, acc2 = 0.f, acc3 = 0.f, acc4 = 0.f, acc5 = 0.f, acc6 = 0.f, acc7 = 0.f;
;   #pragma unroll
;   for (int w = 1; w < WIN; ++w) {
;     if (pos_s - w >= 0) { const uint4 v = *(const uint4*)(U + (long)(tok_s - w) * LD0 + c0); POOL_ACC(v, +); }
;   }
;   #pragma unroll
;   for (int tt = 0; tt < 16; ++tt) {
;     const int tok = tok_s + tt, pos = pos_s + tt;
;     const uint4 cur = *(const uint4*)(U + (long)tok * LD0 + c0);
;     POOL_ACC(cur, +);
;     const float ic = 1.0f / (float)min(WIN, pos + 1);
;     uint4 pk;
;     pk.x = pack2(acc0 * ic - bf_lo(cur.x), acc1 * ic - bf_hi(cur.x));
;     pk.y = pack2(acc2 * ic - bf_lo(cur.y), acc3 * ic - bf_hi(cur.y));
;     pk.z = pack2(acc4 * ic - bf_lo(cur.z), acc5 * ic - bf_hi(cur.z));
;     pk.w = pack2(acc6 * ic - bf_lo(cur.w), acc7 * ic - bf_hi(cur.w));
;     *(uint4*)(PL + (long)tok * 2048 + c0) = pk;
;     if (pos - (WIN - 1) >= 0) { const uint4 old = *(const uint4*)(U + (long)(tok - (WIN - 1)) * LD0 + c0); POOL_ACC(old, -); }
;   }
; }
	v_cvt_pk_bf16_f32 v203, v186, v187
	s_nop 0
	global_store_dwordx4 v[196:197], v[200:203], off
	v_add_co_u32_e32 v196, vcc, 0x1000, v196
	s_nop 1
	v_addc_co_u32_e32 v197, vcc, 0, v197, vcc
	v_lshlrev_b32_e32 v172, 16, v60
	v_and_b32_e32 v173, 0xffff0000, v60
	v_lshlrev_b32_e32 v174, 16, v61
	v_and_b32_e32 v175, 0xffff0000, v61
	v_lshlrev_b32_e32 v176, 16, v62
	v_and_b32_e32 v177, 0xffff0000, v62
	v_lshlrev_b32_e32 v178, 16, v63
	v_and_b32_e32 v179, 0xffff0000, v63
	v_pk_add_f32 v[164:165], v[164:165], v[172:173] neg_lo:[0,1] neg_hi:[0,1]
	v_pk_add_f32 v[166:167], v[166:167], v[174:175] neg_lo:[0,1] neg_hi:[0,1]
	v_pk_add_f32 v[168:169], v[168:169], v[176:177] neg_lo:[0,1] neg_hi:[0,1]
	v_pk_add_f32 v[170:171], v[170:171], v[178:179] neg_lo:[0,1] neg_hi:[0,1]
	v_lshlrev_b32_e32 v172, 16, v68
	v_and_b32_e32 v173, 0xffff0000, v68
	v_lshlrev_b32_e32 v174, 16, v69
	v_and_b32_e32 v175, 0xffff0000, v69
	v_lshlrev_b32_e32 v176, 16, v70
	v_and_b32_e32 v177, 0xffff0000, v70
	v_lshlrev_b32_e32 v178, 16, v71
	v_and_b32_e32 v179, 0xffff0000, v71
	v_pk_add_f32 v[164:165], v[164:165], v[172:173]
	v_pk_add_f32 v[166:167], v[166:167], v[174:175]
	v_pk_add_f32 v[168:169], v[168:169], v[176:177]
	v_pk_add_f32 v[170:171], v[170:171], v[178:179]
	v_pk_fma_f32 v[180:181], v[164:165], v[192:193], v[172:173] neg_lo:[0,0,1] neg_hi:[0,0,1]
	v_pk_fma_f32 v[182:183], v[166:167], v[192:193], v[174:175] neg_lo:[0,0,1] neg_hi:[0,0,1]
	v_pk_fma_f32 v[184:185], v[168:169], v[192:193], v[176:177] neg_lo:[0,0,1] neg_hi:[0,0,1]
	v_pk_fma_f32 v[186:187], v[170:171], v[192:193], v[178:179] neg_lo:[0,0,1] neg_hi:[0,0,1]
	v_cvt_pk_bf16_f32 v188, v180, v181
	v_cvt_pk_bf16_f32 v189, v182, v183
	v_cvt_pk_bf16_f32 v190, v184, v185
	v_cvt_pk_bf16_f32 v191, v186, v187
	s_nop 0
	global_store_dwordx4 v[196:197], v[188:191], off
	v_add_co_u32_e32 v196, vcc, 0x1000, v196
	s_nop 1
	v_addc_co_u32_e32 v197, vcc, 0, v197, vcc
	v_lshlrev_b32_e32 v172, 16, v64
	v_and_b32_e32 v173, 0xffff0000, v64
	v_lshlrev_b32_e32 v174, 16, v65
	v_and_b32_e32 v175, 0xffff0000, v65
	v_lshlrev_b32_e32 v176, 16, v66
	v_and_b32_e32 v177, 0xffff0000, v66
	v_lshlrev_b32_e32 v178, 16, v67
	v_and_b32_e32 v179, 0xffff0000, v67
	v_pk_add_f32 v[164:165], v[164:165], v[172:173] neg_lo:[0,1] neg_hi:[0,1]
	v_pk_add_f32 v[166:167], v[166:167], v[174:175] neg_lo:[0,1] neg_hi:[0,1]
	v_pk_add_f32 v[168:169], v[168:169], v[176:177] neg_lo:[0,1] neg_hi:[0,1]
	v_pk_add_f32 v[170:171], v[170:171], v[178:179] neg_lo:[0,1] neg_hi:[0,1]
	v_lshlrev_b32_e32 v172, 16, v72
	v_and_b32_e32 v173, 0xffff0000, v72
	v_lshlrev_b32_e32 v174, 16, v73
	v_and_b32_e32 v175, 0xffff0000, v73
	v_lshlrev_b32_e32 v176, 16, v74
	v_and_b32_e32 v177, 0xffff0000, v74
	v_lshlrev_b32_e32 v178, 16, v75
	v_and_b32_e32 v179, 0xffff0000, v75
	v_pk_add_f32 v[164:165], v[164:165], v[172:173]
	v_pk_add_f32 v[166:167], v[166:167], v[174:175]
	v_pk_add_f32 v[168:169], v[168:169], v[176:177]
	v_pk_add_f32 v[170:171], v[170:171], v[178:179]
	v_pk_fma_f32 v[180:181], v[164:165], v[192:193], v[172:173] neg_lo:[0,0,1] neg_hi:[0,0,1]
	v_pk_fma_f32 v[182:183], v[166:167], v[192:193], v[174:175] neg_lo:[0,0,1] neg_hi:[0,0,1]
	v_pk_fma_f32 v[184:185], v[168:169], v[192:193], v[176:177] neg_lo:[0,0,1] neg_hi:[0,0,1]
	v_pk_fma_f32 v[186:187], v[170:171], v[192:193], v[178:179] neg_lo:[0,0,1] neg_hi:[0,0,1]
	v_cvt_pk_bf16_f32 v200, v180, v181
	v_cvt_pk_bf16_f32 v201, v182, v183
	v_cvt_pk_bf16_f32 v202, v184, v185
	v_cvt_pk_bf16_f32 v203, v186, v187
	s_nop 0
	global_store_dwordx4 v[196:197], v[200:203], off
	v_add_co_u32_e32 v196, vcc, 0x1000, v196
	s_nop 1
	v_addc_co_u32_e32 v197, vcc, 0, v197, vcc
	v_lshlrev_b32_e32 v172, 16, v68
	v_and_b32_e32 v173, 0xffff0000, v68
	v_lshlrev_b32_e32 v174, 16, v69
	v_and_b32_e32 v175, 0xffff0000, v69
	v_lshlrev_b32_e32 v176, 16, v70
	v_and_b32_e32 v177, 0xffff0000, v70
	v_lshlrev_b32_e32 v178, 16, v71
	v_and_b32_e32 v179, 0xffff0000, v71
	v_pk_add_f32 v[164:165], v[164:165], v[172:173] neg_lo:[0,1] neg_hi:[0,1]
	v_pk_add_f32 v[166:167], v[166:167], v[174:175] neg_lo:[0,1] neg_hi:[0,1]
	v_pk_add_f32 v[168:169], v[168:169], v[176:177] neg_lo:[0,1] neg_hi:[0,1]
	v_pk_add_f32 v[170:171], v[170:171], v[178:179] neg_lo:[0,1] neg_hi:[0,1]
	v_lshlrev_b32_e32 v172, 16, v76
	v_and_b32_e32 v173, 0xffff0000, v76
	v_lshlrev_b32_e32 v174, 16, v77
	v_and_b32_e32 v175, 0xffff0000, v77
	v_lshlrev_b32_e32 v176, 16, v78
	v_and_b32_e32 v177, 0xffff0000, v78
	v_lshlrev_b32_e32 v178, 16, v79
	v_and_b32_e32 v179, 0xffff0000, v79
	v_pk_add_f32 v[164:165], v[164:165], v[172:173]
	v_pk_add_f32 v[166:167], v[166:167], v[174:175]
	v_pk_add_f32 v[168:169], v[168:169], v[176:177]
	v_pk_add_f32 v[170:171], v[170:171], v[178:179]
	v_pk_fma_f32 v[180:181], v[164:165], v[192:193], v[172:173] neg_lo:[0,0,1] neg_hi:[0,0,1]
	v_pk_fma_f32 v[182:183], v[166:167], v[192:193], v[174:175] neg_lo:[0,0,1] neg_hi:[0,0,1]
	v_pk_fma_f32 v[184:185], v[168:169], v[192:193], v[176:177] neg_lo:[0,0,1] neg_hi:[0,0,1]
	v_pk_fma_f32 v[186:187], v[170:171], v[192:193], v[178:179] neg_lo:[0,0,1] neg_hi:[0,0,1]
	v_cvt_pk_bf16_f32 v188, v180, v181
	v_cvt_pk_bf16_f32 v189, v182, v183
	v_cvt_pk_bf16_f32 v190, v184, v185
	v_cvt_pk_bf16_f32 v191, v186, v187
	s_nop 0
	global_store_dwordx4 v[196:197], v[188:191], off
	v_add_co_u32_e32 v196, vcc, 0x1000, v196
	s_nop 1
	v_addc_co_u32_e32 v197, vcc, 0, v197, vcc
	v_lshlrev_b32_e32 v172, 16, v72
	v_and_b32_e32 v173, 0xffff0000, v72
	v_lshlrev_b32_e32 v174, 16, v73
	v_and_b32_e32 v175, 0xffff0000, v73
	v_lshlrev_b32_e32 v176, 16, v74
; __device__ __forceinline__ float bf_lo(u32 v) { return __uint_as_float(v << 16); }
; __device__ __forceinline__ float bf_hi(u32 v) { return __uint_as_float(v & 0xffff0000u); }
; #define POOL_ACC(v, sgn) do { acc0 += sgn bf_lo(v.x); acc1 += sgn bf_hi(v.x); acc2 += sgn bf_lo(v.y); acc3 += sgn bf_hi(v.y); \
;     acc4 += sgn bf_lo(v.z); acc5 += sgn bf_hi(v.z); acc6 += sgn bf_lo(v.w); acc7 += sgn bf_hi(v.w); } while (0)
; template <int WIN>
; __device__ __forceinline__ void pool_run(const u16* U, u16* PL, int tok_s, int c0) {
;   const int pos_s = tok_s & (SEQ - 1);
;   float acc0 = 0.f, acc1 = 0.f, acc2 = 0.f, acc3 = 0.f, acc4 = 0.f, acc5 = 0.f, acc6 = 0.f, acc7 = 0.f;
;   #pragma unroll
;   for (int w = 1; w < WIN; ++w) {
;     if (pos_s - w >= 0) { const uint4 v = *(const uint4*)(U + (long)(tok_s - w) * LD0 + c0); POOL_ACC(v, +); }
;   }
;   #pragma unroll
;   for (int tt = 0; tt < 16; ++tt) {
;     const int tok = tok_s + tt, pos = pos_s + tt;
;     const uint4 cur = *(const uint4*)(U + (long)tok * LD0 + c0);
;     POOL_ACC(cur, +);
;     const float ic = 1.0f / (float)min(WIN, pos + 1);
;     uint4 pk;
;     pk.x = pack2(acc0 * ic - bf_lo(cur.x), acc1 * ic - bf_hi(cur.x));
;     pk.y = pack2(acc2 * ic - bf_lo(cur.y), acc3 * ic - bf_hi(cur.y));
;     pk.z = pack2(acc4 * ic - bf_lo(cur.z), acc5 * ic - bf_hi(cur.z));
;     pk.w = pack2(acc6 * ic - bf_lo(cur.w), acc7 * ic - bf_hi(cur.w));
;     *(uint4*)(PL + (long)tok * 2048 + c0) = pk;
;     if (pos - (WIN - 1) >= 0) { const uint4 old = *(const uint4*)(U + (long)(tok - (WIN - 1)) * LD0 + c0); POOL_ACC(old, -); }
;   }
; }
; __device__ __forceinline__ void pool_item(const Params& p, int item, const int wv) {
;   const u16* U = (const u16*)(p.ws + OFF_PB0) + 4096;
;   u16* PL = (u16*)(p.ws + OFF_PL);
;   const int tid = opaque_tid(wv), ch = tid & 255, half = tid >> 8;
;   const int c0 = ch * 8;
;   const int tok_s = item * 32 + half * 16;
;   const int g = (wv & 3);
;   if (g == 0) pool_run<2>(U, PL, tok_s, c0);
;   else if (g == 1) pool_run<4>(U, PL, tok_s, c0);
;   else if (g == 2) pool_run<8>(U, PL, tok_s, c0);
;   else pool_run<16>(U, PL, tok_s, c0);
	v_and_b32_e32 v177, 0xffff0000, v74
	v_lshlrev_b32_e32 v178, 16, v75
	v_and_b32_e32 v179, 0xffff0000, v75
	v_pk_add_f32 v[164:165], v[164:165], v[172:173] neg_lo:[0,1] neg_hi:[0,1]
	v_pk_add_f32 v[166:167], v[166:167], v[174:175] neg_lo:[0,1] neg_hi:[0,1]
	v_pk_add_f32 v[168:169], v[168:169], v[176:177] neg_lo:[0,1] neg_hi:[0,1]
	v_pk_add_f32 v[170:171], v[170:171], v[178:179] neg_lo:[0,1] neg_hi:[0,1]
	v_lshlrev_b32_e32 v172, 16, v80
	v_and_b32_e32 v173, 0xffff0000, v80
	v_lshlrev_b32_e32 v174, 16, v81
	v_and_b32_e32 v175, 0xffff0000, v81
	v_lshlrev_b32_e32 v176, 16, v82
	v_and_b32_e32 v177, 0xffff0000, v82
	v_lshlrev_b32_e32 v178, 16, v83
	v_and_b32_e32 v179, 0xffff0000, v83
	v_pk_add_f32 v[164:165], v[164:165], v[172:173]
	v_pk_add_f32 v[166:167], v[166:167], v[174:175]
	v_pk_add_f32 v[168:169], v[168:169], v[176:177]
	v_pk_add_f32 v[170:171], v[170:171], v[178:179]
	v_pk_fma_f32 v[180:181], v[164:165], v[192:193], v[172:173] neg_lo:[0,0,1] neg_hi:[0,0,1]
	v_pk_fma_f32 v[182:183], v[166:167], v[192:193], v[174:175] neg_lo:[0,0,1] neg_hi:[0,0,1]
	v_pk_fma_f32 v[184:185], v[168:169], v[192:193], v[176:177] neg_lo:[0,0,1] neg_hi:[0,0,1]
	v_pk_fma_f32 v[186:187], v[170:171], v[192:193], v[178:179] neg_lo:[0,0,1] neg_hi:[0,0,1]
	v_cvt_pk_bf16_f32 v200, v180, v181
	v_cvt_pk_bf16_f32 v201, v182, v183
	v_cvt_pk_bf16_f32 v202, v184, v185
	v_cvt_pk_bf16_f32 v203, v186, v187
	s_nop 0
	global_store_dwordx4 v[196:197], v[200:203], off
	v_add_co_u32_e32 v196, vcc, 0x1000, v196
	s_nop 1
	v_addc_co_u32_e32 v197, vcc, 0, v197, vcc
	v_lshlrev_b32_e32 v172, 16, v76
	v_and_b32_e32 v173, 0xffff0000, v76
	v_lshlrev_b32_e32 v174, 16, v77
	v_and_b32_e32 v175, 0xffff0000, v77
	v_lshlrev_b32_e32 v176, 16, v78
	v_and_b32_e32 v177, 0xffff0000, v78
	v_lshlrev_b32_e32 v178, 16, v79
	v_and_b32_e32 v179, 0xffff0000, v79
	v_pk_add_f32 v[164:165], v[164:165], v[172:173] neg_lo:[0,1] neg_hi:[0,1]
	v_pk_add_f32 v[166:167], v[166:167], v[174:175] neg_lo:[0,1] neg_hi:[0,1]
	v_pk_add_f32 v[168:169], v[168:169], v[176:177] neg_lo:[0,1] neg_hi:[0,1]
	v_pk_add_f32 v[170:171], v[170:171], v[178:179] neg_lo:[0,1] neg_hi:[0,1]
	v_lshlrev_b32_e32 v172, 16, v84
	v_and_b32_e32 v173, 0xffff0000, v84
	v_lshlrev_b32_e32 v174, 16, v85
	v_and_b32_e32 v175, 0xffff0000, v85
	v_lshlrev_b32_e32 v176, 16, v86
	v_and_b32_e32 v177, 0xffff0000, v86
	v_lshlrev_b32_e32 v178, 16, v87
	v_and_b32_e32 v179, 0xffff0000, v87
	v_pk_add_f32 v[164:165], v[164:165], v[172:173]
	v_pk_add_f32 v[166:167], v[166:167], v[174:175]
	v_pk_add_f32 v[168:169], v[168:169], v[176:177]
	v_pk_add_f32 v[170:171], v[170:171], v[178:179]
	v_pk_fma_f32 v[180:181], v[164:165], v[192:193], v[172:173] neg_lo:[0,0,1] neg_hi:[0,0,1]
	v_pk_fma_f32 v[182:183], v[166:167], v[192:193], v[174:175] neg_lo:[0,0,1] neg_hi:[0,0,1]
	v_pk_fma_f32 v[184:185], v[168:169], v[192:193], v[176:177] neg_lo:[0,0,1] neg_hi:[0,0,1]
	v_pk_fma_f32 v[186:187], v[170:171], v[192:193], v[178:179] neg_lo:[0,0,1] neg_hi:[0,0,1]
	v_cvt_pk_bf16_f32 v188, v180, v181
	v_cvt_pk_bf16_f32 v189, v182, v183
	v_cvt_pk_bf16_f32 v190, v184, v185
	v_cvt_pk_bf16_f32 v191, v186, v187
	s_nop 0
	global_store_dwordx4 v[196:197], v[188:191], off
	v_add_co_u32_e32 v196, vcc, 0x1000, v196
	s_nop 1
	v_addc_co_u32_e32 v197, vcc, 0, v197, vcc
	v_lshlrev_b32_e32 v172, 16, v80
	v_and_b32_e32 v173, 0xffff0000, v80
	v_lshlrev_b32_e32 v174, 16, v81
	v_and_b32_e32 v175, 0xffff0000, v81
	v_lshlrev_b32_e32 v176, 16, v82
	v_and_b32_e32 v177, 0xffff0000, v82
	v_lshlrev_b32_e32 v178, 16, v83
	v_and_b32_e32 v179, 0xffff0000, v83
	v_pk_add_f32 v[164:165], v[164:165], v[172:173] neg_lo:[0,1] neg_hi:[0,1]
	v_pk_add_f32 v[166:167], v[166:167], v[174:175] neg_lo:[0,1] neg_hi:[0,1]
	v_pk_add_f32 v[168:169], v[168:169], v[176:177] neg_lo:[0,1] neg_hi:[0,1]
	v_pk_add_f32 v[170:171], v[170:171], v[178:179] neg_lo:[0,1] neg_hi:[0,1]
	v_lshlrev_b32_e32 v172, 16, v88
	v_and_b32_e32 v173, 0xffff0000, v88
	v_lshlrev_b32_e32 v174, 16, v89
	v_and_b32_e32 v175, 0xffff0000, v89
	v_lshlrev_b32_e32 v176, 16, v90
	v_and_b32_e32 v177, 0xffff0000, v90
	v_lshlrev_b32_e32 v178, 16, v91
	v_and_b32_e32 v179, 0xffff0000, v91
	v_pk_add_f32 v[164:165], v[164:165], v[172:173]
	v_pk_add_f32 v[166:167], v[166:167], v[174:175]
	v_pk_add_f32 v[168:169], v[168:169], v[176:177]
	v_pk_add_f32 v[170:171], v[170:171], v[178:179]
	v_pk_fma_f32 v[180:181], v[164:165], v[192:193], v[172:173] neg_lo:[0,0,1] neg_hi:[0,0,1]
	v_pk_fma_f32 v[182:183], v[166:167], v[192:193], v[174:175] neg_lo:[0,0,1] neg_hi:[0,0,1]
	v_pk_fma_f32 v[184:185], v[168:169], v[192:193], v[176:177] neg_lo:[0,0,1] neg_hi:[0,0,1]
	v_pk_fma_f32 v[186:187], v[170:171], v[192:193], v[178:179] neg_lo:[0,0,1] neg_hi:[0,0,1]
	v_cvt_pk_bf16_f32 v200, v180, v181
	v_cvt_pk_bf16_f32 v201, v182, v183
	v_cvt_pk_bf16_f32 v202, v184, v185
	v_cvt_pk_bf16_f32 v203, v186, v187
	s_nop 0
	global_store_dwordx4 v[196:197], v[200:203], off
	s_branch .LBB0_333
.Lpool_slow:
	s_cmp_lt_i32 s0, 2
	s_mov_b64 s[4:5], -1
	s_cbranch_scc1 .LBB0_415
	v_readlane_b32 s0, v255, 24
	s_cmp_gt_i32 s0, 2
	s_cbranch_scc0 .LBB0_390
	v_readlane_b32 s0, v255, 20
	v_lshlrev_b32_e32 v140, 1, v22
	v_readlane_b32 s1, v255, 21
	v_mov_b32_e32 v0, v141
	v_mov_b32_e32 v1, v141
	v_lshl_add_u64 v[18:19], s[0:1], 0, v[140:141]
	v_cmp_ne_u32_e64 s[0:1], 0, v23
	v_mov_b64_e32 v[2:3], v[0:1]
	v_mov_b64_e32 v[4:5], v[0:1]
	v_mov_b64_e32 v[6:7], v[0:1]
	s_and_saveexec_b64 s[4:5], s[0:1]
	s_cbranch_execnz .LBB0_452
	s_or_b64 exec, exec, s[4:5]
	s_and_saveexec_b64 s[4:5], s[0:1]
	s_cbranch_execnz .LBB0_453
